# counted vmcnt waits in the in-proj (hyena inputs) epilogue: vmcnt(0) after a 5-load batch replaced by per-use counted waits
# baseline (speedup 1.0000x reference)
.LBB0_422:
	s_lshl_b32 s8, s84, 12
	s_and_b32 s8, s8, 0x1000
	v_add_u32_e32 v128, s8, v175
	ds_read_b128 v[176:179], v128
	ds_read_b128 v[180:183], v128 offset:256
	ds_read_b128 v[184:187], v128 offset:512
	ds_read_b128 v[188:191], v128 offset:768
	ds_read_b128 v[192:195], v128 offset:1024
	ds_read_b128 v[196:199], v128 offset:1280
	s_waitcnt lgkmcnt(0)
	v_mov_b32_e32 v156, v177
	v_mov_b32_e32 v157, v178
	v_mov_b32_e32 v177, v179
	v_mov_b32_e32 v168, v181
	v_mov_b32_e32 v169, v182
	v_mov_b32_e32 v181, v183
	v_pk_add_f32 v[156:157], v[156:157], v[176:177]
	v_pk_add_f32 v[168:169], v[168:169], v[180:181]
	v_mov_b32_e32 v177, v156
	v_mov_b32_e32 v176, v168
	v_mov_b32_e32 v156, v169
	s_mov_b32 s8, 0x358637bd
	v_pk_add_f32 v[156:157], v[176:177], v[156:157]
	v_mov_b64_e32 v[168:169], s[8:9]
	v_pk_fma_f32 v[156:157], v[156:157], s[14:15], v[168:169] op_sel_hi:[1,0,0]
	ds_read_b128 v[176:179], v128 offset:1536
	ds_read_b128 v[180:183], v128 offset:1792
	v_mul_f32_e32 v153, 0x4b800000, v157
	v_cmp_gt_f32_e32 vcc, s37, v157
	v_mul_f32_e32 v154, 0x4b800000, v156
	v_cmp_gt_f32_e64 s[8:9], s37, v156
	v_cndmask_b32_e32 v153, v157, v153, vcc
	v_mov_b32_e32 v157, v186
	v_cndmask_b32_e64 v154, v156, v154, s[8:9]
	v_mov_b32_e32 v156, v185
	v_mov_b32_e32 v185, v187
	v_rsq_f32_e32 v153, v153
	v_pk_add_f32 v[156:157], v[156:157], v[184:185]
	v_mov_b32_e32 v184, v189
	v_mov_b32_e32 v185, v190
	v_mov_b32_e32 v189, v191
	v_pk_add_f32 v[184:185], v[184:185], v[188:189]
	v_mov_b32_e32 v187, v156
	v_mov_b32_e32 v186, v184
	v_mov_b32_e32 v156, v185
	v_pk_add_f32 v[156:157], v[186:187], v[156:157]
	v_mul_f32_e32 v128, 0x45800000, v153
	v_pk_fma_f32 v[156:157], v[156:157], s[14:15], v[168:169] op_sel_hi:[1,0,0]
	v_cndmask_b32_e32 v174, v153, v128, vcc
	v_mul_f32_e32 v153, 0x4b800000, v157
	v_cmp_gt_f32_e32 vcc, s37, v157
	v_cmp_gt_f32_e64 s[10:11], s37, v156
	v_rsq_f32_e32 v154, v154
	v_cndmask_b32_e32 v153, v157, v153, vcc
	v_mul_f32_e32 v157, 0x4b800000, v156
	v_cndmask_b32_e64 v156, v156, v157, s[10:11]
	v_rsq_f32_e32 v153, v153
	v_rsq_f32_e32 v158, v156
	v_mov_b32_e32 v156, v193
	v_mov_b32_e32 v157, v194
	v_mov_b32_e32 v193, v195
	v_mov_b32_e32 v184, v197
	v_mov_b32_e32 v185, v198
	v_mov_b32_e32 v197, v199
	v_pk_add_f32 v[156:157], v[156:157], v[192:193]
	v_pk_add_f32 v[184:185], v[184:185], v[196:197]
	v_mov_b32_e32 v187, v156
	v_mov_b32_e32 v186, v184
	v_mov_b32_e32 v156, v185
	v_mul_f32_e32 v128, 0x45800000, v154
	v_pk_add_f32 v[156:157], v[186:187], v[156:157]
	v_cndmask_b32_e64 v172, v154, v128, s[8:9]
	v_mul_f32_e32 v128, 0x45800000, v153
	v_pk_fma_f32 v[156:157], v[156:157], s[14:15], v[168:169] op_sel_hi:[1,0,0]
	v_cndmask_b32_e32 v166, v153, v128, vcc
	v_mul_f32_e32 v153, 0x4b800000, v157
	v_cmp_gt_f32_e32 vcc, s37, v157
	v_mul_f32_e32 v154, 0x4b800000, v156
	v_cmp_gt_f32_e64 s[8:9], s37, v156
	v_cndmask_b32_e32 v153, v157, v153, vcc
	s_waitcnt lgkmcnt(0)
	v_mov_b32_e32 v157, v178
	v_cndmask_b32_e64 v154, v156, v154, s[8:9]
	v_mov_b32_e32 v156, v177
	v_mov_b32_e32 v177, v179
	v_rsq_f32_e32 v153, v153
	v_pk_add_f32 v[156:157], v[156:157], v[176:177]
	v_mov_b32_e32 v176, v181
	v_mov_b32_e32 v177, v182
	v_mov_b32_e32 v181, v183
	v_pk_add_f32 v[176:177], v[176:177], v[180:181]
	v_mov_b32_e32 v179, v156
	v_mov_b32_e32 v178, v176
	v_mov_b32_e32 v156, v177
	v_mul_f32_e32 v128, 0x45800000, v158
	v_pk_add_f32 v[156:157], v[178:179], v[156:157]
	v_cndmask_b32_e64 v164, v158, v128, s[10:11]
	v_mul_f32_e32 v128, 0x45800000, v153
	v_pk_fma_f32 v[156:157], v[156:157], s[14:15], v[168:169] op_sel_hi:[1,0,0]
	v_cndmask_b32_e32 v162, v153, v128, vcc
	v_mul_f32_e32 v153, 0x4b800000, v157
	v_cmp_gt_f32_e32 vcc, s37, v157
	v_rsq_f32_e32 v154, v154
	v_cmp_gt_f32_e64 s[10:11], s37, v156
	v_cndmask_b32_e32 v153, v157, v153, vcc
	v_mul_f32_e32 v157, 0x4b800000, v156
	v_rsq_f32_e32 v153, v153
	v_cndmask_b32_e64 v156, v156, v157, s[10:11]
	v_rsq_f32_e32 v156, v156
	v_mul_f32_e32 v128, 0x45800000, v154
	v_cndmask_b32_e64 v160, v154, v128, s[8:9]
	v_mul_f32_e32 v128, 0x45800000, v153
	v_cndmask_b32_e32 v158, v153, v128, vcc
	v_mul_f32_e32 v128, 0x45800000, v156
	v_lshl_or_b32 v170, s53, 6, v142
	v_cndmask_b32_e64 v154, v156, v128, s[10:11]
	v_lshl_add_u32 v156, s62, 8, v167
	s_mov_b64 s[8:9], -1
	s_andn2_b64 vcc, exec, s[64:65]
	v_ashrrev_i32_e32 v171, 31, v170
	v_ashrrev_i32_e32 v157, 31, v156
	v_or_b32_e32 v178, 16, v156
	v_or_b32_e32 v176, 32, v156
	v_or_b32_e32 v168, 48, v156
	s_cbranch_vccz .LBB0_424
	v_lshlrev_b32_e32 v128, 7, v156
	v_lshl_add_u64 v[180:181], s[66:67], 2, v[144:145]
	v_and_b32_e32 v128, 0x3e780, v128
	global_load_dwordx4 v[182:185], v[180:181], off
	global_load_dwordx4 v[202:205], v[180:181], off offset:16
	v_mov_b32_e32 v153, v129
	v_lshl_add_u64 v[180:181], s[26:27], 0, v[128:129]
	v_lshl_add_u64 v[198:199], v[180:181], 0, v[152:153]
	global_load_dwordx4 v[206:209], v[198:199], off
	global_load_dwordx4 v[210:213], v[198:199], off offset:16
	v_cmp_lt_i32_e32 vcc, v215, v214
	v_mul_f32_e32 v177, v116, v116
	v_mul_f32_e32 v179, v117, v117
	v_cndmask_b32_e32 v128, v161, v215, vcc
	v_pk_mul_f32 v[180:181], v[118:119], v[118:119]
	v_fmac_f32_e32 v177, v124, v124
	v_fmac_f32_e32 v179, v125, v125
	v_lshlrev_b32_e32 v169, 2, v128
	v_pk_fma_f32 v[180:181], v[126:127], v[126:127], v[180:181]
	v_add_f32_e32 v128, v177, v179
	v_pk_mul_f32 v[188:189], v[112:113], v[112:113]
	v_add_f32_e32 v128, v180, v128
	v_pk_fma_f32 v[188:189], v[120:121], v[120:121], v[188:189]
	v_add_f32_e32 v128, v181, v128
	v_pk_mul_f32 v[186:187], v[114:115], v[114:115]
	v_add_f32_e32 v128, v188, v128
	v_pk_fma_f32 v[186:187], v[122:123], v[122:123], v[186:187]
	v_add_f32_e32 v128, v189, v128
	v_add_f32_e32 v128, v186, v128
	v_add_f32_e32 v128, v187, v128
	ds_bpermute_b32 v179, v169, v128
	v_cmp_lt_i32_e32 vcc, v216, v214
	global_load_dwordx4 v[218:221], v[198:199], off offset:2048
	v_lshl_add_u64 v[180:181], v[170:171], 1, s[48:49]
	v_cndmask_b32_e32 v177, v161, v216, vcc
	v_lshlrev_b32_e32 v177, 2, v177
	s_waitcnt lgkmcnt(0)
	v_add_f32_e32 v128, v128, v179
	ds_bpermute_b32 v179, v177, v128
	v_pk_mul_f32 v[236:237], v[80:81], v[80:81]
	v_mul_lo_u32 v217, s61, v178
	v_pk_fma_f32 v[236:237], v[88:89], v[88:89], v[236:237]
	s_waitcnt lgkmcnt(0)
	v_add_f32_e32 v128, v128, v179
	v_mul_f32_e32 v128, v174, v128
	v_mul_f32_e32 v128, v174, v128
	v_fmamk_f32 v128, v128, 0x3c800000, v143
	v_mul_f32_e32 v179, 0x4b800000, v128
	v_cmp_gt_f32_e32 vcc, s37, v128
	s_waitcnt vmcnt(4)
	v_cvt_f32_f16_sdwa v187, v185 dst_sel:DWORD dst_unused:UNUSED_PAD src0_sel:WORD_1
	v_cndmask_b32_e32 v128, v128, v179, vcc
	v_rsq_f32_e32 v128, v128
	v_cvt_f32_f16_sdwa v186, v184 dst_sel:DWORD dst_unused:UNUSED_PAD src0_sel:WORD_1
	v_cvt_f32_f16_sdwa v195, v183 dst_sel:DWORD dst_unused:UNUSED_PAD src0_sel:WORD_1
	v_cvt_f32_f16_sdwa v194, v182 dst_sel:DWORD dst_unused:UNUSED_PAD src0_sel:WORD_1
	v_mul_f32_e32 v179, 0x45800000, v128
	v_cndmask_b32_e32 v128, v128, v179, vcc
	v_cvt_f32_f16_e32 v191, v185
	v_cvt_f32_f16_e32 v190, v184
	v_mul_f32_e32 v128, v174, v128
	v_cvt_f32_f16_e32 v197, v183
	v_cvt_f32_f16_e32 v196, v182
	s_waitcnt vmcnt(2)
	v_cvt_f32_f16_sdwa v189, v207 dst_sel:DWORD dst_unused:UNUSED_PAD src0_sel:WORD_1
	v_cvt_f32_f16_sdwa v188, v206 dst_sel:DWORD dst_unused:UNUSED_PAD src0_sel:WORD_1
	v_cvt_f32_f16_e32 v193, v207
	v_cvt_f32_f16_e32 v192, v206
	v_cvt_f32_f16_e32 v207, v209
	v_cvt_f32_f16_e32 v206, v208
	v_mul_f32_e32 v128, s83, v128
	v_cvt_f32_f16_e32 v185, v203
	v_cvt_f32_f16_e32 v184, v202
	v_cvt_f32_f16_sdwa v183, v203 dst_sel:DWORD dst_unused:UNUSED_PAD src0_sel:WORD_1
	v_cvt_f32_f16_sdwa v182, v202 dst_sel:DWORD dst_unused:UNUSED_PAD src0_sel:WORD_1
	v_cvt_f32_f16_sdwa v203, v209 dst_sel:DWORD dst_unused:UNUSED_PAD src0_sel:WORD_1
	v_cvt_f32_f16_sdwa v202, v208 dst_sel:DWORD dst_unused:UNUSED_PAD src0_sel:WORD_1
	v_pk_mul_f32 v[226:227], v[128:129], v[186:187] op_sel_hi:[0,1]
	v_pk_mul_f32 v[222:223], v[128:129], v[194:195] op_sel_hi:[0,1]
	v_pk_mul_f32 v[224:225], v[128:129], v[190:191] op_sel_hi:[0,1]
	v_pk_mul_f32 v[226:227], v[118:119], v[226:227]
	v_pk_mul_f32 v[208:209], v[128:129], v[196:197] op_sel_hi:[0,1]
	v_pk_mul_f32 v[222:223], v[116:117], v[222:223]
	v_pk_mul_f32 v[224:225], v[126:127], v[224:225]
	v_pk_mul_f32 v[234:235], v[226:227], v[206:207]
	v_pk_mul_f32 v[208:209], v[124:125], v[208:209]
	v_pk_mul_f32 v[230:231], v[222:223], v[192:193]
	v_pk_mul_f32 v[222:223], v[222:223], v[188:189]
	v_pk_mul_f32 v[226:227], v[226:227], v[202:203]
	v_pk_fma_f32 v[202:203], v[224:225], v[202:203], v[234:235]
	v_pk_fma_f32 v[192:193], v[208:209], v[192:193], v[222:223] neg_lo:[0,0,1] neg_hi:[0,0,1]
	v_cvt_pk_bf16_f32 v223, v202, v203
	s_waitcnt vmcnt(1)
	v_cvt_f32_f16_e32 v203, v211
	v_cvt_f32_f16_e32 v202, v210
	v_pk_fma_f32 v[188:189], v[208:209], v[188:189], v[230:231]
	v_pk_fma_f32 v[208:209], v[224:225], v[206:207], v[226:227] neg_lo:[0,0,1] neg_hi:[0,0,1]
	v_cvt_pk_bf16_f32 v206, v192, v193
	v_cvt_f32_f16_sdwa v193, v211 dst_sel:DWORD dst_unused:UNUSED_PAD src0_sel:WORD_1
	v_cvt_f32_f16_sdwa v192, v210 dst_sel:DWORD dst_unused:UNUSED_PAD src0_sel:WORD_1
	v_cvt_pk_bf16_f32 v207, v208, v209
	v_pk_mul_f32 v[208:209], v[128:129], v[182:183] op_sel_hi:[0,1]
	v_pk_mul_f32 v[228:229], v[128:129], v[184:185] op_sel_hi:[0,1]
	v_pk_mul_f32 v[208:209], v[112:113], v[208:209]
	v_cvt_pk_bf16_f32 v222, v188, v189
	v_pk_mul_f32 v[188:189], v[120:121], v[228:229]
	v_pk_mul_f32 v[210:211], v[208:209], v[202:203]
	v_cvt_f32_f16_e32 v227, v213
	v_pk_fma_f32 v[210:211], v[188:189], v[192:193], v[210:211]
	v_pk_mul_f32 v[192:193], v[208:209], v[192:193]
	v_cvt_f32_f16_e32 v226, v212
	v_pk_fma_f32 v[188:189], v[188:189], v[202:203], v[192:193] neg_lo:[0,0,1] neg_hi:[0,0,1]
	v_cvt_f32_f16_e32 v193, v205
	v_cvt_f32_f16_e32 v192, v204
	v_cvt_pk_bf16_f32 v208, v188, v189
	v_cvt_f32_f16_sdwa v189, v205 dst_sel:DWORD dst_unused:UNUSED_PAD src0_sel:WORD_1
	v_cvt_f32_f16_sdwa v188, v204 dst_sel:DWORD dst_unused:UNUSED_PAD src0_sel:WORD_1
	v_pk_mul_f32 v[202:203], v[128:129], v[192:193] op_sel_hi:[0,1]
	v_cvt_pk_bf16_f32 v224, v210, v211
	v_pk_mul_f32 v[210:211], v[122:123], v[202:203]
	v_cvt_f32_f16_sdwa v203, v213 dst_sel:DWORD dst_unused:UNUSED_PAD src0_sel:WORD_1
	v_cvt_f32_f16_sdwa v202, v212 dst_sel:DWORD dst_unused:UNUSED_PAD src0_sel:WORD_1
	v_pk_mul_f32 v[204:205], v[128:129], v[188:189] op_sel_hi:[0,1]
	v_pk_mul_f32 v[204:205], v[114:115], v[204:205]
	v_mul_f32_e32 v128, v100, v100
	v_pk_mul_f32 v[212:213], v[204:205], v[226:227]
	v_mul_f32_e32 v179, v101, v101
	v_pk_fma_f32 v[212:213], v[210:211], v[202:203], v[212:213]
	v_fmac_f32_e32 v128, v108, v108
	v_cvt_pk_bf16_f32 v225, v212, v213
	v_pk_mul_f32 v[212:213], v[204:205], v[202:203]
	global_load_dwordx4 v[202:205], v[198:199], off offset:2064
	v_fmac_f32_e32 v179, v109, v109
	v_pk_mul_f32 v[228:229], v[102:103], v[102:103]
	v_add_f32_e32 v128, v128, v179
	v_pk_fma_f32 v[228:229], v[110:111], v[110:111], v[228:229]
	v_pk_mul_f32 v[230:231], v[96:97], v[96:97]
	v_add_f32_e32 v128, v228, v128
	v_add_f32_e32 v128, v229, v128
	v_pk_fma_f32 v[230:231], v[104:105], v[104:105], v[230:231]
	v_pk_mul_f32 v[228:229], v[98:99], v[98:99]
	v_add_f32_e32 v128, v230, v128
	v_pk_fma_f32 v[228:229], v[106:107], v[106:107], v[228:229]
	v_add_f32_e32 v128, v231, v128
	v_add_f32_e32 v128, v228, v128
	v_add_f32_e32 v128, v229, v128
	ds_bpermute_b32 v201, v169, v128
	v_pk_fma_f32 v[210:211], v[210:211], v[226:227], v[212:213] neg_lo:[0,0,1] neg_hi:[0,0,1]
	v_mul_lo_u32 v212, s61, v156
	v_cvt_pk_bf16_f32 v209, v210, v211
	v_mul_lo_u32 v179, s60, v157
	s_waitcnt lgkmcnt(0)
	v_add_f32_e32 v128, v128, v201
	ds_bpermute_b32 v201, v177, v128
	v_mad_u64_u32 v[210:211], s[8:9], s60, v156, 0
	v_add3_u32 v211, v211, v179, v212
	v_lshl_add_u64 v[210:211], v[210:211], 1, v[180:181]
	s_waitcnt lgkmcnt(0)
	v_add_f32_e32 v128, v128, v201
	v_mul_f32_e32 v128, v172, v128
	v_mul_f32_e32 v128, v172, v128
	v_fmamk_f32 v128, v128, 0x3c800000, v143
	v_mul_f32_e32 v201, 0x4b800000, v128
	v_cmp_gt_f32_e32 vcc, s37, v128
	global_store_dwordx4 v[210:211], v[206:209], off
	global_store_dwordx4 v[210:211], v[222:225], off offset:64
	v_cndmask_b32_e32 v128, v128, v201, vcc
	v_rsq_f32_e32 v128, v128
	s_waitcnt vmcnt(3)
	v_cvt_f32_f16_e32 v211, v219
	v_cvt_f32_f16_e32 v210, v218
	v_cvt_f32_f16_sdwa v209, v219 dst_sel:DWORD dst_unused:UNUSED_PAD src0_sel:WORD_1
	v_mul_f32_e32 v201, 0x45800000, v128
	v_cndmask_b32_e32 v128, v128, v201, vcc
	v_mul_f32_e32 v128, v172, v128
	v_mul_f32_e32 v128, s83, v128
	v_cvt_f32_f16_sdwa v208, v218 dst_sel:DWORD dst_unused:UNUSED_PAD src0_sel:WORD_1
	v_pk_mul_f32 v[212:213], v[128:129], v[194:195] op_sel_hi:[0,1]
	v_pk_mul_f32 v[206:207], v[128:129], v[196:197] op_sel_hi:[0,1]
	v_pk_mul_f32 v[212:213], v[100:101], v[212:213]
	v_pk_mul_f32 v[206:207], v[108:109], v[206:207]
	v_pk_mul_f32 v[218:219], v[212:213], v[210:211]
	v_add_co_u32_e32 v230, vcc, s36, v198
	v_pk_fma_f32 v[218:219], v[206:207], v[208:209], v[218:219]
	v_pk_mul_f32 v[208:209], v[212:213], v[208:209]
	v_addc_co_u32_e32 v231, vcc, 0, v199, vcc
	v_pk_fma_f32 v[210:211], v[206:207], v[210:211], v[208:209] neg_lo:[0,0,1] neg_hi:[0,0,1]
	v_pk_mul_f32 v[206:207], v[128:129], v[190:191] op_sel_hi:[0,1]
	v_pk_mul_f32 v[212:213], v[110:111], v[206:207]
	v_pk_mul_f32 v[206:207], v[128:129], v[186:187] op_sel_hi:[0,1]
	v_cvt_f32_f16_sdwa v225, v221 dst_sel:DWORD dst_unused:UNUSED_PAD src0_sel:WORD_1
	v_cvt_f32_f16_e32 v227, v221
	v_cvt_f32_f16_e32 v226, v220
	v_cvt_f32_f16_sdwa v224, v220 dst_sel:DWORD dst_unused:UNUSED_PAD src0_sel:WORD_1
	v_pk_mul_f32 v[220:221], v[102:103], v[206:207]
	global_load_dwordx4 v[206:209], v[230:231], off
	v_pk_mul_f32 v[228:229], v[220:221], v[226:227]
	v_pk_mul_f32 v[220:221], v[220:221], v[224:225]
	v_pk_fma_f32 v[228:229], v[212:213], v[224:225], v[228:229]
	v_pk_fma_f32 v[212:213], v[212:213], v[226:227], v[220:221] neg_lo:[0,0,1] neg_hi:[0,0,1]
	v_cvt_pk_bf16_f32 v210, v210, v211
	v_cvt_pk_bf16_f32 v211, v212, v213
	v_pk_mul_f32 v[212:213], v[128:129], v[184:185] op_sel_hi:[0,1]
	v_pk_mul_f32 v[212:213], v[104:105], v[212:213]
	v_lshl_add_u64 v[222:223], v[198:199], 0, s[16:17]
	v_cvt_pk_bf16_f32 v218, v218, v219
	v_cvt_pk_bf16_f32 v219, v228, v229
	v_pk_mul_f32 v[234:235], v[128:129], v[188:189] op_sel_hi:[0,1]
	v_mul_f32_e32 v201, v85, v85
	v_fmac_f32_e32 v201, v93, v93
	s_waitcnt vmcnt(3)
	v_cvt_f32_f16_sdwa v225, v203 dst_sel:DWORD dst_unused:UNUSED_PAD src0_sel:WORD_1
	v_cvt_f32_f16_e32 v227, v203
	v_cvt_f32_f16_e32 v226, v202
	v_cvt_f32_f16_sdwa v224, v202 dst_sel:DWORD dst_unused:UNUSED_PAD src0_sel:WORD_1
	v_pk_mul_f32 v[202:203], v[128:129], v[182:183] op_sel_hi:[0,1]
	v_pk_mul_f32 v[202:203], v[96:97], v[202:203]
	v_cvt_f32_f16_e32 v229, v205
	v_pk_mul_f32 v[220:221], v[202:203], v[226:227]
	v_pk_mul_f32 v[202:203], v[202:203], v[224:225]
	v_pk_fma_f32 v[220:221], v[212:213], v[224:225], v[220:221]
	v_pk_fma_f32 v[202:203], v[212:213], v[226:227], v[202:203] neg_lo:[0,0,1] neg_hi:[0,0,1]
	v_cvt_f32_f16_sdwa v227, v205 dst_sel:DWORD dst_unused:UNUSED_PAD src0_sel:WORD_1
	v_cvt_pk_bf16_f32 v212, v202, v203
	v_pk_mul_f32 v[202:203], v[128:129], v[192:193] op_sel_hi:[0,1]
	v_pk_mul_f32 v[224:225], v[106:107], v[202:203]
	v_cvt_f32_f16_sdwa v226, v204 dst_sel:DWORD dst_unused:UNUSED_PAD src0_sel:WORD_1
	v_cvt_f32_f16_e32 v228, v204
	global_load_dwordx4 v[202:205], v[222:223], off offset:16
	v_pk_mul_f32 v[222:223], v[98:99], v[234:235]
	v_mul_f32_e32 v128, v84, v84
	v_pk_mul_f32 v[234:235], v[222:223], v[228:229]
	v_cvt_pk_bf16_f32 v220, v220, v221
	v_pk_fma_f32 v[234:235], v[224:225], v[226:227], v[234:235]
	v_fmac_f32_e32 v128, v92, v92
	v_cvt_pk_bf16_f32 v221, v234, v235
	v_pk_mul_f32 v[234:235], v[86:87], v[86:87]
	v_add_f32_e32 v128, v128, v201
	v_pk_fma_f32 v[234:235], v[94:95], v[94:95], v[234:235]
	v_pk_mul_f32 v[222:223], v[222:223], v[226:227]
	v_add_f32_e32 v128, v234, v128
	v_add_f32_e32 v128, v235, v128
	v_pk_mul_f32 v[234:235], v[82:83], v[82:83]
	v_add_f32_e32 v128, v236, v128
	v_pk_fma_f32 v[234:235], v[90:91], v[90:91], v[234:235]
	v_add_f32_e32 v128, v237, v128
	v_add_f32_e32 v128, v234, v128
	v_add_f32_e32 v128, v235, v128
	ds_bpermute_b32 v201, v169, v128
	v_pk_fma_f32 v[222:223], v[224:225], v[228:229], v[222:223] neg_lo:[0,0,1] neg_hi:[0,0,1]
	v_lshl_add_u64 v[198:199], v[198:199], 0, s[18:19]
	v_cvt_pk_bf16_f32 v213, v222, v223
	v_mad_u64_u32 v[222:223], s[8:9], s60, v178, 0
	s_waitcnt lgkmcnt(0)
	v_add_f32_e32 v128, v128, v201
	ds_bpermute_b32 v201, v177, v128
	v_add3_u32 v223, v223, v179, v217
	v_lshl_add_u64 v[222:223], v[222:223], 1, v[180:181]
	global_store_dwordx4 v[222:223], v[210:213], off
	global_store_dwordx4 v[222:223], v[218:221], off offset:64
	s_waitcnt lgkmcnt(0)
	v_add_f32_e32 v128, v128, v201
	v_mul_f32_e32 v128, v166, v128
	v_mul_f32_e32 v128, v166, v128
	v_fmamk_f32 v128, v128, 0x3c800000, v143
	v_mul_f32_e32 v201, 0x4b800000, v128
	v_cmp_gt_f32_e32 vcc, s37, v128
	s_waitcnt vmcnt(3)
	v_cvt_f32_f16_sdwa v213, v207 dst_sel:DWORD dst_unused:UNUSED_PAD src0_sel:WORD_1
	v_cndmask_b32_e32 v128, v128, v201, vcc
	v_rsq_f32_e32 v128, v128
	v_cvt_f32_f16_e32 v219, v207
	v_cvt_f32_f16_e32 v218, v206
	v_cvt_f32_f16_sdwa v212, v206 dst_sel:DWORD dst_unused:UNUSED_PAD src0_sel:WORD_1
	v_mul_f32_e32 v201, 0x45800000, v128
	v_cndmask_b32_e32 v128, v128, v201, vcc
	v_mul_f32_e32 v128, v166, v128
	v_mul_f32_e32 v128, s83, v128
	v_pk_mul_f32 v[206:207], v[128:129], v[194:195] op_sel_hi:[0,1]
	v_pk_mul_f32 v[210:211], v[128:129], v[196:197] op_sel_hi:[0,1]
	v_pk_mul_f32 v[206:207], v[84:85], v[206:207]
	v_pk_mul_f32 v[210:211], v[92:93], v[210:211]
	v_pk_mul_f32 v[220:221], v[206:207], v[218:219]
	v_pk_mul_f32 v[206:207], v[206:207], v[212:213]
	v_pk_fma_f32 v[220:221], v[210:211], v[212:213], v[220:221]
	v_pk_fma_f32 v[210:211], v[210:211], v[218:219], v[206:207] neg_lo:[0,0,1] neg_hi:[0,0,1]
	v_cvt_f32_f16_sdwa v213, v209 dst_sel:DWORD dst_unused:UNUSED_PAD src0_sel:WORD_1
	v_cvt_f32_f16_e32 v219, v209
	v_cvt_f32_f16_e32 v218, v208
	v_cvt_f32_f16_sdwa v212, v208 dst_sel:DWORD dst_unused:UNUSED_PAD src0_sel:WORD_1
	v_pk_mul_f32 v[208:209], v[128:129], v[186:187] op_sel_hi:[0,1]
	v_pk_mul_f32 v[206:207], v[128:129], v[190:191] op_sel_hi:[0,1]
	v_pk_mul_f32 v[208:209], v[86:87], v[208:209]
	v_pk_mul_f32 v[206:207], v[94:95], v[206:207]
	v_pk_mul_f32 v[222:223], v[208:209], v[218:219]
	v_pk_mul_f32 v[208:209], v[208:209], v[212:213]
	v_pk_fma_f32 v[222:223], v[206:207], v[212:213], v[222:223]
	v_pk_fma_f32 v[212:213], v[206:207], v[218:219], v[208:209] neg_lo:[0,0,1] neg_hi:[0,0,1]
	global_load_dwordx4 v[206:209], v[230:231], off offset:2048
	v_cvt_pk_bf16_f32 v219, v222, v223
	s_waitcnt vmcnt(3)
	v_cvt_f32_f16_sdwa v223, v203 dst_sel:DWORD dst_unused:UNUSED_PAD src0_sel:WORD_1
	v_cvt_f32_f16_e32 v225, v203
	v_cvt_f32_f16_e32 v224, v202
	v_cvt_f32_f16_sdwa v222, v202 dst_sel:DWORD dst_unused:UNUSED_PAD src0_sel:WORD_1
	v_pk_mul_f32 v[202:203], v[128:129], v[182:183] op_sel_hi:[0,1]
	v_cvt_pk_bf16_f32 v210, v210, v211
	v_cvt_pk_bf16_f32 v211, v212, v213
	v_pk_mul_f32 v[212:213], v[128:129], v[184:185] op_sel_hi:[0,1]
	v_pk_mul_f32 v[202:203], v[80:81], v[202:203]
	v_cvt_pk_bf16_f32 v218, v220, v221
	v_pk_mul_f32 v[212:213], v[88:89], v[212:213]
	v_pk_mul_f32 v[220:221], v[202:203], v[224:225]
	v_pk_mul_f32 v[202:203], v[202:203], v[222:223]
	v_cvt_f32_f16_e32 v227, v205
	v_pk_fma_f32 v[202:203], v[212:213], v[224:225], v[202:203] neg_lo:[0,0,1] neg_hi:[0,0,1]
	v_cvt_f32_f16_e32 v226, v204
	v_pk_fma_f32 v[220:221], v[212:213], v[222:223], v[220:221]
	v_cvt_pk_bf16_f32 v212, v202, v203
	v_pk_mul_f32 v[202:203], v[128:129], v[192:193] op_sel_hi:[0,1]
	v_cvt_f32_f16_sdwa v225, v205 dst_sel:DWORD dst_unused:UNUSED_PAD src0_sel:WORD_1
	v_cvt_f32_f16_sdwa v224, v204 dst_sel:DWORD dst_unused:UNUSED_PAD src0_sel:WORD_1
	v_pk_mul_f32 v[222:223], v[90:91], v[202:203]
	v_pk_mul_f32 v[202:203], v[128:129], v[188:189] op_sel_hi:[0,1]
	v_pk_mul_f32 v[228:229], v[82:83], v[202:203]
	v_mul_lo_u32 v128, s61, v176
	v_pk_mul_f32 v[202:203], v[228:229], v[226:227]
	v_cvt_pk_bf16_f32 v220, v220, v221
	v_pk_fma_f32 v[230:231], v[222:223], v[224:225], v[202:203]
	global_load_dwordx4 v[202:205], v[198:199], off offset:16
	v_pk_mul_f32 v[198:199], v[228:229], v[224:225]
	v_cvt_pk_bf16_f32 v221, v230, v231
	v_pk_fma_f32 v[198:199], v[222:223], v[226:227], v[198:199] neg_lo:[0,0,1] neg_hi:[0,0,1]
	v_pk_mul_f32 v[222:223], v[64:65], v[64:65]
	v_cvt_pk_bf16_f32 v213, v198, v199
	v_mul_f32_e32 v198, v68, v68
	v_mul_f32_e32 v199, v69, v69
	v_fmac_f32_e32 v198, v76, v76
	v_fmac_f32_e32 v199, v77, v77
	v_add_f32_e32 v201, v198, v199
	v_pk_mul_f32 v[198:199], v[70:71], v[70:71]
	v_pk_fma_f32 v[222:223], v[72:73], v[72:73], v[222:223]
	v_pk_fma_f32 v[198:199], v[78:79], v[78:79], v[198:199]
	s_waitcnt vmcnt(0)
	v_cvt_f32_f16_e32 v225, v203
	v_add_f32_e32 v198, v198, v201
	v_add_f32_e32 v201, v199, v198
	v_pk_mul_f32 v[198:199], v[66:67], v[66:67]
	v_add_f32_e32 v201, v222, v201
	v_pk_fma_f32 v[198:199], v[74:75], v[74:75], v[198:199]
	v_add_f32_e32 v201, v223, v201
	v_add_f32_e32 v198, v198, v201
	v_add_f32_e32 v201, v199, v198
	ds_bpermute_b32 v217, v169, v201
	v_mad_u64_u32 v[198:199], s[8:9], s60, v176, 0
	v_add3_u32 v199, v199, v179, v128
	v_lshl_add_u64 v[198:199], v[198:199], 1, v[180:181]
	s_waitcnt lgkmcnt(0)
	v_add_f32_e32 v128, v201, v217
	ds_bpermute_b32 v201, v177, v128
	global_store_dwordx4 v[198:199], v[210:213], off
	global_store_dwordx4 v[198:199], v[218:221], off offset:64
	v_lshl_add_u32 v198, v156, 5, v159
	v_cvt_f32_f16_sdwa v213, v207 dst_sel:DWORD dst_unused:UNUSED_PAD src0_sel:WORD_1
	v_cvt_f32_f16_e32 v219, v207
	s_waitcnt lgkmcnt(0)
	v_add_f32_e32 v128, v128, v201
	v_mul_f32_e32 v128, v164, v128
	v_mul_f32_e32 v128, v164, v128
	v_fmamk_f32 v128, v128, 0x3c800000, v143
	v_mul_f32_e32 v199, 0x4b800000, v128
	v_cmp_gt_f32_e32 vcc, s37, v128
	v_cvt_f32_f16_e32 v218, v206
	v_cvt_f32_f16_sdwa v212, v206 dst_sel:DWORD dst_unused:UNUSED_PAD src0_sel:WORD_1
	v_cndmask_b32_e32 v128, v128, v199, vcc
	v_rsq_f32_e32 v201, v128
	v_and_b32_e32 v128, 0xf9e0, v198
	v_lshlrev_b32_e32 v128, 2, v128
	v_lshl_add_u64 v[198:199], v[146:147], 0, v[128:129]
	v_mul_f32_e32 v128, 0x45800000, v201
	v_cndmask_b32_e32 v128, v201, v128, vcc
	v_mul_f32_e32 v128, v164, v128
	v_mul_f32_e32 v128, s83, v128
	v_pk_mul_f32 v[206:207], v[128:129], v[194:195] op_sel_hi:[0,1]
	v_pk_mul_f32 v[210:211], v[128:129], v[196:197] op_sel_hi:[0,1]
	v_pk_mul_f32 v[206:207], v[68:69], v[206:207]
	v_pk_mul_f32 v[210:211], v[76:77], v[210:211]
	v_pk_mul_f32 v[220:221], v[206:207], v[218:219]
	v_pk_mul_f32 v[206:207], v[206:207], v[212:213]
	v_pk_fma_f32 v[220:221], v[210:211], v[212:213], v[220:221]
	v_pk_fma_f32 v[206:207], v[210:211], v[218:219], v[206:207] neg_lo:[0,0,1] neg_hi:[0,0,1]
	v_cvt_f32_f16_sdwa v213, v209 dst_sel:DWORD dst_unused:UNUSED_PAD src0_sel:WORD_1
	v_cvt_f32_f16_e32 v219, v209
	v_cvt_f32_f16_e32 v218, v208
	v_cvt_f32_f16_sdwa v212, v208 dst_sel:DWORD dst_unused:UNUSED_PAD src0_sel:WORD_1
	v_pk_mul_f32 v[208:209], v[128:129], v[186:187] op_sel_hi:[0,1]
	v_pk_mul_f32 v[210:211], v[128:129], v[190:191] op_sel_hi:[0,1]
	v_pk_mul_f32 v[208:209], v[70:71], v[208:209]
	v_pk_mul_f32 v[210:211], v[78:79], v[210:211]
	v_pk_mul_f32 v[222:223], v[208:209], v[218:219]
	v_pk_mul_f32 v[208:209], v[208:209], v[212:213]
	v_pk_fma_f32 v[222:223], v[210:211], v[212:213], v[222:223]
	v_pk_fma_f32 v[208:209], v[210:211], v[218:219], v[208:209] neg_lo:[0,0,1] neg_hi:[0,0,1]
	global_load_dwordx4 v[210:213], v[198:199], off
	v_cvt_pk_bf16_f32 v219, v222, v223
	v_cvt_f32_f16_sdwa v223, v203 dst_sel:DWORD dst_unused:UNUSED_PAD src0_sel:WORD_1
	v_cvt_f32_f16_e32 v224, v202
	v_cvt_f32_f16_sdwa v222, v202 dst_sel:DWORD dst_unused:UNUSED_PAD src0_sel:WORD_1
	v_pk_mul_f32 v[202:203], v[128:129], v[182:183] op_sel_hi:[0,1]
	v_cvt_pk_bf16_f32 v206, v206, v207
	v_cvt_pk_bf16_f32 v207, v208, v209
	v_pk_mul_f32 v[208:209], v[128:129], v[184:185] op_sel_hi:[0,1]
	v_pk_mul_f32 v[202:203], v[64:65], v[202:203]
	v_cvt_pk_bf16_f32 v218, v220, v221
	v_pk_mul_f32 v[208:209], v[72:73], v[208:209]
	v_pk_mul_f32 v[220:221], v[202:203], v[224:225]
	v_pk_mul_f32 v[202:203], v[202:203], v[222:223]
	v_cvt_f32_f16_e32 v227, v205
	v_pk_fma_f32 v[202:203], v[208:209], v[224:225], v[202:203] neg_lo:[0,0,1] neg_hi:[0,0,1]
	v_cvt_f32_f16_e32 v226, v204
	v_pk_fma_f32 v[220:221], v[208:209], v[222:223], v[220:221]
	v_cvt_pk_bf16_f32 v208, v202, v203
	v_pk_mul_f32 v[202:203], v[128:129], v[192:193] op_sel_hi:[0,1]
	v_cvt_f32_f16_sdwa v225, v205 dst_sel:DWORD dst_unused:UNUSED_PAD src0_sel:WORD_1
	v_cvt_f32_f16_sdwa v224, v204 dst_sel:DWORD dst_unused:UNUSED_PAD src0_sel:WORD_1
	v_pk_mul_f32 v[222:223], v[74:75], v[202:203]
	v_pk_mul_f32 v[202:203], v[128:129], v[188:189] op_sel_hi:[0,1]
	v_pk_mul_f32 v[228:229], v[66:67], v[202:203]
	v_cvt_pk_bf16_f32 v220, v220, v221
	v_pk_mul_f32 v[202:203], v[228:229], v[226:227]
	v_mul_lo_u32 v128, s61, v168
	v_pk_fma_f32 v[202:203], v[222:223], v[224:225], v[202:203]
	s_nop 0
	v_cvt_pk_bf16_f32 v221, v202, v203
	global_load_dwordx4 v[202:205], v[198:199], off offset:16
	v_pk_mul_f32 v[198:199], v[228:229], v[224:225]
	s_waitcnt vmcnt(0)
	v_cvt_f32_f16_e32 v225, v203
	v_pk_fma_f32 v[198:199], v[222:223], v[226:227], v[198:199] neg_lo:[0,0,1] neg_hi:[0,0,1]
	v_pk_mul_f32 v[222:223], v[48:49], v[48:49]
	v_cvt_pk_bf16_f32 v209, v198, v199
	v_mul_f32_e32 v198, v52, v52
	v_mul_f32_e32 v199, v53, v53
	v_fmac_f32_e32 v198, v60, v60
	v_fmac_f32_e32 v199, v61, v61
	v_add_f32_e32 v201, v198, v199
	v_pk_mul_f32 v[198:199], v[54:55], v[54:55]
	v_pk_fma_f32 v[222:223], v[56:57], v[56:57], v[222:223]
	v_pk_fma_f32 v[198:199], v[62:63], v[62:63], v[198:199]
	v_cvt_f32_f16_e32 v224, v202
	v_add_f32_e32 v198, v198, v201
	v_add_f32_e32 v201, v199, v198
	v_pk_mul_f32 v[198:199], v[50:51], v[50:51]
	v_add_f32_e32 v201, v222, v201
	v_pk_fma_f32 v[198:199], v[58:59], v[58:59], v[198:199]
	v_add_f32_e32 v201, v223, v201
	v_add_f32_e32 v198, v198, v201
	v_add_f32_e32 v201, v199, v198
	ds_bpermute_b32 v217, v169, v201
	v_mad_u64_u32 v[198:199], s[8:9], s60, v168, 0
	v_add3_u32 v199, v199, v179, v128
	v_lshl_add_u64 v[198:199], v[198:199], 1, v[180:181]
	s_waitcnt lgkmcnt(0)
	v_add_f32_e32 v128, v201, v217
	ds_bpermute_b32 v179, v177, v128
	v_add_u32_e32 v201, 0x80, v156
	global_store_dwordx4 v[198:199], v[206:209], off
	global_store_dwordx4 v[198:199], v[218:221], off offset:64
	v_lshlrev_b32_e32 v198, 7, v201
	s_waitcnt lgkmcnt(0)
	v_add_f32_e32 v128, v128, v179
	v_mul_f32_e32 v128, v162, v128
	v_mul_f32_e32 v128, v162, v128
	v_fmamk_f32 v128, v128, 0x3c800000, v143
	v_mul_f32_e32 v179, 0x4b800000, v128
	v_cmp_gt_f32_e32 vcc, s37, v128
	v_cvt_f32_f16_e32 v219, v211
	v_cvt_f32_f16_e32 v218, v210
	v_cndmask_b32_e32 v128, v128, v179, vcc
	v_rsq_f32_e32 v179, v128
	v_and_b32_e32 v128, 0x3e780, v198
	v_lshl_add_u64 v[198:199], s[26:27], 0, v[128:129]
	v_cvt_f32_f16_sdwa v209, v211 dst_sel:DWORD dst_unused:UNUSED_PAD src0_sel:WORD_1
	v_mul_f32_e32 v128, 0x45800000, v179
	v_cndmask_b32_e32 v128, v179, v128, vcc
	v_mul_f32_e32 v128, v162, v128
	v_mul_f32_e32 v128, s83, v128
	v_cvt_f32_f16_sdwa v208, v210 dst_sel:DWORD dst_unused:UNUSED_PAD src0_sel:WORD_1
	v_pk_mul_f32 v[210:211], v[128:129], v[194:195] op_sel_hi:[0,1]
	v_pk_mul_f32 v[206:207], v[128:129], v[196:197] op_sel_hi:[0,1]
	v_pk_mul_f32 v[210:211], v[52:53], v[210:211]
	v_pk_mul_f32 v[206:207], v[60:61], v[206:207]
	v_pk_mul_f32 v[220:221], v[210:211], v[218:219]
	v_lshl_add_u64 v[198:199], v[198:199], 0, v[152:153]
	v_pk_fma_f32 v[220:221], v[206:207], v[208:209], v[220:221]
	v_pk_mul_f32 v[208:209], v[210:211], v[208:209]
	v_mul_f32_e32 v153, v36, v36
	v_pk_fma_f32 v[210:211], v[206:207], v[218:219], v[208:209] neg_lo:[0,0,1] neg_hi:[0,0,1]
	v_cvt_f32_f16_e32 v219, v213
	v_cvt_f32_f16_e32 v218, v212
	v_cvt_f32_f16_sdwa v209, v213 dst_sel:DWORD dst_unused:UNUSED_PAD src0_sel:WORD_1
	v_cvt_f32_f16_sdwa v208, v212 dst_sel:DWORD dst_unused:UNUSED_PAD src0_sel:WORD_1
	v_pk_mul_f32 v[212:213], v[128:129], v[186:187] op_sel_hi:[0,1]
	v_pk_mul_f32 v[206:207], v[128:129], v[190:191] op_sel_hi:[0,1]
	v_pk_mul_f32 v[212:213], v[54:55], v[212:213]
	v_pk_mul_f32 v[206:207], v[62:63], v[206:207]
	v_pk_mul_f32 v[222:223], v[212:213], v[218:219]
	v_cvt_pk_bf16_f32 v210, v210, v211
	v_pk_fma_f32 v[222:223], v[206:207], v[208:209], v[222:223]
	v_pk_mul_f32 v[208:209], v[212:213], v[208:209]
	v_mul_f32_e32 v179, v37, v37
	v_pk_fma_f32 v[212:213], v[206:207], v[218:219], v[208:209] neg_lo:[0,0,1] neg_hi:[0,0,1]
	global_load_dwordx4 v[206:209], v[198:199], off offset:2048
	v_cvt_pk_bf16_f32 v219, v222, v223
	v_cvt_f32_f16_sdwa v223, v203 dst_sel:DWORD dst_unused:UNUSED_PAD src0_sel:WORD_1
	v_cvt_f32_f16_sdwa v222, v202 dst_sel:DWORD dst_unused:UNUSED_PAD src0_sel:WORD_1
	v_pk_mul_f32 v[202:203], v[128:129], v[182:183] op_sel_hi:[0,1]
	v_cvt_pk_bf16_f32 v211, v212, v213
	v_pk_mul_f32 v[212:213], v[128:129], v[184:185] op_sel_hi:[0,1]
	v_pk_mul_f32 v[202:203], v[48:49], v[202:203]
	v_cvt_pk_bf16_f32 v218, v220, v221
	v_pk_mul_f32 v[212:213], v[56:57], v[212:213]
	v_pk_mul_f32 v[220:221], v[202:203], v[224:225]
	v_pk_mul_f32 v[202:203], v[202:203], v[222:223]
	v_pk_fma_f32 v[220:221], v[212:213], v[222:223], v[220:221]
	v_pk_fma_f32 v[202:203], v[212:213], v[224:225], v[202:203] neg_lo:[0,0,1] neg_hi:[0,0,1]
	v_cvt_f32_f16_sdwa v223, v205 dst_sel:DWORD dst_unused:UNUSED_PAD src0_sel:WORD_1
	v_cvt_f32_f16_e32 v225, v205
	v_cvt_f32_f16_e32 v224, v204
	v_cvt_f32_f16_sdwa v222, v204 dst_sel:DWORD dst_unused:UNUSED_PAD src0_sel:WORD_1
	v_pk_mul_f32 v[204:205], v[128:129], v[188:189] op_sel_hi:[0,1]
	v_cvt_pk_bf16_f32 v212, v202, v203
	v_pk_mul_f32 v[202:203], v[128:129], v[192:193] op_sel_hi:[0,1]
	v_pk_mul_f32 v[204:205], v[50:51], v[204:205]
	v_pk_mul_f32 v[202:203], v[58:59], v[202:203]
	v_pk_mul_f32 v[226:227], v[204:205], v[224:225]
	v_pk_mul_f32 v[204:205], v[204:205], v[222:223]
	v_pk_fma_f32 v[226:227], v[202:203], v[222:223], v[226:227]
	v_pk_fma_f32 v[202:203], v[202:203], v[224:225], v[204:205] neg_lo:[0,0,1] neg_hi:[0,0,1]
	v_fmac_f32_e32 v153, v44, v44
	v_cvt_pk_bf16_f32 v213, v202, v203
	global_load_dwordx4 v[202:205], v[198:199], off offset:2064
	v_fmac_f32_e32 v179, v45, v45
	v_pk_mul_f32 v[222:223], v[38:39], v[38:39]
	v_add_f32_e32 v153, v153, v179
	v_pk_fma_f32 v[222:223], v[46:47], v[46:47], v[222:223]
	v_pk_mul_f32 v[224:225], v[32:33], v[32:33]
	v_add_f32_e32 v153, v222, v153
	v_add_f32_e32 v153, v223, v153
	v_pk_fma_f32 v[224:225], v[40:41], v[40:41], v[224:225]
	v_pk_mul_f32 v[222:223], v[34:35], v[34:35]
	v_add_f32_e32 v153, v224, v153
	v_pk_fma_f32 v[222:223], v[42:43], v[42:43], v[222:223]
	v_add_f32_e32 v153, v225, v153
	v_add_f32_e32 v153, v222, v153
	v_add_f32_e32 v153, v223, v153
	ds_bpermute_b32 v179, v169, v153
	v_ashrrev_i32_e32 v128, 31, v201
	v_mul_lo_u32 v128, s60, v128
	v_mul_lo_u32 v217, s61, v201
	v_mad_u64_u32 v[222:223], s[8:9], s60, v201, 0
	s_waitcnt lgkmcnt(0)
	v_add_f32_e32 v153, v153, v179
	ds_bpermute_b32 v179, v177, v153
	v_add3_u32 v223, v223, v128, v217
	v_lshl_add_u64 v[222:223], v[222:223], 1, v[180:181]
	v_cvt_pk_bf16_f32 v220, v220, v221
	v_cvt_pk_bf16_f32 v221, v226, v227
	s_waitcnt lgkmcnt(0)
	v_add_f32_e32 v128, v153, v179
	v_mul_f32_e32 v128, v160, v128
	v_mul_f32_e32 v128, v160, v128
	v_fmamk_f32 v128, v128, 0x3c800000, v143
	v_mul_f32_e32 v153, 0x4b800000, v128
	v_cmp_gt_f32_e32 vcc, s37, v128
	global_store_dwordx4 v[222:223], v[210:213], off
	global_store_dwordx4 v[222:223], v[218:221], off offset:64
	v_cndmask_b32_e32 v128, v128, v153, vcc
	v_rsq_f32_e32 v128, v128
	v_lshl_add_u64 v[222:223], v[198:199], 0, s[16:17]
	v_mul_f32_e32 v201, v21, v21
	v_mul_f32_e32 v179, 0x45800000, v128
	v_cndmask_b32_e32 v128, v128, v179, vcc
	v_mul_f32_e32 v128, v160, v128
	v_mul_f32_e32 v128, s83, v128
	v_pk_mul_f32 v[210:211], v[128:129], v[196:197] op_sel_hi:[0,1]
	v_pk_mul_f32 v[210:211], v[44:45], v[210:211]
	v_add_co_u32_e32 v226, vcc, s36, v198
	v_mul_f32_e32 v179, v20, v20
	s_nop 0
	v_addc_co_u32_e32 v227, vcc, 0, v199, vcc
	v_fmac_f32_e32 v179, v28, v28
	s_waitcnt vmcnt(3)
	v_cvt_f32_f16_sdwa v213, v207 dst_sel:DWORD dst_unused:UNUSED_PAD src0_sel:WORD_1
	v_cvt_f32_f16_e32 v219, v207
	v_cvt_f32_f16_e32 v218, v206
	v_cvt_f32_f16_sdwa v212, v206 dst_sel:DWORD dst_unused:UNUSED_PAD src0_sel:WORD_1
	v_pk_mul_f32 v[206:207], v[128:129], v[194:195] op_sel_hi:[0,1]
	v_pk_mul_f32 v[206:207], v[36:37], v[206:207]
	v_fmac_f32_e32 v201, v29, v29
	v_pk_mul_f32 v[220:221], v[206:207], v[218:219]
	v_pk_mul_f32 v[206:207], v[206:207], v[212:213]
	v_pk_fma_f32 v[220:221], v[210:211], v[212:213], v[220:221]
	v_pk_fma_f32 v[210:211], v[210:211], v[218:219], v[206:207] neg_lo:[0,0,1] neg_hi:[0,0,1]
	v_cvt_f32_f16_sdwa v213, v209 dst_sel:DWORD dst_unused:UNUSED_PAD src0_sel:WORD_1
	v_cvt_f32_f16_e32 v219, v209
	v_cvt_f32_f16_e32 v218, v208
	v_cvt_f32_f16_sdwa v212, v208 dst_sel:DWORD dst_unused:UNUSED_PAD src0_sel:WORD_1
	v_pk_mul_f32 v[208:209], v[128:129], v[186:187] op_sel_hi:[0,1]
	v_pk_mul_f32 v[206:207], v[128:129], v[190:191] op_sel_hi:[0,1]
	v_pk_mul_f32 v[208:209], v[38:39], v[208:209]
	v_pk_mul_f32 v[206:207], v[46:47], v[206:207]
	v_pk_mul_f32 v[224:225], v[208:209], v[218:219]
	v_pk_mul_f32 v[208:209], v[208:209], v[212:213]
	v_pk_fma_f32 v[224:225], v[206:207], v[212:213], v[224:225]
	v_pk_fma_f32 v[212:213], v[206:207], v[218:219], v[208:209] neg_lo:[0,0,1] neg_hi:[0,0,1]
	global_load_dwordx4 v[206:209], v[226:227], off
	v_cvt_pk_bf16_f32 v219, v224, v225
	v_cvt_pk_bf16_f32 v210, v210, v211
	v_cvt_pk_bf16_f32 v211, v212, v213
	v_pk_mul_f32 v[212:213], v[128:129], v[184:185] op_sel_hi:[0,1]
	v_cvt_pk_bf16_f32 v218, v220, v221
	s_waitcnt vmcnt(3)
	v_cvt_f32_f16_sdwa v225, v203 dst_sel:DWORD dst_unused:UNUSED_PAD src0_sel:WORD_1
	v_cvt_f32_f16_e32 v229, v203
	v_cvt_f32_f16_e32 v228, v202
	v_cvt_f32_f16_sdwa v224, v202 dst_sel:DWORD dst_unused:UNUSED_PAD src0_sel:WORD_1
	v_pk_mul_f32 v[202:203], v[128:129], v[182:183] op_sel_hi:[0,1]
	v_pk_mul_f32 v[202:203], v[32:33], v[202:203]
	v_pk_mul_f32 v[212:213], v[40:41], v[212:213]
	v_pk_mul_f32 v[220:221], v[202:203], v[228:229]
	v_pk_mul_f32 v[202:203], v[202:203], v[224:225]
	v_cvt_f32_f16_e32 v231, v205
	v_pk_fma_f32 v[202:203], v[212:213], v[228:229], v[202:203] neg_lo:[0,0,1] neg_hi:[0,0,1]
	v_cvt_f32_f16_e32 v230, v204
	v_pk_fma_f32 v[220:221], v[212:213], v[224:225], v[220:221]
	v_cvt_pk_bf16_f32 v212, v202, v203
	v_pk_mul_f32 v[202:203], v[128:129], v[192:193] op_sel_hi:[0,1]
	v_cvt_f32_f16_sdwa v229, v205 dst_sel:DWORD dst_unused:UNUSED_PAD src0_sel:WORD_1
	v_cvt_f32_f16_sdwa v228, v204 dst_sel:DWORD dst_unused:UNUSED_PAD src0_sel:WORD_1
	v_pk_mul_f32 v[224:225], v[42:43], v[202:203]
	v_pk_mul_f32 v[202:203], v[128:129], v[188:189] op_sel_hi:[0,1]
	v_pk_mul_f32 v[234:235], v[34:35], v[202:203]
	v_add_f32_e32 v179, v179, v201
	v_pk_mul_f32 v[202:203], v[234:235], v[230:231]
	v_add_u32_e32 v153, 0x90, v156
	v_pk_fma_f32 v[236:237], v[224:225], v[228:229], v[202:203]
	global_load_dwordx4 v[202:205], v[222:223], off offset:16
	v_pk_mul_f32 v[222:223], v[234:235], v[228:229]
	v_ashrrev_i32_e32 v128, 31, v153
	v_pk_fma_f32 v[222:223], v[224:225], v[230:231], v[222:223] neg_lo:[0,0,1] neg_hi:[0,0,1]
	v_pk_mul_f32 v[224:225], v[16:17], v[16:17]
	v_cvt_pk_bf16_f32 v213, v222, v223
	v_pk_mul_f32 v[222:223], v[22:23], v[22:23]
	v_pk_fma_f32 v[224:225], v[24:25], v[24:25], v[224:225]
	v_pk_fma_f32 v[222:223], v[30:31], v[30:31], v[222:223]
	v_mul_lo_u32 v217, s61, v153
	v_add_f32_e32 v179, v222, v179
	v_add_f32_e32 v179, v223, v179
	v_pk_mul_f32 v[222:223], v[18:19], v[18:19]
	v_add_f32_e32 v179, v224, v179
	v_pk_fma_f32 v[222:223], v[26:27], v[26:27], v[222:223]
	v_add_f32_e32 v179, v225, v179
	v_add_f32_e32 v179, v222, v179
	v_add_f32_e32 v179, v223, v179
	ds_bpermute_b32 v201, v169, v179
	v_mad_u64_u32 v[222:223], s[8:9], s60, v153, 0
	v_mul_lo_u32 v128, s60, v128
	v_add3_u32 v223, v223, v128, v217
	s_waitcnt lgkmcnt(0)
	v_add_f32_e32 v153, v179, v201
	ds_bpermute_b32 v179, v177, v153
	v_lshl_add_u64 v[222:223], v[222:223], 1, v[180:181]
	v_cvt_pk_bf16_f32 v220, v220, v221
	v_cvt_pk_bf16_f32 v221, v236, v237
	global_store_dwordx4 v[222:223], v[210:213], off
	global_store_dwordx4 v[222:223], v[218:221], off offset:64
	s_waitcnt lgkmcnt(0)
	v_add_f32_e32 v128, v153, v179
	v_mul_f32_e32 v128, v158, v128
	v_mul_f32_e32 v128, v158, v128
	v_fmamk_f32 v128, v128, 0x3c800000, v143
	v_mul_f32_e32 v153, 0x4b800000, v128
	v_cmp_gt_f32_e32 vcc, s37, v128
	v_lshl_add_u64 v[198:199], v[198:199], 0, s[18:19]
	s_waitcnt vmcnt(3)
	v_cvt_f32_f16_sdwa v213, v207 dst_sel:DWORD dst_unused:UNUSED_PAD src0_sel:WORD_1
	v_cndmask_b32_e32 v128, v128, v153, vcc
	v_rsq_f32_e32 v128, v128
	v_cvt_f32_f16_e32 v219, v207
	v_cvt_f32_f16_e32 v218, v206
	v_cvt_f32_f16_sdwa v212, v206 dst_sel:DWORD dst_unused:UNUSED_PAD src0_sel:WORD_1
	v_mul_f32_e32 v179, 0x45800000, v128
	v_cndmask_b32_e32 v128, v128, v179, vcc
	v_mul_f32_e32 v128, v158, v128
	v_mul_f32_e32 v128, s83, v128
	v_pk_mul_f32 v[206:207], v[128:129], v[194:195] op_sel_hi:[0,1]
	v_pk_mul_f32 v[210:211], v[128:129], v[196:197] op_sel_hi:[0,1]
	v_pk_mul_f32 v[206:207], v[20:21], v[206:207]
	v_pk_mul_f32 v[210:211], v[28:29], v[210:211]
	v_pk_mul_f32 v[220:221], v[206:207], v[218:219]
	v_pk_mul_f32 v[206:207], v[206:207], v[212:213]
	v_pk_fma_f32 v[220:221], v[210:211], v[212:213], v[220:221]
	v_pk_fma_f32 v[210:211], v[210:211], v[218:219], v[206:207] neg_lo:[0,0,1] neg_hi:[0,0,1]
	v_pk_mul_f32 v[206:207], v[128:129], v[190:191] op_sel_hi:[0,1]
	v_cvt_f32_f16_e32 v219, v209
	v_cvt_f32_f16_e32 v218, v208
	v_pk_mul_f32 v[212:213], v[30:31], v[206:207]
	v_cvt_f32_f16_sdwa v207, v209 dst_sel:DWORD dst_unused:UNUSED_PAD src0_sel:WORD_1
	v_cvt_f32_f16_sdwa v206, v208 dst_sel:DWORD dst_unused:UNUSED_PAD src0_sel:WORD_1
	v_pk_mul_f32 v[208:209], v[128:129], v[186:187] op_sel_hi:[0,1]
	v_pk_mul_f32 v[208:209], v[22:23], v[208:209]
	v_cvt_pk_bf16_f32 v210, v210, v211
	v_pk_mul_f32 v[222:223], v[208:209], v[218:219]
	v_pk_mul_f32 v[224:225], v[208:209], v[206:207]
	v_pk_fma_f32 v[222:223], v[212:213], v[206:207], v[222:223]
	global_load_dwordx4 v[206:209], v[226:227], off offset:2048
	v_pk_fma_f32 v[212:213], v[212:213], v[218:219], v[224:225] neg_lo:[0,0,1] neg_hi:[0,0,1]
	v_cvt_pk_bf16_f32 v219, v222, v223
	s_waitcnt vmcnt(3)
	v_cvt_f32_f16_sdwa v223, v203 dst_sel:DWORD dst_unused:UNUSED_PAD src0_sel:WORD_1
	v_cvt_f32_f16_e32 v225, v203
	v_cvt_f32_f16_e32 v224, v202
	v_cvt_f32_f16_sdwa v222, v202 dst_sel:DWORD dst_unused:UNUSED_PAD src0_sel:WORD_1
	v_pk_mul_f32 v[202:203], v[128:129], v[182:183] op_sel_hi:[0,1]
	v_cvt_pk_bf16_f32 v211, v212, v213
	v_pk_mul_f32 v[212:213], v[128:129], v[184:185] op_sel_hi:[0,1]
	v_pk_mul_f32 v[202:203], v[16:17], v[202:203]
	v_cvt_pk_bf16_f32 v218, v220, v221
	v_pk_mul_f32 v[212:213], v[24:25], v[212:213]
	v_pk_mul_f32 v[220:221], v[202:203], v[224:225]
	v_pk_mul_f32 v[202:203], v[202:203], v[222:223]
	v_pk_fma_f32 v[220:221], v[212:213], v[222:223], v[220:221]
	v_pk_fma_f32 v[202:203], v[212:213], v[224:225], v[202:203] neg_lo:[0,0,1] neg_hi:[0,0,1]
	v_cvt_f32_f16_sdwa v225, v205 dst_sel:DWORD dst_unused:UNUSED_PAD src0_sel:WORD_1
	v_cvt_pk_bf16_f32 v212, v202, v203
	v_pk_mul_f32 v[202:203], v[128:129], v[192:193] op_sel_hi:[0,1]
	v_pk_mul_f32 v[222:223], v[26:27], v[202:203]
	v_pk_mul_f32 v[202:203], v[128:129], v[188:189] op_sel_hi:[0,1]
	v_cvt_f32_f16_sdwa v224, v204 dst_sel:DWORD dst_unused:UNUSED_PAD src0_sel:WORD_1
	v_cvt_f32_f16_e32 v227, v205
	v_cvt_f32_f16_e32 v226, v204
	v_pk_mul_f32 v[228:229], v[18:19], v[202:203]
	global_load_dwordx4 v[202:205], v[198:199], off offset:16
	v_cvt_pk_bf16_f32 v220, v220, v221
	v_pk_mul_f32 v[198:199], v[228:229], v[226:227]
	v_mul_f32_e32 v128, v4, v4
	v_pk_fma_f32 v[198:199], v[222:223], v[224:225], v[198:199]
	v_mul_f32_e32 v179, v5, v5
	v_cvt_pk_bf16_f32 v221, v198, v199
	v_pk_mul_f32 v[198:199], v[228:229], v[224:225]
	v_fmac_f32_e32 v128, v12, v12
	v_pk_fma_f32 v[198:199], v[222:223], v[226:227], v[198:199] neg_lo:[0,0,1] neg_hi:[0,0,1]
	v_fmac_f32_e32 v179, v13, v13
	v_pk_mul_f32 v[222:223], v[6:7], v[6:7]
	v_add_f32_e32 v128, v128, v179
	v_pk_fma_f32 v[222:223], v[14:15], v[14:15], v[222:223]
	v_pk_mul_f32 v[224:225], v[0:1], v[0:1]
	v_add_f32_e32 v128, v222, v128
	v_add_f32_e32 v128, v223, v128
	v_pk_fma_f32 v[224:225], v[8:9], v[8:9], v[224:225]
	v_pk_mul_f32 v[222:223], v[2:3], v[2:3]
	v_add_f32_e32 v128, v224, v128
	v_pk_fma_f32 v[222:223], v[10:11], v[10:11], v[222:223]
	v_add_f32_e32 v128, v225, v128
	v_add_f32_e32 v128, v222, v128
	v_add_f32_e32 v128, v223, v128
	ds_bpermute_b32 v169, v169, v128
	v_add_u32_e32 v153, 0xa0, v156
	v_cvt_pk_bf16_f32 v213, v198, v199
	v_ashrrev_i32_e32 v179, 31, v153
	v_mul_lo_u32 v201, s61, v153
	s_waitcnt lgkmcnt(0)
	v_add_f32_e32 v128, v128, v169
	ds_bpermute_b32 v169, v177, v128
	v_mad_u64_u32 v[198:199], s[8:9], s60, v153, 0
	v_mul_lo_u32 v179, s60, v179
	v_add3_u32 v199, v199, v179, v201
	s_waitcnt lgkmcnt(0)
	v_add_f32_e32 v128, v128, v169
	v_mul_f32_e32 v128, v154, v128
	v_mul_f32_e32 v128, v154, v128
	v_fmamk_f32 v128, v128, 0x3c800000, v143
	v_mul_f32_e32 v153, 0x4b800000, v128
	v_cmp_gt_f32_e32 vcc, s37, v128
	v_lshl_add_u64 v[198:199], v[198:199], 1, v[180:181]
	global_store_dwordx4 v[198:199], v[210:213], off
	v_cndmask_b32_e32 v128, v128, v153, vcc
	v_rsq_f32_e32 v128, v128
	global_store_dwordx4 v[198:199], v[218:221], off offset:64
	v_add_u32_e32 v153, 0xb0, v156
	v_mul_f32_e32 v169, 0x45800000, v128
	v_cndmask_b32_e32 v128, v128, v169, vcc
	v_mul_f32_e32 v128, v154, v128
	v_mul_f32_e32 v128, s83, v128
	v_pk_mul_f32 v[194:195], v[128:129], v[194:195] op_sel_hi:[0,1]
	v_pk_mul_f32 v[196:197], v[128:129], v[196:197] op_sel_hi:[0,1]
	s_waitcnt vmcnt(3)
	v_cvt_f32_f16_sdwa v199, v207 dst_sel:DWORD dst_unused:UNUSED_PAD src0_sel:WORD_1
	v_cvt_f32_f16_e32 v211, v207
	v_cvt_f32_f16_e32 v210, v206
	v_cvt_f32_f16_sdwa v198, v206 dst_sel:DWORD dst_unused:UNUSED_PAD src0_sel:WORD_1
	v_pk_mul_f32 v[194:195], v[4:5], v[194:195]
	v_pk_mul_f32 v[196:197], v[12:13], v[196:197]
	v_pk_mul_f32 v[206:207], v[194:195], v[210:211]
	v_pk_mul_f32 v[194:195], v[194:195], v[198:199]
	v_pk_fma_f32 v[206:207], v[196:197], v[198:199], v[206:207]
	v_pk_fma_f32 v[194:195], v[196:197], v[210:211], v[194:195] neg_lo:[0,0,1] neg_hi:[0,0,1]
	v_cvt_f32_f16_sdwa v197, v209 dst_sel:DWORD dst_unused:UNUSED_PAD src0_sel:WORD_1
	v_cvt_f32_f16_e32 v199, v209
	v_cvt_f32_f16_e32 v198, v208
	v_cvt_f32_f16_sdwa v196, v208 dst_sel:DWORD dst_unused:UNUSED_PAD src0_sel:WORD_1
	v_pk_mul_f32 v[186:187], v[128:129], v[186:187] op_sel_hi:[0,1]
	v_pk_mul_f32 v[190:191], v[128:129], v[190:191] op_sel_hi:[0,1]
	v_pk_mul_f32 v[186:187], v[6:7], v[186:187]
	v_pk_mul_f32 v[190:191], v[14:15], v[190:191]
	v_pk_mul_f32 v[208:209], v[186:187], v[198:199]
	v_pk_mul_f32 v[186:187], v[186:187], v[196:197]
	v_pk_fma_f32 v[208:209], v[190:191], v[196:197], v[208:209]
	v_pk_fma_f32 v[186:187], v[190:191], v[198:199], v[186:187] neg_lo:[0,0,1] neg_hi:[0,0,1]
	v_cvt_pk_bf16_f32 v194, v194, v195
	v_cvt_pk_bf16_f32 v195, v186, v187
	v_pk_mul_f32 v[182:183], v[128:129], v[182:183] op_sel_hi:[0,1]
	v_pk_mul_f32 v[184:185], v[128:129], v[184:185] op_sel_hi:[0,1]
	s_waitcnt vmcnt(2)
	v_cvt_f32_f16_e32 v191, v203
	v_cvt_f32_f16_e32 v190, v202
	v_cvt_f32_f16_sdwa v187, v203 dst_sel:DWORD dst_unused:UNUSED_PAD src0_sel:WORD_1
	v_cvt_f32_f16_sdwa v186, v202 dst_sel:DWORD dst_unused:UNUSED_PAD src0_sel:WORD_1
	v_pk_mul_f32 v[182:183], v[0:1], v[182:183]
	v_pk_mul_f32 v[184:185], v[8:9], v[184:185]
	v_pk_mul_f32 v[196:197], v[182:183], v[190:191]
	v_pk_mul_f32 v[182:183], v[182:183], v[186:187]
	v_pk_fma_f32 v[196:197], v[184:185], v[186:187], v[196:197]
	v_cvt_f32_f16_e32 v187, v205
	v_cvt_f32_f16_e32 v186, v204
	v_pk_fma_f32 v[182:183], v[184:185], v[190:191], v[182:183] neg_lo:[0,0,1] neg_hi:[0,0,1]
	v_cvt_f32_f16_sdwa v185, v205 dst_sel:DWORD dst_unused:UNUSED_PAD src0_sel:WORD_1
	v_cvt_f32_f16_sdwa v184, v204 dst_sel:DWORD dst_unused:UNUSED_PAD src0_sel:WORD_1
	v_pk_mul_f32 v[188:189], v[128:129], v[188:189] op_sel_hi:[0,1]
	v_cvt_pk_bf16_f32 v206, v206, v207
	v_cvt_pk_bf16_f32 v207, v208, v209
	v_cvt_pk_bf16_f32 v208, v196, v197
	v_cvt_pk_bf16_f32 v196, v182, v183
	v_pk_mul_f32 v[182:183], v[128:129], v[192:193] op_sel_hi:[0,1]
	v_pk_mul_f32 v[188:189], v[2:3], v[188:189]
	v_pk_mul_f32 v[182:183], v[10:11], v[182:183]
	v_pk_mul_f32 v[190:191], v[188:189], v[186:187]
	v_ashrrev_i32_e32 v128, 31, v153
	v_pk_fma_f32 v[190:191], v[182:183], v[184:185], v[190:191]
	v_pk_mul_f32 v[184:185], v[188:189], v[184:185]
	v_mul_lo_u32 v128, s60, v128
	v_pk_fma_f32 v[182:183], v[182:183], v[186:187], v[184:185] neg_lo:[0,0,1] neg_hi:[0,0,1]
	v_mul_lo_u32 v169, s61, v153
	v_cvt_pk_bf16_f32 v197, v182, v183
	v_mad_u64_u32 v[182:183], s[8:9], s60, v153, 0
	v_add3_u32 v183, v183, v128, v169
	v_lshl_add_u64 v[180:181], v[182:183], 1, v[180:181]
	v_cvt_pk_bf16_f32 v209, v190, v191
	global_store_dwordx4 v[180:181], v[194:197], off
	global_store_dwordx4 v[180:181], v[206:209], off offset:64
	s_mov_b64 s[8:9], 0

.LBB0_2132:
	s_lshl_b32 s6, s86, 12
	s_and_b32 s6, s6, 0x1000
	v_add_u32_e32 v128, s6, v179
	ds_read_b128 v[180:183], v128
	ds_read_b128 v[184:187], v128 offset:256
	ds_read_b128 v[188:191], v128 offset:512
	ds_read_b128 v[192:195], v128 offset:768
	ds_read_b128 v[196:199], v128 offset:1024
	ds_read_b128 v[202:205], v128 offset:1280
	s_waitcnt lgkmcnt(0)
	v_mov_b32_e32 v156, v181
	v_mov_b32_e32 v157, v182
	v_mov_b32_e32 v181, v183
	v_mov_b32_e32 v166, v185
	v_mov_b32_e32 v167, v186
	v_mov_b32_e32 v185, v187
	v_pk_add_f32 v[156:157], v[156:157], v[180:181]
	v_pk_add_f32 v[166:167], v[166:167], v[184:185]
	v_mov_b32_e32 v171, v156
	v_mov_b32_e32 v170, v166
	v_mov_b32_e32 v156, v167
	v_pk_add_f32 v[156:157], v[170:171], v[156:157]
	v_mov_b64_e32 v[166:167], s[20:21]
	v_pk_fma_f32 v[156:157], v[156:157], s[18:19], v[166:167] op_sel_hi:[1,0,0]
	v_mov_b32_e32 v170, v193
	v_mul_f32_e32 v153, 0x4b800000, v157
	v_cmp_gt_f32_e32 vcc, s19, v157
	v_mul_f32_e32 v154, 0x4b800000, v156
	v_cmp_gt_f32_e64 s[6:7], s19, v156
	v_cndmask_b32_e32 v153, v157, v153, vcc
	v_rsq_f32_e32 v153, v153
	v_cndmask_b32_e64 v154, v156, v154, s[6:7]
	v_mov_b32_e32 v156, v189
	v_mov_b32_e32 v157, v190
	v_mov_b32_e32 v189, v191
	v_mov_b32_e32 v171, v194
	v_mov_b32_e32 v193, v195
	v_pk_add_f32 v[156:157], v[156:157], v[188:189]
	v_pk_add_f32 v[170:171], v[170:171], v[192:193]
	v_mov_b32_e32 v177, v156
	v_mov_b32_e32 v176, v170
	v_mov_b32_e32 v156, v171
	v_pk_add_f32 v[156:157], v[176:177], v[156:157]
	ds_read_b128 v[180:183], v128 offset:1536
	ds_read_b128 v[184:187], v128 offset:1792
	v_mul_f32_e32 v128, 0x45800000, v153
	v_pk_fma_f32 v[156:157], v[156:157], s[18:19], v[166:167] op_sel_hi:[1,0,0]
	v_cndmask_b32_e32 v178, v153, v128, vcc
	v_mul_f32_e32 v153, 0x4b800000, v157
	v_cmp_gt_f32_e32 vcc, s19, v157
	v_cmp_gt_f32_e64 s[8:9], s19, v156
	v_rsq_f32_e32 v154, v154
	v_cndmask_b32_e32 v153, v157, v153, vcc
	v_mul_f32_e32 v157, 0x4b800000, v156
	v_cndmask_b32_e64 v156, v156, v157, s[8:9]
	v_rsq_f32_e32 v153, v153
	v_rsq_f32_e32 v158, v156
	v_mov_b32_e32 v156, v197
	v_mov_b32_e32 v157, v198
	v_mov_b32_e32 v197, v199
	v_mov_b32_e32 v170, v203
	v_mov_b32_e32 v171, v204
	v_mov_b32_e32 v203, v205
	v_pk_add_f32 v[156:157], v[156:157], v[196:197]
	v_pk_add_f32 v[170:171], v[170:171], v[202:203]
	v_mov_b32_e32 v177, v156
	v_mov_b32_e32 v176, v170
	v_mov_b32_e32 v156, v171
	v_mul_f32_e32 v128, 0x45800000, v154
	v_pk_add_f32 v[156:157], v[176:177], v[156:157]
	v_cndmask_b32_e64 v172, v154, v128, s[6:7]
	v_mul_f32_e32 v128, 0x45800000, v153
	v_pk_fma_f32 v[156:157], v[156:157], s[18:19], v[166:167] op_sel_hi:[1,0,0]
	v_cndmask_b32_e32 v168, v153, v128, vcc
	v_mul_f32_e32 v153, 0x4b800000, v157
	v_cmp_gt_f32_e32 vcc, s19, v157
	v_mul_f32_e32 v154, 0x4b800000, v156
	v_cmp_gt_f32_e64 s[6:7], s19, v156
	v_cndmask_b32_e32 v153, v157, v153, vcc
	v_rsq_f32_e32 v153, v153
	v_cndmask_b32_e64 v154, v156, v154, s[6:7]
	s_waitcnt lgkmcnt(0)
	v_mov_b32_e32 v156, v181
	v_mov_b32_e32 v157, v182
	v_mov_b32_e32 v181, v183
	v_mov_b32_e32 v170, v185
	v_mov_b32_e32 v171, v186
	v_mov_b32_e32 v185, v187
	v_pk_add_f32 v[156:157], v[156:157], v[180:181]
	v_pk_add_f32 v[170:171], v[170:171], v[184:185]
	v_mov_b32_e32 v177, v156
	v_mov_b32_e32 v176, v170
	v_mov_b32_e32 v156, v171
	v_mul_f32_e32 v128, 0x45800000, v158
	v_pk_add_f32 v[156:157], v[176:177], v[156:157]
	v_cndmask_b32_e64 v164, v158, v128, s[8:9]
	v_mul_f32_e32 v128, 0x45800000, v153
	v_pk_fma_f32 v[156:157], v[156:157], s[18:19], v[166:167] op_sel_hi:[1,0,0]
	v_cndmask_b32_e32 v162, v153, v128, vcc
	v_mul_f32_e32 v153, 0x4b800000, v157
	v_cmp_gt_f32_e32 vcc, s19, v157
	v_rsq_f32_e32 v154, v154
	v_cmp_gt_f32_e64 s[8:9], s19, v156
	v_cndmask_b32_e32 v153, v157, v153, vcc
	v_mul_f32_e32 v157, 0x4b800000, v156
	v_rsq_f32_e32 v153, v153
	v_cndmask_b32_e64 v156, v156, v157, s[8:9]
	v_rsq_f32_e32 v156, v156
	v_mul_f32_e32 v128, 0x45800000, v154
	v_cndmask_b32_e64 v160, v154, v128, s[6:7]
	v_mul_f32_e32 v128, 0x45800000, v153
	v_cndmask_b32_e32 v158, v153, v128, vcc
	v_mul_f32_e32 v128, 0x45800000, v156
	v_lshl_or_b32 v174, s57, 6, v142
	v_cndmask_b32_e64 v154, v156, v128, s[8:9]
	v_lshl_add_u32 v156, s66, 8, v169
	s_mov_b64 s[6:7], -1
	s_andn2_b64 vcc, exec, s[68:69]
	v_ashrrev_i32_e32 v175, 31, v174
	v_ashrrev_i32_e32 v157, 31, v156
	v_or_b32_e32 v176, 16, v156
	v_or_b32_e32 v170, 32, v156
	v_or_b32_e32 v166, 48, v156
	s_cbranch_vccz .LBB0_2134
	v_lshlrev_b32_e32 v128, 7, v156
	v_lshl_add_u64 v[180:181], s[70:71], 2, v[144:145]
	v_and_b32_e32 v128, 0x3e780, v128
	global_load_dwordx4 v[182:185], v[180:181], off
	global_load_dwordx4 v[202:205], v[180:181], off offset:16
	v_mov_b32_e32 v153, v129
	v_lshl_add_u64 v[180:181], s[34:35], 0, v[128:129]
	v_lshl_add_u64 v[198:199], v[180:181], 0, v[152:153]
	global_load_dwordx4 v[206:209], v[198:199], off
	global_load_dwordx4 v[216:219], v[198:199], off offset:16
	v_cmp_lt_i32_e32 vcc, v213, v212
	v_mul_f32_e32 v171, v116, v116
	v_mul_f32_e32 v177, v117, v117
	v_cndmask_b32_e32 v128, v159, v213, vcc
	v_pk_mul_f32 v[180:181], v[118:119], v[118:119]
	v_fmac_f32_e32 v171, v124, v124
	v_fmac_f32_e32 v177, v125, v125
	v_lshlrev_b32_e32 v167, 2, v128
	v_pk_fma_f32 v[180:181], v[126:127], v[126:127], v[180:181]
	v_add_f32_e32 v128, v171, v177
	v_pk_mul_f32 v[188:189], v[112:113], v[112:113]
	v_add_f32_e32 v128, v180, v128
	v_pk_fma_f32 v[188:189], v[120:121], v[120:121], v[188:189]
	v_add_f32_e32 v128, v181, v128
	v_pk_mul_f32 v[186:187], v[114:115], v[114:115]
	v_add_f32_e32 v128, v188, v128
	v_pk_fma_f32 v[186:187], v[122:123], v[122:123], v[186:187]
	v_add_f32_e32 v128, v189, v128
	v_add_f32_e32 v128, v186, v128
	v_add_f32_e32 v128, v187, v128
	ds_bpermute_b32 v177, v167, v128
	v_cmp_lt_i32_e32 vcc, v214, v212
	global_load_dwordx4 v[220:223], v[198:199], off offset:2048
	v_mul_lo_u32 v215, s65, v156
	v_cndmask_b32_e32 v171, v159, v214, vcc
	v_lshlrev_b32_e32 v171, 2, v171
	s_waitcnt lgkmcnt(0)
	v_add_f32_e32 v128, v128, v177
	ds_bpermute_b32 v177, v171, v128
	v_lshl_add_u64 v[180:181], v[174:175], 1, s[48:49]
	v_pk_mul_f32 v[236:237], v[80:81], v[80:81]
	s_waitcnt lgkmcnt(0)
	v_add_f32_e32 v128, v128, v177
	v_mul_f32_e32 v128, v178, v128
	v_mul_f32_e32 v128, v178, v128
	v_fmamk_f32 v128, v128, 0x3c800000, v143
	v_mul_f32_e32 v177, 0x4b800000, v128
	v_cmp_gt_f32_e32 vcc, s19, v128
	v_pk_fma_f32 v[236:237], v[88:89], v[88:89], v[236:237]
	s_waitcnt vmcnt(4)
	v_cvt_f32_f16_sdwa v187, v185 dst_sel:DWORD dst_unused:UNUSED_PAD src0_sel:WORD_1
	v_cndmask_b32_e32 v128, v128, v177, vcc
	v_rsq_f32_e32 v128, v128
	v_cvt_f32_f16_sdwa v186, v184 dst_sel:DWORD dst_unused:UNUSED_PAD src0_sel:WORD_1
	v_cvt_f32_f16_sdwa v195, v183 dst_sel:DWORD dst_unused:UNUSED_PAD src0_sel:WORD_1
	v_cvt_f32_f16_sdwa v194, v182 dst_sel:DWORD dst_unused:UNUSED_PAD src0_sel:WORD_1
	v_mul_f32_e32 v177, 0x45800000, v128
	v_cndmask_b32_e32 v128, v128, v177, vcc
	v_cvt_f32_f16_e32 v191, v185
	v_cvt_f32_f16_e32 v190, v184
	v_mul_f32_e32 v128, v178, v128
	v_cvt_f32_f16_e32 v197, v183
	v_cvt_f32_f16_e32 v196, v182
	s_waitcnt vmcnt(2)
	v_cvt_f32_f16_sdwa v189, v207 dst_sel:DWORD dst_unused:UNUSED_PAD src0_sel:WORD_1
	v_cvt_f32_f16_sdwa v188, v206 dst_sel:DWORD dst_unused:UNUSED_PAD src0_sel:WORD_1
	v_cvt_f32_f16_e32 v193, v207
	v_cvt_f32_f16_e32 v192, v206
	v_cvt_f32_f16_e32 v207, v209
	v_cvt_f32_f16_e32 v206, v208
	v_mul_f32_e32 v128, s85, v128
	v_cvt_f32_f16_e32 v185, v203
	v_cvt_f32_f16_e32 v184, v202
	v_cvt_f32_f16_sdwa v183, v203 dst_sel:DWORD dst_unused:UNUSED_PAD src0_sel:WORD_1
	v_cvt_f32_f16_sdwa v182, v202 dst_sel:DWORD dst_unused:UNUSED_PAD src0_sel:WORD_1
	v_cvt_f32_f16_sdwa v203, v209 dst_sel:DWORD dst_unused:UNUSED_PAD src0_sel:WORD_1
	v_cvt_f32_f16_sdwa v202, v208 dst_sel:DWORD dst_unused:UNUSED_PAD src0_sel:WORD_1
	v_pk_mul_f32 v[226:227], v[128:129], v[186:187] op_sel_hi:[0,1]
	v_pk_mul_f32 v[210:211], v[128:129], v[194:195] op_sel_hi:[0,1]
	v_pk_mul_f32 v[224:225], v[128:129], v[190:191] op_sel_hi:[0,1]
	v_pk_mul_f32 v[226:227], v[118:119], v[226:227]
	v_pk_mul_f32 v[208:209], v[128:129], v[196:197] op_sel_hi:[0,1]
	v_pk_mul_f32 v[210:211], v[116:117], v[210:211]
	v_pk_mul_f32 v[224:225], v[126:127], v[224:225]
	v_pk_mul_f32 v[234:235], v[226:227], v[206:207]
	v_pk_mul_f32 v[208:209], v[124:125], v[208:209]
	v_pk_mul_f32 v[230:231], v[210:211], v[192:193]
	v_pk_mul_f32 v[210:211], v[210:211], v[188:189]
	v_pk_mul_f32 v[226:227], v[226:227], v[202:203]
	v_pk_fma_f32 v[202:203], v[224:225], v[202:203], v[234:235]
	v_pk_fma_f32 v[188:189], v[208:209], v[188:189], v[230:231]
	v_pk_fma_f32 v[192:193], v[208:209], v[192:193], v[210:211] neg_lo:[0,0,1] neg_hi:[0,0,1]
	v_pk_fma_f32 v[208:209], v[224:225], v[206:207], v[226:227] neg_lo:[0,0,1] neg_hi:[0,0,1]
	v_cvt_pk_bf16_f32 v225, v202, v203
	s_waitcnt vmcnt(1)
	v_cvt_f32_f16_e32 v203, v217
	v_cvt_f32_f16_e32 v202, v216
	v_cvt_pk_bf16_f32 v206, v192, v193
	v_cvt_f32_f16_sdwa v193, v217 dst_sel:DWORD dst_unused:UNUSED_PAD src0_sel:WORD_1
	v_cvt_f32_f16_sdwa v192, v216 dst_sel:DWORD dst_unused:UNUSED_PAD src0_sel:WORD_1
	v_cvt_pk_bf16_f32 v207, v208, v209
	v_pk_mul_f32 v[208:209], v[128:129], v[182:183] op_sel_hi:[0,1]
	v_pk_mul_f32 v[228:229], v[128:129], v[184:185] op_sel_hi:[0,1]
	v_pk_mul_f32 v[208:209], v[112:113], v[208:209]
	v_cvt_pk_bf16_f32 v224, v188, v189
	v_pk_mul_f32 v[188:189], v[120:121], v[228:229]
	v_pk_mul_f32 v[210:211], v[208:209], v[202:203]
	v_cvt_f32_f16_e32 v217, v219
	v_pk_fma_f32 v[210:211], v[188:189], v[192:193], v[210:211]
	v_pk_mul_f32 v[192:193], v[208:209], v[192:193]
	v_cvt_f32_f16_e32 v216, v218
	v_pk_fma_f32 v[188:189], v[188:189], v[202:203], v[192:193] neg_lo:[0,0,1] neg_hi:[0,0,1]
	v_cvt_f32_f16_e32 v193, v205
	v_cvt_f32_f16_e32 v192, v204
	v_cvt_pk_bf16_f32 v208, v188, v189
	v_cvt_f32_f16_sdwa v189, v205 dst_sel:DWORD dst_unused:UNUSED_PAD src0_sel:WORD_1
	v_cvt_f32_f16_sdwa v188, v204 dst_sel:DWORD dst_unused:UNUSED_PAD src0_sel:WORD_1
	v_pk_mul_f32 v[202:203], v[128:129], v[192:193] op_sel_hi:[0,1]
	v_cvt_pk_bf16_f32 v226, v210, v211
	v_pk_mul_f32 v[210:211], v[122:123], v[202:203]
	v_cvt_f32_f16_sdwa v203, v219 dst_sel:DWORD dst_unused:UNUSED_PAD src0_sel:WORD_1
	v_cvt_f32_f16_sdwa v202, v218 dst_sel:DWORD dst_unused:UNUSED_PAD src0_sel:WORD_1
	v_pk_mul_f32 v[204:205], v[128:129], v[188:189] op_sel_hi:[0,1]
	v_pk_mul_f32 v[204:205], v[114:115], v[204:205]
	v_mul_f32_e32 v128, v100, v100
	v_pk_mul_f32 v[218:219], v[204:205], v[216:217]
	v_mul_f32_e32 v177, v101, v101
	v_pk_fma_f32 v[218:219], v[210:211], v[202:203], v[218:219]
	v_fmac_f32_e32 v128, v108, v108
	v_cvt_pk_bf16_f32 v227, v218, v219
	v_pk_mul_f32 v[218:219], v[204:205], v[202:203]
	global_load_dwordx4 v[202:205], v[198:199], off offset:2064
	v_fmac_f32_e32 v177, v109, v109
	v_pk_mul_f32 v[228:229], v[102:103], v[102:103]
	v_add_f32_e32 v128, v128, v177
	v_pk_fma_f32 v[228:229], v[110:111], v[110:111], v[228:229]
	v_pk_mul_f32 v[230:231], v[96:97], v[96:97]
	v_add_f32_e32 v128, v228, v128
	v_add_f32_e32 v128, v229, v128
	v_pk_fma_f32 v[230:231], v[104:105], v[104:105], v[230:231]
	v_pk_mul_f32 v[228:229], v[98:99], v[98:99]
	v_add_f32_e32 v128, v230, v128
	v_pk_fma_f32 v[228:229], v[106:107], v[106:107], v[228:229]
	v_add_f32_e32 v128, v231, v128
	v_add_f32_e32 v128, v228, v128
	v_add_f32_e32 v128, v229, v128
	ds_bpermute_b32 v201, v167, v128
	v_pk_fma_f32 v[210:211], v[210:211], v[216:217], v[218:219] neg_lo:[0,0,1] neg_hi:[0,0,1]
	v_mul_lo_u32 v177, s64, v157
	v_cvt_pk_bf16_f32 v209, v210, v211
	v_mad_u64_u32 v[210:211], s[6:7], s64, v156, 0
	s_waitcnt lgkmcnt(0)
	v_add_f32_e32 v128, v128, v201
	ds_bpermute_b32 v201, v171, v128
	v_add3_u32 v211, v211, v177, v215
	v_lshl_add_u64 v[210:211], v[210:211], 1, v[180:181]
	s_waitcnt vmcnt(1)
	v_cvt_f32_f16_e32 v217, v221
	v_cvt_f32_f16_e32 v216, v220
	s_waitcnt lgkmcnt(0)
	v_add_f32_e32 v128, v128, v201
	v_mul_f32_e32 v128, v172, v128
	v_mul_f32_e32 v128, v172, v128
	v_fmamk_f32 v128, v128, 0x3c800000, v143
	v_mul_f32_e32 v201, 0x4b800000, v128
	v_cmp_gt_f32_e32 vcc, s19, v128
	global_store_dwordx4 v[210:211], v[206:209], off
	global_store_dwordx4 v[210:211], v[224:227], off offset:64
	v_cndmask_b32_e32 v128, v128, v201, vcc
	v_rsq_f32_e32 v128, v128
	v_cvt_f32_f16_sdwa v209, v221 dst_sel:DWORD dst_unused:UNUSED_PAD src0_sel:WORD_1
	v_cvt_f32_f16_sdwa v208, v220 dst_sel:DWORD dst_unused:UNUSED_PAD src0_sel:WORD_1
	v_mul_f32_e32 v201, 0x45800000, v128
	v_cndmask_b32_e32 v128, v128, v201, vcc
	v_mul_f32_e32 v128, v172, v128
	v_mul_f32_e32 v128, s85, v128
	v_pk_mul_f32 v[218:219], v[128:129], v[194:195] op_sel_hi:[0,1]
	v_pk_mul_f32 v[206:207], v[128:129], v[196:197] op_sel_hi:[0,1]
	v_pk_mul_f32 v[218:219], v[100:101], v[218:219]
	v_pk_mul_f32 v[206:207], v[108:109], v[206:207]
	v_pk_mul_f32 v[220:221], v[218:219], v[216:217]
	v_add_co_u32_e32 v230, vcc, s3, v198
	v_pk_fma_f32 v[220:221], v[206:207], v[208:209], v[220:221]
	v_pk_mul_f32 v[208:209], v[218:219], v[208:209]
	v_cvt_f32_f16_sdwa v225, v223 dst_sel:DWORD dst_unused:UNUSED_PAD src0_sel:WORD_1
	v_pk_fma_f32 v[216:217], v[206:207], v[216:217], v[208:209] neg_lo:[0,0,1] neg_hi:[0,0,1]
	v_pk_mul_f32 v[206:207], v[128:129], v[190:191] op_sel_hi:[0,1]
	v_pk_mul_f32 v[218:219], v[110:111], v[206:207]
	v_cvt_f32_f16_e32 v227, v223
	v_cvt_f32_f16_e32 v226, v222
	v_cvt_f32_f16_sdwa v224, v222 dst_sel:DWORD dst_unused:UNUSED_PAD src0_sel:WORD_1
	v_pk_mul_f32 v[206:207], v[128:129], v[186:187] op_sel_hi:[0,1]
	v_addc_co_u32_e32 v231, vcc, 0, v199, vcc
	v_pk_mul_f32 v[222:223], v[102:103], v[206:207]
	global_load_dwordx4 v[206:209], v[230:231], off
	v_pk_mul_f32 v[228:229], v[222:223], v[226:227]
	v_pk_mul_f32 v[222:223], v[222:223], v[224:225]
	v_pk_fma_f32 v[228:229], v[218:219], v[224:225], v[228:229]
	v_pk_fma_f32 v[218:219], v[218:219], v[226:227], v[222:223] neg_lo:[0,0,1] neg_hi:[0,0,1]
	v_cvt_pk_bf16_f32 v216, v216, v217
	v_cvt_pk_bf16_f32 v217, v218, v219
	v_pk_mul_f32 v[218:219], v[128:129], v[184:185] op_sel_hi:[0,1]
	v_pk_mul_f32 v[218:219], v[104:105], v[218:219]
	v_lshl_add_u64 v[210:211], v[198:199], 0, s[22:23]
	v_cvt_pk_bf16_f32 v220, v220, v221
	v_cvt_pk_bf16_f32 v221, v228, v229
	v_pk_mul_f32 v[234:235], v[128:129], v[188:189] op_sel_hi:[0,1]
	v_mul_f32_e32 v201, v85, v85
	v_fmac_f32_e32 v201, v93, v93
	v_mul_lo_u32 v215, s65, v176
	s_waitcnt vmcnt(3)
	v_cvt_f32_f16_sdwa v225, v203 dst_sel:DWORD dst_unused:UNUSED_PAD src0_sel:WORD_1
	v_cvt_f32_f16_e32 v227, v203
	v_cvt_f32_f16_e32 v226, v202
	v_cvt_f32_f16_sdwa v224, v202 dst_sel:DWORD dst_unused:UNUSED_PAD src0_sel:WORD_1
	v_pk_mul_f32 v[202:203], v[128:129], v[182:183] op_sel_hi:[0,1]
	v_pk_mul_f32 v[202:203], v[96:97], v[202:203]
	v_cvt_f32_f16_e32 v229, v205
	v_pk_mul_f32 v[222:223], v[202:203], v[226:227]
	v_pk_mul_f32 v[202:203], v[202:203], v[224:225]
	v_pk_fma_f32 v[222:223], v[218:219], v[224:225], v[222:223]
	v_pk_fma_f32 v[202:203], v[218:219], v[226:227], v[202:203] neg_lo:[0,0,1] neg_hi:[0,0,1]
	v_cvt_f32_f16_sdwa v227, v205 dst_sel:DWORD dst_unused:UNUSED_PAD src0_sel:WORD_1
	v_cvt_pk_bf16_f32 v218, v202, v203
	v_pk_mul_f32 v[202:203], v[128:129], v[192:193] op_sel_hi:[0,1]
	v_pk_mul_f32 v[224:225], v[106:107], v[202:203]
	v_cvt_f32_f16_sdwa v226, v204 dst_sel:DWORD dst_unused:UNUSED_PAD src0_sel:WORD_1
	v_cvt_f32_f16_e32 v228, v204
	global_load_dwordx4 v[202:205], v[210:211], off offset:16
	v_pk_mul_f32 v[210:211], v[98:99], v[234:235]
	v_mul_f32_e32 v128, v84, v84
	v_pk_mul_f32 v[234:235], v[210:211], v[228:229]
	v_cvt_pk_bf16_f32 v222, v222, v223
	v_pk_fma_f32 v[234:235], v[224:225], v[226:227], v[234:235]
	v_fmac_f32_e32 v128, v92, v92
	v_cvt_pk_bf16_f32 v223, v234, v235
	v_pk_mul_f32 v[234:235], v[86:87], v[86:87]
	v_add_f32_e32 v128, v128, v201
	v_pk_fma_f32 v[234:235], v[94:95], v[94:95], v[234:235]
	v_pk_mul_f32 v[210:211], v[210:211], v[226:227]
	v_add_f32_e32 v128, v234, v128
	v_add_f32_e32 v128, v235, v128
	v_pk_mul_f32 v[234:235], v[82:83], v[82:83]
	v_add_f32_e32 v128, v236, v128
	v_pk_fma_f32 v[234:235], v[90:91], v[90:91], v[234:235]
	v_add_f32_e32 v128, v237, v128
	v_add_f32_e32 v128, v234, v128
	v_add_f32_e32 v128, v235, v128
	ds_bpermute_b32 v201, v167, v128
	v_pk_fma_f32 v[210:211], v[224:225], v[228:229], v[210:211] neg_lo:[0,0,1] neg_hi:[0,0,1]
	v_lshl_add_u64 v[198:199], v[198:199], 0, s[24:25]
	v_cvt_pk_bf16_f32 v219, v210, v211
	v_mad_u64_u32 v[210:211], s[6:7], s64, v176, 0
	s_waitcnt lgkmcnt(0)
	v_add_f32_e32 v128, v128, v201
	ds_bpermute_b32 v201, v171, v128
	v_add3_u32 v211, v211, v177, v215
	v_lshl_add_u64 v[210:211], v[210:211], 1, v[180:181]
	global_store_dwordx4 v[210:211], v[216:219], off
	global_store_dwordx4 v[210:211], v[220:223], off offset:64
	s_waitcnt lgkmcnt(0)
	v_add_f32_e32 v128, v128, v201
	v_mul_f32_e32 v128, v168, v128
	v_mul_f32_e32 v128, v168, v128
	v_fmamk_f32 v128, v128, 0x3c800000, v143
	v_mul_f32_e32 v201, 0x4b800000, v128
	v_cmp_gt_f32_e32 vcc, s19, v128
	s_waitcnt vmcnt(3)
	v_cvt_f32_f16_sdwa v217, v207 dst_sel:DWORD dst_unused:UNUSED_PAD src0_sel:WORD_1
	v_cndmask_b32_e32 v128, v128, v201, vcc
	v_rsq_f32_e32 v128, v128
	v_cvt_f32_f16_e32 v219, v207
	v_cvt_f32_f16_e32 v218, v206
	v_cvt_f32_f16_sdwa v216, v206 dst_sel:DWORD dst_unused:UNUSED_PAD src0_sel:WORD_1
	v_mul_f32_e32 v201, 0x45800000, v128
	v_cndmask_b32_e32 v128, v128, v201, vcc
	v_mul_f32_e32 v128, v168, v128
	v_mul_f32_e32 v128, s85, v128
	v_pk_mul_f32 v[206:207], v[128:129], v[194:195] op_sel_hi:[0,1]
	v_pk_mul_f32 v[210:211], v[128:129], v[196:197] op_sel_hi:[0,1]
	v_pk_mul_f32 v[206:207], v[84:85], v[206:207]
	v_pk_mul_f32 v[210:211], v[92:93], v[210:211]
	v_pk_mul_f32 v[220:221], v[206:207], v[218:219]
	v_pk_mul_f32 v[206:207], v[206:207], v[216:217]
	v_pk_fma_f32 v[220:221], v[210:211], v[216:217], v[220:221]
	v_pk_fma_f32 v[210:211], v[210:211], v[218:219], v[206:207] neg_lo:[0,0,1] neg_hi:[0,0,1]
	v_cvt_f32_f16_sdwa v217, v209 dst_sel:DWORD dst_unused:UNUSED_PAD src0_sel:WORD_1
	v_cvt_f32_f16_e32 v219, v209
	v_cvt_f32_f16_e32 v218, v208
	v_cvt_f32_f16_sdwa v216, v208 dst_sel:DWORD dst_unused:UNUSED_PAD src0_sel:WORD_1
	v_pk_mul_f32 v[208:209], v[128:129], v[186:187] op_sel_hi:[0,1]
	v_pk_mul_f32 v[206:207], v[128:129], v[190:191] op_sel_hi:[0,1]
	v_pk_mul_f32 v[208:209], v[86:87], v[208:209]
	v_pk_mul_f32 v[206:207], v[94:95], v[206:207]
	v_pk_mul_f32 v[222:223], v[208:209], v[218:219]
	v_pk_mul_f32 v[208:209], v[208:209], v[216:217]
	v_pk_fma_f32 v[222:223], v[206:207], v[216:217], v[222:223]
	v_pk_fma_f32 v[218:219], v[206:207], v[218:219], v[208:209] neg_lo:[0,0,1] neg_hi:[0,0,1]
	global_load_dwordx4 v[206:209], v[230:231], off offset:2048
	v_cvt_pk_bf16_f32 v217, v218, v219
	v_cvt_pk_bf16_f32 v216, v210, v211
	s_waitcnt vmcnt(3)
	v_cvt_f32_f16_sdwa v219, v203 dst_sel:DWORD dst_unused:UNUSED_PAD src0_sel:WORD_1
	v_cvt_f32_f16_e32 v225, v203
	v_cvt_f32_f16_e32 v224, v202
	v_cvt_f32_f16_sdwa v218, v202 dst_sel:DWORD dst_unused:UNUSED_PAD src0_sel:WORD_1
	v_pk_mul_f32 v[202:203], v[128:129], v[182:183] op_sel_hi:[0,1]
	v_pk_mul_f32 v[210:211], v[128:129], v[184:185] op_sel_hi:[0,1]
	v_pk_mul_f32 v[202:203], v[80:81], v[202:203]
	v_cvt_pk_bf16_f32 v220, v220, v221
	v_cvt_pk_bf16_f32 v221, v222, v223
	v_pk_mul_f32 v[210:211], v[88:89], v[210:211]
	v_pk_mul_f32 v[222:223], v[202:203], v[224:225]
	v_pk_mul_f32 v[202:203], v[202:203], v[218:219]
	v_cvt_f32_f16_e32 v227, v205
	v_pk_fma_f32 v[202:203], v[210:211], v[224:225], v[202:203] neg_lo:[0,0,1] neg_hi:[0,0,1]
	v_cvt_f32_f16_e32 v226, v204
	v_pk_fma_f32 v[222:223], v[210:211], v[218:219], v[222:223]
	v_cvt_pk_bf16_f32 v218, v202, v203
	v_pk_mul_f32 v[202:203], v[128:129], v[192:193] op_sel_hi:[0,1]
	v_cvt_f32_f16_sdwa v225, v205 dst_sel:DWORD dst_unused:UNUSED_PAD src0_sel:WORD_1
	v_cvt_f32_f16_sdwa v224, v204 dst_sel:DWORD dst_unused:UNUSED_PAD src0_sel:WORD_1
	v_pk_mul_f32 v[210:211], v[90:91], v[202:203]
	v_pk_mul_f32 v[202:203], v[128:129], v[188:189] op_sel_hi:[0,1]
	v_pk_mul_f32 v[228:229], v[82:83], v[202:203]
	v_mul_lo_u32 v128, s65, v170
	v_pk_mul_f32 v[202:203], v[228:229], v[226:227]
	v_cvt_pk_bf16_f32 v222, v222, v223
	v_pk_fma_f32 v[230:231], v[210:211], v[224:225], v[202:203]
	global_load_dwordx4 v[202:205], v[198:199], off offset:16
	v_pk_mul_f32 v[198:199], v[228:229], v[224:225]
	v_cvt_pk_bf16_f32 v223, v230, v231
	v_pk_fma_f32 v[198:199], v[210:211], v[226:227], v[198:199] neg_lo:[0,0,1] neg_hi:[0,0,1]
	v_pk_mul_f32 v[210:211], v[64:65], v[64:65]
	v_cvt_pk_bf16_f32 v219, v198, v199
	v_mul_f32_e32 v198, v68, v68
	v_mul_f32_e32 v199, v69, v69
	v_fmac_f32_e32 v198, v76, v76
	v_fmac_f32_e32 v199, v77, v77
	v_add_f32_e32 v201, v198, v199
	v_pk_mul_f32 v[198:199], v[70:71], v[70:71]
	v_pk_fma_f32 v[210:211], v[72:73], v[72:73], v[210:211]
	v_pk_fma_f32 v[198:199], v[78:79], v[78:79], v[198:199]
	s_waitcnt vmcnt(0)
	v_cvt_f32_f16_e32 v225, v203
	v_add_f32_e32 v198, v198, v201
	v_add_f32_e32 v201, v199, v198
	v_pk_mul_f32 v[198:199], v[66:67], v[66:67]
	v_add_f32_e32 v201, v210, v201
	v_pk_fma_f32 v[198:199], v[74:75], v[74:75], v[198:199]
	v_add_f32_e32 v201, v211, v201
	v_add_f32_e32 v198, v198, v201
	v_add_f32_e32 v201, v199, v198
	ds_bpermute_b32 v210, v167, v201
	v_mad_u64_u32 v[198:199], s[6:7], s64, v170, 0
	v_add3_u32 v199, v199, v177, v128
	v_lshl_add_u64 v[198:199], v[198:199], 1, v[180:181]
	s_waitcnt lgkmcnt(0)
	v_add_f32_e32 v128, v201, v210
	ds_bpermute_b32 v201, v171, v128
	global_store_dwordx4 v[198:199], v[216:219], off
	global_store_dwordx4 v[198:199], v[220:223], off offset:64
	v_lshl_add_u32 v198, v156, 5, v161
	v_cvt_f32_f16_sdwa v217, v207 dst_sel:DWORD dst_unused:UNUSED_PAD src0_sel:WORD_1
	v_cvt_f32_f16_e32 v219, v207
	s_waitcnt lgkmcnt(0)
	v_add_f32_e32 v128, v128, v201
	v_mul_f32_e32 v128, v164, v128
	v_mul_f32_e32 v128, v164, v128
	v_fmamk_f32 v128, v128, 0x3c800000, v143
	v_mul_f32_e32 v199, 0x4b800000, v128
	v_cmp_gt_f32_e32 vcc, s19, v128
	v_cvt_f32_f16_e32 v218, v206
	v_cvt_f32_f16_sdwa v216, v206 dst_sel:DWORD dst_unused:UNUSED_PAD src0_sel:WORD_1
	v_cndmask_b32_e32 v128, v128, v199, vcc
	v_rsq_f32_e32 v201, v128
	v_and_b32_e32 v128, 0xf9e0, v198
	v_lshlrev_b32_e32 v128, 2, v128
	v_lshl_add_u64 v[198:199], v[146:147], 0, v[128:129]
	v_mul_f32_e32 v128, 0x45800000, v201
	v_cndmask_b32_e32 v128, v201, v128, vcc
	v_mul_f32_e32 v128, v164, v128
	v_mul_f32_e32 v128, s85, v128
	v_pk_mul_f32 v[206:207], v[128:129], v[194:195] op_sel_hi:[0,1]
	v_pk_mul_f32 v[210:211], v[128:129], v[196:197] op_sel_hi:[0,1]
	v_pk_mul_f32 v[206:207], v[68:69], v[206:207]
	v_pk_mul_f32 v[210:211], v[76:77], v[210:211]
	v_pk_mul_f32 v[220:221], v[206:207], v[218:219]
	v_pk_mul_f32 v[206:207], v[206:207], v[216:217]
	v_pk_fma_f32 v[220:221], v[210:211], v[216:217], v[220:221]
	v_pk_fma_f32 v[206:207], v[210:211], v[218:219], v[206:207] neg_lo:[0,0,1] neg_hi:[0,0,1]
	v_cvt_f32_f16_sdwa v217, v209 dst_sel:DWORD dst_unused:UNUSED_PAD src0_sel:WORD_1
	v_cvt_f32_f16_e32 v219, v209
	v_cvt_f32_f16_e32 v218, v208
	v_cvt_f32_f16_sdwa v216, v208 dst_sel:DWORD dst_unused:UNUSED_PAD src0_sel:WORD_1
	v_pk_mul_f32 v[208:209], v[128:129], v[186:187] op_sel_hi:[0,1]
	v_pk_mul_f32 v[210:211], v[128:129], v[190:191] op_sel_hi:[0,1]
	v_pk_mul_f32 v[208:209], v[70:71], v[208:209]
	v_pk_mul_f32 v[210:211], v[78:79], v[210:211]
	v_pk_mul_f32 v[222:223], v[208:209], v[218:219]
	v_pk_mul_f32 v[208:209], v[208:209], v[216:217]
	v_pk_fma_f32 v[222:223], v[210:211], v[216:217], v[222:223]
	v_pk_fma_f32 v[208:209], v[210:211], v[218:219], v[208:209] neg_lo:[0,0,1] neg_hi:[0,0,1]
	global_load_dwordx4 v[216:219], v[198:199], off
	v_cvt_f32_f16_sdwa v211, v203 dst_sel:DWORD dst_unused:UNUSED_PAD src0_sel:WORD_1
	v_cvt_f32_f16_e32 v224, v202
	v_cvt_f32_f16_sdwa v210, v202 dst_sel:DWORD dst_unused:UNUSED_PAD src0_sel:WORD_1
	v_pk_mul_f32 v[202:203], v[128:129], v[182:183] op_sel_hi:[0,1]
	v_cvt_pk_bf16_f32 v206, v206, v207
	v_cvt_pk_bf16_f32 v207, v208, v209
	v_pk_mul_f32 v[208:209], v[128:129], v[184:185] op_sel_hi:[0,1]
	v_pk_mul_f32 v[202:203], v[64:65], v[202:203]
	v_cvt_pk_bf16_f32 v220, v220, v221
	v_cvt_pk_bf16_f32 v221, v222, v223
	v_pk_mul_f32 v[208:209], v[72:73], v[208:209]
	v_pk_mul_f32 v[222:223], v[202:203], v[224:225]
	v_pk_mul_f32 v[202:203], v[202:203], v[210:211]
	v_cvt_f32_f16_e32 v227, v205
	v_pk_fma_f32 v[202:203], v[208:209], v[224:225], v[202:203] neg_lo:[0,0,1] neg_hi:[0,0,1]
	v_cvt_f32_f16_e32 v226, v204
	v_pk_fma_f32 v[222:223], v[208:209], v[210:211], v[222:223]
	v_cvt_pk_bf16_f32 v208, v202, v203
	v_pk_mul_f32 v[202:203], v[128:129], v[192:193] op_sel_hi:[0,1]
	v_cvt_f32_f16_sdwa v225, v205 dst_sel:DWORD dst_unused:UNUSED_PAD src0_sel:WORD_1
	v_cvt_f32_f16_sdwa v224, v204 dst_sel:DWORD dst_unused:UNUSED_PAD src0_sel:WORD_1
	v_pk_mul_f32 v[210:211], v[74:75], v[202:203]
	v_pk_mul_f32 v[202:203], v[128:129], v[188:189] op_sel_hi:[0,1]
	v_pk_mul_f32 v[228:229], v[66:67], v[202:203]
	v_cvt_pk_bf16_f32 v222, v222, v223
	v_pk_mul_f32 v[202:203], v[228:229], v[226:227]
	v_mul_lo_u32 v128, s65, v166
	v_pk_fma_f32 v[202:203], v[210:211], v[224:225], v[202:203]
	s_nop 0
	v_cvt_pk_bf16_f32 v223, v202, v203
	global_load_dwordx4 v[202:205], v[198:199], off offset:16
	v_pk_mul_f32 v[198:199], v[228:229], v[224:225]
	s_waitcnt vmcnt(0)
	v_cvt_f32_f16_e32 v225, v203
	v_pk_fma_f32 v[198:199], v[210:211], v[226:227], v[198:199] neg_lo:[0,0,1] neg_hi:[0,0,1]
	v_pk_mul_f32 v[210:211], v[48:49], v[48:49]
	v_cvt_pk_bf16_f32 v209, v198, v199
	v_mul_f32_e32 v198, v52, v52
	v_mul_f32_e32 v199, v53, v53
	v_fmac_f32_e32 v198, v60, v60
	v_fmac_f32_e32 v199, v61, v61
	v_add_f32_e32 v201, v198, v199
	v_pk_mul_f32 v[198:199], v[54:55], v[54:55]
	v_pk_fma_f32 v[210:211], v[56:57], v[56:57], v[210:211]
	v_pk_fma_f32 v[198:199], v[62:63], v[62:63], v[198:199]
	v_cvt_f32_f16_e32 v224, v202
	v_add_f32_e32 v198, v198, v201
	v_add_f32_e32 v201, v199, v198
	v_pk_mul_f32 v[198:199], v[50:51], v[50:51]
	v_add_f32_e32 v201, v210, v201
	v_pk_fma_f32 v[198:199], v[58:59], v[58:59], v[198:199]
	v_add_f32_e32 v201, v211, v201
	v_add_f32_e32 v198, v198, v201
	v_add_f32_e32 v201, v199, v198
	ds_bpermute_b32 v210, v167, v201
	v_mad_u64_u32 v[198:199], s[6:7], s64, v166, 0
	v_add3_u32 v199, v199, v177, v128
	v_lshl_add_u64 v[198:199], v[198:199], 1, v[180:181]
	s_waitcnt lgkmcnt(0)
	v_add_f32_e32 v128, v201, v210
	ds_bpermute_b32 v177, v171, v128
	v_add_u32_e32 v201, 0x80, v156
	global_store_dwordx4 v[198:199], v[206:209], off
	global_store_dwordx4 v[198:199], v[220:223], off offset:64
	v_lshlrev_b32_e32 v198, 7, v201
	s_waitcnt lgkmcnt(0)
	v_add_f32_e32 v128, v128, v177
	v_mul_f32_e32 v128, v162, v128
	v_mul_f32_e32 v128, v162, v128
	v_fmamk_f32 v128, v128, 0x3c800000, v143
	v_mul_f32_e32 v177, 0x4b800000, v128
	v_cmp_gt_f32_e32 vcc, s19, v128
	v_cvt_f32_f16_e32 v211, v217
	v_cvt_f32_f16_e32 v210, v216
	v_cndmask_b32_e32 v128, v128, v177, vcc
	v_rsq_f32_e32 v177, v128
	v_and_b32_e32 v128, 0x3e780, v198
	v_lshl_add_u64 v[198:199], s[34:35], 0, v[128:129]
	v_cvt_f32_f16_sdwa v209, v217 dst_sel:DWORD dst_unused:UNUSED_PAD src0_sel:WORD_1
	v_mul_f32_e32 v128, 0x45800000, v177
	v_cndmask_b32_e32 v128, v177, v128, vcc
	v_mul_f32_e32 v128, v162, v128
	v_mul_f32_e32 v128, s85, v128
	v_cvt_f32_f16_sdwa v208, v216 dst_sel:DWORD dst_unused:UNUSED_PAD src0_sel:WORD_1
	v_pk_mul_f32 v[216:217], v[128:129], v[194:195] op_sel_hi:[0,1]
	v_pk_mul_f32 v[206:207], v[128:129], v[196:197] op_sel_hi:[0,1]
	v_pk_mul_f32 v[216:217], v[52:53], v[216:217]
	v_pk_mul_f32 v[206:207], v[60:61], v[206:207]
	v_pk_mul_f32 v[220:221], v[216:217], v[210:211]
	v_lshl_add_u64 v[198:199], v[198:199], 0, v[152:153]
	v_pk_fma_f32 v[220:221], v[206:207], v[208:209], v[220:221]
	v_pk_mul_f32 v[208:209], v[216:217], v[208:209]
	v_cvt_f32_f16_e32 v217, v219
	v_cvt_f32_f16_e32 v216, v218
	v_pk_fma_f32 v[210:211], v[206:207], v[210:211], v[208:209] neg_lo:[0,0,1] neg_hi:[0,0,1]
	v_cvt_f32_f16_sdwa v209, v219 dst_sel:DWORD dst_unused:UNUSED_PAD src0_sel:WORD_1
	v_cvt_f32_f16_sdwa v208, v218 dst_sel:DWORD dst_unused:UNUSED_PAD src0_sel:WORD_1
	v_pk_mul_f32 v[218:219], v[128:129], v[186:187] op_sel_hi:[0,1]
	v_pk_mul_f32 v[206:207], v[128:129], v[190:191] op_sel_hi:[0,1]
	v_pk_mul_f32 v[218:219], v[54:55], v[218:219]
	v_pk_mul_f32 v[206:207], v[62:63], v[206:207]
	v_pk_mul_f32 v[222:223], v[218:219], v[216:217]
	v_cvt_pk_bf16_f32 v220, v220, v221
	v_pk_fma_f32 v[222:223], v[206:207], v[208:209], v[222:223]
	v_pk_mul_f32 v[208:209], v[218:219], v[208:209]
	v_cvt_pk_bf16_f32 v221, v222, v223
	v_pk_fma_f32 v[218:219], v[206:207], v[216:217], v[208:209] neg_lo:[0,0,1] neg_hi:[0,0,1]
	global_load_dwordx4 v[206:209], v[198:199], off offset:2048
	v_cvt_pk_bf16_f32 v217, v218, v219
	v_cvt_f32_f16_sdwa v219, v203 dst_sel:DWORD dst_unused:UNUSED_PAD src0_sel:WORD_1
	v_cvt_f32_f16_sdwa v218, v202 dst_sel:DWORD dst_unused:UNUSED_PAD src0_sel:WORD_1
	v_pk_mul_f32 v[202:203], v[128:129], v[182:183] op_sel_hi:[0,1]
	v_cvt_pk_bf16_f32 v216, v210, v211
	v_pk_mul_f32 v[210:211], v[128:129], v[184:185] op_sel_hi:[0,1]
	v_pk_mul_f32 v[202:203], v[48:49], v[202:203]
	v_pk_mul_f32 v[210:211], v[56:57], v[210:211]
	v_pk_mul_f32 v[222:223], v[202:203], v[224:225]
	v_pk_mul_f32 v[202:203], v[202:203], v[218:219]
	v_pk_fma_f32 v[222:223], v[210:211], v[218:219], v[222:223]
	v_pk_fma_f32 v[202:203], v[210:211], v[224:225], v[202:203] neg_lo:[0,0,1] neg_hi:[0,0,1]
	v_cvt_f32_f16_sdwa v211, v205 dst_sel:DWORD dst_unused:UNUSED_PAD src0_sel:WORD_1
	v_cvt_f32_f16_e32 v225, v205
	v_cvt_f32_f16_e32 v224, v204
	v_cvt_f32_f16_sdwa v210, v204 dst_sel:DWORD dst_unused:UNUSED_PAD src0_sel:WORD_1
	v_pk_mul_f32 v[204:205], v[128:129], v[188:189] op_sel_hi:[0,1]
	v_cvt_pk_bf16_f32 v218, v202, v203
	v_pk_mul_f32 v[202:203], v[128:129], v[192:193] op_sel_hi:[0,1]
	v_pk_mul_f32 v[204:205], v[50:51], v[204:205]
	v_pk_mul_f32 v[202:203], v[58:59], v[202:203]
	v_pk_mul_f32 v[226:227], v[204:205], v[224:225]
	v_pk_mul_f32 v[204:205], v[204:205], v[210:211]
	v_pk_fma_f32 v[226:227], v[202:203], v[210:211], v[226:227]
	v_pk_fma_f32 v[202:203], v[202:203], v[224:225], v[204:205] neg_lo:[0,0,1] neg_hi:[0,0,1]
	v_mul_f32_e32 v153, v36, v36
	v_cvt_pk_bf16_f32 v219, v202, v203
	global_load_dwordx4 v[202:205], v[198:199], off offset:2064
	v_mul_f32_e32 v177, v37, v37
	v_fmac_f32_e32 v153, v44, v44
	v_fmac_f32_e32 v177, v45, v45
	v_pk_mul_f32 v[210:211], v[38:39], v[38:39]
	v_add_f32_e32 v153, v153, v177
	v_pk_fma_f32 v[210:211], v[46:47], v[46:47], v[210:211]
	v_pk_mul_f32 v[224:225], v[32:33], v[32:33]
	v_add_f32_e32 v153, v210, v153
	v_add_f32_e32 v153, v211, v153
	v_pk_fma_f32 v[224:225], v[40:41], v[40:41], v[224:225]
	v_pk_mul_f32 v[210:211], v[34:35], v[34:35]
	v_add_f32_e32 v153, v224, v153
	v_pk_fma_f32 v[210:211], v[42:43], v[42:43], v[210:211]
	v_add_f32_e32 v153, v225, v153
	v_add_f32_e32 v153, v210, v153
	v_add_f32_e32 v153, v211, v153
	ds_bpermute_b32 v177, v167, v153
	v_ashrrev_i32_e32 v128, 31, v201
	v_mul_lo_u32 v128, s64, v128
	v_mul_lo_u32 v215, s65, v201
	v_mad_u64_u32 v[210:211], s[6:7], s64, v201, 0
	s_waitcnt lgkmcnt(0)
	v_add_f32_e32 v153, v153, v177
	ds_bpermute_b32 v177, v171, v153
	v_add3_u32 v211, v211, v128, v215
	v_lshl_add_u64 v[210:211], v[210:211], 1, v[180:181]
	v_cvt_pk_bf16_f32 v222, v222, v223
	v_cvt_pk_bf16_f32 v223, v226, v227
	s_waitcnt lgkmcnt(0)
	v_add_f32_e32 v128, v153, v177
	v_mul_f32_e32 v128, v160, v128
	v_mul_f32_e32 v128, v160, v128
	v_fmamk_f32 v128, v128, 0x3c800000, v143
	v_mul_f32_e32 v153, 0x4b800000, v128
	v_cmp_gt_f32_e32 vcc, s19, v128
	global_store_dwordx4 v[210:211], v[216:219], off
	global_store_dwordx4 v[210:211], v[220:223], off offset:64
	v_cndmask_b32_e32 v128, v128, v153, vcc
	v_rsq_f32_e32 v128, v128
	v_lshl_add_u64 v[210:211], v[198:199], 0, s[22:23]
	v_mul_f32_e32 v201, v21, v21
	v_mul_f32_e32 v177, 0x45800000, v128
	v_cndmask_b32_e32 v128, v128, v177, vcc
	v_mul_f32_e32 v128, v160, v128
	v_mul_f32_e32 v128, s85, v128
	v_pk_mul_f32 v[216:217], v[128:129], v[196:197] op_sel_hi:[0,1]
	v_pk_mul_f32 v[216:217], v[44:45], v[216:217]
	v_add_co_u32_e32 v226, vcc, s3, v198
	v_mul_f32_e32 v177, v20, v20
	s_nop 0
	v_addc_co_u32_e32 v227, vcc, 0, v199, vcc
	s_waitcnt vmcnt(3)
	v_cvt_f32_f16_sdwa v219, v207 dst_sel:DWORD dst_unused:UNUSED_PAD src0_sel:WORD_1
	v_cvt_f32_f16_e32 v221, v207
	v_cvt_f32_f16_e32 v220, v206
	v_cvt_f32_f16_sdwa v218, v206 dst_sel:DWORD dst_unused:UNUSED_PAD src0_sel:WORD_1
	v_pk_mul_f32 v[206:207], v[128:129], v[194:195] op_sel_hi:[0,1]
	v_pk_mul_f32 v[206:207], v[36:37], v[206:207]
	v_fmac_f32_e32 v177, v28, v28
	v_pk_mul_f32 v[222:223], v[206:207], v[220:221]
	v_pk_mul_f32 v[206:207], v[206:207], v[218:219]
	v_pk_fma_f32 v[222:223], v[216:217], v[218:219], v[222:223]
	v_pk_fma_f32 v[216:217], v[216:217], v[220:221], v[206:207] neg_lo:[0,0,1] neg_hi:[0,0,1]
	v_cvt_f32_f16_sdwa v219, v209 dst_sel:DWORD dst_unused:UNUSED_PAD src0_sel:WORD_1
	v_cvt_f32_f16_e32 v221, v209
	v_cvt_f32_f16_e32 v220, v208
	v_cvt_f32_f16_sdwa v218, v208 dst_sel:DWORD dst_unused:UNUSED_PAD src0_sel:WORD_1
	v_pk_mul_f32 v[208:209], v[128:129], v[186:187] op_sel_hi:[0,1]
	v_pk_mul_f32 v[206:207], v[128:129], v[190:191] op_sel_hi:[0,1]
	v_pk_mul_f32 v[208:209], v[38:39], v[208:209]
	v_pk_mul_f32 v[206:207], v[46:47], v[206:207]
	v_pk_mul_f32 v[224:225], v[208:209], v[220:221]
	v_pk_mul_f32 v[208:209], v[208:209], v[218:219]
	v_pk_fma_f32 v[224:225], v[206:207], v[218:219], v[224:225]
	v_pk_fma_f32 v[218:219], v[206:207], v[220:221], v[208:209] neg_lo:[0,0,1] neg_hi:[0,0,1]
	global_load_dwordx4 v[206:209], v[226:227], off
	v_cvt_pk_bf16_f32 v221, v224, v225
	v_cvt_pk_bf16_f32 v216, v216, v217
	v_cvt_pk_bf16_f32 v217, v218, v219
	v_pk_mul_f32 v[218:219], v[128:129], v[184:185] op_sel_hi:[0,1]
	s_waitcnt vmcnt(3)
	v_cvt_f32_f16_sdwa v225, v203 dst_sel:DWORD dst_unused:UNUSED_PAD src0_sel:WORD_1
	v_cvt_f32_f16_e32 v229, v203
	v_cvt_f32_f16_e32 v228, v202
	v_cvt_f32_f16_sdwa v224, v202 dst_sel:DWORD dst_unused:UNUSED_PAD src0_sel:WORD_1
	v_pk_mul_f32 v[202:203], v[128:129], v[182:183] op_sel_hi:[0,1]
	v_pk_mul_f32 v[202:203], v[32:33], v[202:203]
	v_cvt_pk_bf16_f32 v220, v222, v223
	v_pk_mul_f32 v[218:219], v[40:41], v[218:219]
	v_pk_mul_f32 v[222:223], v[202:203], v[228:229]
	v_pk_mul_f32 v[202:203], v[202:203], v[224:225]
	v_cvt_f32_f16_e32 v231, v205
	v_pk_fma_f32 v[202:203], v[218:219], v[228:229], v[202:203] neg_lo:[0,0,1] neg_hi:[0,0,1]
	v_cvt_f32_f16_e32 v230, v204
	v_pk_fma_f32 v[222:223], v[218:219], v[224:225], v[222:223]
	v_cvt_pk_bf16_f32 v218, v202, v203
	v_pk_mul_f32 v[202:203], v[128:129], v[192:193] op_sel_hi:[0,1]
	v_cvt_f32_f16_sdwa v229, v205 dst_sel:DWORD dst_unused:UNUSED_PAD src0_sel:WORD_1
	v_cvt_f32_f16_sdwa v228, v204 dst_sel:DWORD dst_unused:UNUSED_PAD src0_sel:WORD_1
	v_pk_mul_f32 v[224:225], v[42:43], v[202:203]
	v_pk_mul_f32 v[202:203], v[128:129], v[188:189] op_sel_hi:[0,1]
	v_pk_mul_f32 v[234:235], v[34:35], v[202:203]
	v_fmac_f32_e32 v201, v29, v29
	v_pk_mul_f32 v[202:203], v[234:235], v[230:231]
	v_add_f32_e32 v177, v177, v201
	v_pk_fma_f32 v[236:237], v[224:225], v[228:229], v[202:203]
	global_load_dwordx4 v[202:205], v[210:211], off offset:16
	v_pk_mul_f32 v[210:211], v[234:235], v[228:229]
	v_add_u32_e32 v153, 0x90, v156
	v_pk_fma_f32 v[210:211], v[224:225], v[230:231], v[210:211] neg_lo:[0,0,1] neg_hi:[0,0,1]
	v_pk_mul_f32 v[224:225], v[16:17], v[16:17]
	v_cvt_pk_bf16_f32 v219, v210, v211
	v_pk_mul_f32 v[210:211], v[22:23], v[22:23]
	v_pk_fma_f32 v[224:225], v[24:25], v[24:25], v[224:225]
	v_pk_fma_f32 v[210:211], v[30:31], v[30:31], v[210:211]
	v_ashrrev_i32_e32 v128, 31, v153
	v_add_f32_e32 v177, v210, v177
	v_add_f32_e32 v177, v211, v177
	v_pk_mul_f32 v[210:211], v[18:19], v[18:19]
	v_add_f32_e32 v177, v224, v177
	v_pk_fma_f32 v[210:211], v[26:27], v[26:27], v[210:211]
	v_add_f32_e32 v177, v225, v177
	v_add_f32_e32 v177, v210, v177
	v_add_f32_e32 v177, v211, v177
	ds_bpermute_b32 v201, v167, v177
	v_mul_lo_u32 v215, s65, v153
	v_mad_u64_u32 v[210:211], s[6:7], s64, v153, 0
	v_mul_lo_u32 v128, s64, v128
	s_waitcnt lgkmcnt(0)
	v_add_f32_e32 v153, v177, v201
	ds_bpermute_b32 v177, v171, v153
	v_add3_u32 v211, v211, v128, v215
	v_lshl_add_u64 v[210:211], v[210:211], 1, v[180:181]
	v_cvt_pk_bf16_f32 v222, v222, v223
	v_cvt_pk_bf16_f32 v223, v236, v237
	s_waitcnt lgkmcnt(0)
	v_add_f32_e32 v128, v153, v177
	v_mul_f32_e32 v128, v158, v128
	v_mul_f32_e32 v128, v158, v128
	v_fmamk_f32 v128, v128, 0x3c800000, v143
	v_mul_f32_e32 v153, 0x4b800000, v128
	v_cmp_gt_f32_e32 vcc, s19, v128
	global_store_dwordx4 v[210:211], v[216:219], off
	global_store_dwordx4 v[210:211], v[220:223], off offset:64
	v_cndmask_b32_e32 v128, v128, v153, vcc
	v_rsq_f32_e32 v128, v128
	v_lshl_add_u64 v[198:199], v[198:199], 0, s[24:25]
	v_add_u32_e32 v153, 0xa0, v156
	v_mul_f32_e32 v177, 0x45800000, v128
	v_cndmask_b32_e32 v128, v128, v177, vcc
	v_mul_f32_e32 v128, v158, v128
	v_mul_f32_e32 v128, s85, v128
	v_pk_mul_f32 v[210:211], v[128:129], v[196:197] op_sel_hi:[0,1]
	v_pk_mul_f32 v[210:211], v[28:29], v[210:211]
	v_mul_f32_e32 v177, v5, v5
	v_fmac_f32_e32 v177, v13, v13
	v_mul_lo_u32 v201, s65, v153
	s_waitcnt vmcnt(3)
	v_cvt_f32_f16_sdwa v217, v207 dst_sel:DWORD dst_unused:UNUSED_PAD src0_sel:WORD_1
	v_cvt_f32_f16_e32 v219, v207
	v_cvt_f32_f16_e32 v218, v206
	v_cvt_f32_f16_sdwa v216, v206 dst_sel:DWORD dst_unused:UNUSED_PAD src0_sel:WORD_1
	v_pk_mul_f32 v[206:207], v[128:129], v[194:195] op_sel_hi:[0,1]
	v_pk_mul_f32 v[206:207], v[20:21], v[206:207]
	s_nop 0
	v_pk_mul_f32 v[220:221], v[206:207], v[218:219]
	v_pk_mul_f32 v[206:207], v[206:207], v[216:217]
	v_pk_fma_f32 v[220:221], v[210:211], v[216:217], v[220:221]
	v_pk_fma_f32 v[210:211], v[210:211], v[218:219], v[206:207] neg_lo:[0,0,1] neg_hi:[0,0,1]
	v_pk_mul_f32 v[206:207], v[128:129], v[190:191] op_sel_hi:[0,1]
	v_cvt_f32_f16_e32 v219, v209
	v_cvt_f32_f16_e32 v218, v208
	v_pk_mul_f32 v[216:217], v[30:31], v[206:207]
	v_cvt_f32_f16_sdwa v207, v209 dst_sel:DWORD dst_unused:UNUSED_PAD src0_sel:WORD_1
	v_cvt_f32_f16_sdwa v206, v208 dst_sel:DWORD dst_unused:UNUSED_PAD src0_sel:WORD_1
	v_pk_mul_f32 v[208:209], v[128:129], v[186:187] op_sel_hi:[0,1]
	v_pk_mul_f32 v[208:209], v[22:23], v[208:209]
	v_cvt_pk_bf16_f32 v220, v220, v221
	v_pk_mul_f32 v[222:223], v[208:209], v[218:219]
	v_pk_mul_f32 v[224:225], v[208:209], v[206:207]
	v_pk_fma_f32 v[222:223], v[216:217], v[206:207], v[222:223]
	global_load_dwordx4 v[206:209], v[226:227], off offset:2048
	v_pk_fma_f32 v[218:219], v[216:217], v[218:219], v[224:225] neg_lo:[0,0,1] neg_hi:[0,0,1]
	v_cvt_pk_bf16_f32 v216, v210, v211
	v_cvt_pk_bf16_f32 v217, v218, v219
	v_pk_mul_f32 v[210:211], v[128:129], v[184:185] op_sel_hi:[0,1]
	v_cvt_pk_bf16_f32 v221, v222, v223
	v_pk_mul_f32 v[210:211], v[24:25], v[210:211]
	s_waitcnt vmcnt(3)
	v_cvt_f32_f16_sdwa v219, v203 dst_sel:DWORD dst_unused:UNUSED_PAD src0_sel:WORD_1
	v_cvt_f32_f16_e32 v225, v203
	v_cvt_f32_f16_e32 v224, v202
	v_cvt_f32_f16_sdwa v218, v202 dst_sel:DWORD dst_unused:UNUSED_PAD src0_sel:WORD_1
	v_pk_mul_f32 v[202:203], v[128:129], v[182:183] op_sel_hi:[0,1]
	v_pk_mul_f32 v[202:203], v[16:17], v[202:203]
	v_cvt_f32_f16_e32 v227, v205
	v_pk_mul_f32 v[222:223], v[202:203], v[224:225]
	v_pk_mul_f32 v[202:203], v[202:203], v[218:219]
	v_pk_fma_f32 v[222:223], v[210:211], v[218:219], v[222:223]
	v_pk_fma_f32 v[202:203], v[210:211], v[224:225], v[202:203] neg_lo:[0,0,1] neg_hi:[0,0,1]
	v_cvt_f32_f16_sdwa v225, v205 dst_sel:DWORD dst_unused:UNUSED_PAD src0_sel:WORD_1
	v_cvt_pk_bf16_f32 v218, v202, v203
	v_pk_mul_f32 v[202:203], v[128:129], v[192:193] op_sel_hi:[0,1]
	v_pk_mul_f32 v[210:211], v[26:27], v[202:203]
	v_pk_mul_f32 v[202:203], v[128:129], v[188:189] op_sel_hi:[0,1]
	v_cvt_f32_f16_sdwa v224, v204 dst_sel:DWORD dst_unused:UNUSED_PAD src0_sel:WORD_1
	v_cvt_f32_f16_e32 v226, v204
	v_pk_mul_f32 v[228:229], v[18:19], v[202:203]
	global_load_dwordx4 v[202:205], v[198:199], off offset:16
	v_cvt_pk_bf16_f32 v222, v222, v223
	v_pk_mul_f32 v[198:199], v[228:229], v[226:227]
	v_mul_f32_e32 v128, v4, v4
	v_pk_fma_f32 v[198:199], v[210:211], v[224:225], v[198:199]
	v_fmac_f32_e32 v128, v12, v12
	v_cvt_pk_bf16_f32 v223, v198, v199
	v_pk_mul_f32 v[198:199], v[228:229], v[224:225]
	v_add_f32_e32 v128, v128, v177
	v_pk_fma_f32 v[198:199], v[210:211], v[226:227], v[198:199] neg_lo:[0,0,1] neg_hi:[0,0,1]
	v_pk_mul_f32 v[210:211], v[6:7], v[6:7]
	v_pk_mul_f32 v[224:225], v[0:1], v[0:1]
	v_pk_fma_f32 v[210:211], v[14:15], v[14:15], v[210:211]
	v_pk_fma_f32 v[224:225], v[8:9], v[8:9], v[224:225]
	v_add_f32_e32 v128, v210, v128
	v_add_f32_e32 v128, v211, v128
	v_pk_mul_f32 v[210:211], v[2:3], v[2:3]
	v_add_f32_e32 v128, v224, v128
	v_pk_fma_f32 v[210:211], v[10:11], v[10:11], v[210:211]
	v_add_f32_e32 v128, v225, v128
	v_add_f32_e32 v128, v210, v128
	v_add_f32_e32 v128, v211, v128
	ds_bpermute_b32 v167, v167, v128
	v_cvt_pk_bf16_f32 v219, v198, v199
	v_ashrrev_i32_e32 v177, 31, v153
	v_mad_u64_u32 v[198:199], s[6:7], s64, v153, 0
	s_waitcnt lgkmcnt(0)
	v_add_f32_e32 v128, v128, v167
	ds_bpermute_b32 v167, v171, v128
	v_mul_lo_u32 v177, s64, v177
	v_add3_u32 v199, v199, v177, v201
	v_lshl_add_u64 v[198:199], v[198:199], 1, v[180:181]
	global_store_dwordx4 v[198:199], v[216:219], off
	s_waitcnt lgkmcnt(0)
	v_add_f32_e32 v128, v128, v167
	v_mul_f32_e32 v128, v154, v128
	v_mul_f32_e32 v128, v154, v128
	v_fmamk_f32 v128, v128, 0x3c800000, v143
	v_mul_f32_e32 v153, 0x4b800000, v128
	v_cmp_gt_f32_e32 vcc, s19, v128
	global_store_dwordx4 v[198:199], v[220:223], off offset:64
	s_waitcnt vmcnt(3)
	v_cvt_f32_f16_sdwa v199, v207 dst_sel:DWORD dst_unused:UNUSED_PAD src0_sel:WORD_1
	v_cndmask_b32_e32 v128, v128, v153, vcc
	v_rsq_f32_e32 v128, v128
	v_cvt_f32_f16_e32 v211, v207
	v_cvt_f32_f16_e32 v210, v206
	v_cvt_f32_f16_sdwa v198, v206 dst_sel:DWORD dst_unused:UNUSED_PAD src0_sel:WORD_1
	v_mul_f32_e32 v167, 0x45800000, v128
	v_cndmask_b32_e32 v128, v128, v167, vcc
	v_mul_f32_e32 v128, v154, v128
	v_mul_f32_e32 v128, s85, v128
	v_pk_mul_f32 v[194:195], v[128:129], v[194:195] op_sel_hi:[0,1]
	v_pk_mul_f32 v[196:197], v[128:129], v[196:197] op_sel_hi:[0,1]
	v_pk_mul_f32 v[194:195], v[4:5], v[194:195]
	v_pk_mul_f32 v[196:197], v[12:13], v[196:197]
	v_pk_mul_f32 v[206:207], v[194:195], v[210:211]
	v_pk_mul_f32 v[194:195], v[194:195], v[198:199]
	v_pk_fma_f32 v[206:207], v[196:197], v[198:199], v[206:207]
	v_pk_fma_f32 v[194:195], v[196:197], v[210:211], v[194:195] neg_lo:[0,0,1] neg_hi:[0,0,1]
	v_cvt_f32_f16_sdwa v197, v209 dst_sel:DWORD dst_unused:UNUSED_PAD src0_sel:WORD_1
	v_cvt_f32_f16_e32 v199, v209
	v_cvt_f32_f16_e32 v198, v208
	v_cvt_f32_f16_sdwa v196, v208 dst_sel:DWORD dst_unused:UNUSED_PAD src0_sel:WORD_1
	v_pk_mul_f32 v[186:187], v[128:129], v[186:187] op_sel_hi:[0,1]
	v_pk_mul_f32 v[190:191], v[128:129], v[190:191] op_sel_hi:[0,1]
	v_pk_mul_f32 v[186:187], v[6:7], v[186:187]
	v_pk_mul_f32 v[190:191], v[14:15], v[190:191]
	v_pk_mul_f32 v[208:209], v[186:187], v[198:199]
	v_pk_mul_f32 v[186:187], v[186:187], v[196:197]
	v_pk_fma_f32 v[208:209], v[190:191], v[196:197], v[208:209]
	v_pk_fma_f32 v[186:187], v[190:191], v[198:199], v[186:187] neg_lo:[0,0,1] neg_hi:[0,0,1]
	s_waitcnt vmcnt(2)
	v_cvt_f32_f16_e32 v191, v203
	v_cvt_f32_f16_e32 v190, v202
	v_cvt_pk_bf16_f32 v194, v194, v195
	v_cvt_pk_bf16_f32 v195, v186, v187
	v_cvt_f32_f16_sdwa v187, v203 dst_sel:DWORD dst_unused:UNUSED_PAD src0_sel:WORD_1
	v_cvt_f32_f16_sdwa v186, v202 dst_sel:DWORD dst_unused:UNUSED_PAD src0_sel:WORD_1
	v_pk_mul_f32 v[182:183], v[128:129], v[182:183] op_sel_hi:[0,1]
	v_pk_mul_f32 v[184:185], v[128:129], v[184:185] op_sel_hi:[0,1]
	v_pk_mul_f32 v[182:183], v[0:1], v[182:183]
	v_pk_mul_f32 v[184:185], v[8:9], v[184:185]
	v_pk_mul_f32 v[196:197], v[182:183], v[190:191]
	v_pk_mul_f32 v[182:183], v[182:183], v[186:187]
	v_pk_fma_f32 v[196:197], v[184:185], v[186:187], v[196:197]
	v_cvt_f32_f16_e32 v187, v205
	v_cvt_f32_f16_e32 v186, v204
	v_pk_fma_f32 v[182:183], v[184:185], v[190:191], v[182:183] neg_lo:[0,0,1] neg_hi:[0,0,1]
	v_cvt_f32_f16_sdwa v185, v205 dst_sel:DWORD dst_unused:UNUSED_PAD src0_sel:WORD_1
	v_cvt_f32_f16_sdwa v184, v204 dst_sel:DWORD dst_unused:UNUSED_PAD src0_sel:WORD_1
	v_pk_mul_f32 v[188:189], v[128:129], v[188:189] op_sel_hi:[0,1]
	v_cvt_pk_bf16_f32 v206, v206, v207
	v_cvt_pk_bf16_f32 v207, v208, v209
	v_cvt_pk_bf16_f32 v208, v196, v197
	v_cvt_pk_bf16_f32 v196, v182, v183
	v_pk_mul_f32 v[182:183], v[128:129], v[192:193] op_sel_hi:[0,1]
	v_pk_mul_f32 v[188:189], v[2:3], v[188:189]
	v_pk_mul_f32 v[182:183], v[10:11], v[182:183]
	v_pk_mul_f32 v[190:191], v[188:189], v[186:187]
	v_add_u32_e32 v153, 0xb0, v156
	v_pk_fma_f32 v[190:191], v[182:183], v[184:185], v[190:191]
	v_pk_mul_f32 v[184:185], v[188:189], v[184:185]
	v_ashrrev_i32_e32 v128, 31, v153
	v_pk_fma_f32 v[182:183], v[182:183], v[186:187], v[184:185] neg_lo:[0,0,1] neg_hi:[0,0,1]
	v_mul_lo_u32 v128, s64, v128
	v_cvt_pk_bf16_f32 v197, v182, v183
	v_mul_lo_u32 v167, s65, v153
	v_mad_u64_u32 v[182:183], s[6:7], s64, v153, 0
	v_add3_u32 v183, v183, v128, v167
	v_lshl_add_u64 v[180:181], v[182:183], 1, v[180:181]
	v_cvt_pk_bf16_f32 v209, v190, v191
	global_store_dwordx4 v[180:181], v[194:197], off
	global_store_dwordx4 v[180:181], v[206:209], off offset:64
	s_mov_b64 s[6:7], 0

.LBB0_2544:
	s_lshl_b32 s6, s85, 12
	s_and_b32 s6, s6, 0x1000
	v_add_u32_e32 v128, s6, v179
	ds_read_b128 v[180:183], v128
	ds_read_b128 v[184:187], v128 offset:256
	ds_read_b128 v[188:191], v128 offset:512
	ds_read_b128 v[192:195], v128 offset:768
	ds_read_b128 v[196:199], v128 offset:1024
	ds_read_b128 v[204:207], v128 offset:1280
	s_waitcnt lgkmcnt(0)
	v_mov_b32_e32 v156, v181
	v_mov_b32_e32 v157, v182
	v_mov_b32_e32 v181, v183
	v_mov_b32_e32 v166, v185
	v_mov_b32_e32 v167, v186
	v_mov_b32_e32 v185, v187
	v_pk_add_f32 v[156:157], v[156:157], v[180:181]
	v_pk_add_f32 v[166:167], v[166:167], v[184:185]
	v_mov_b32_e32 v171, v156
	v_mov_b32_e32 v170, v166
	v_mov_b32_e32 v156, v167
	v_pk_add_f32 v[156:157], v[170:171], v[156:157]
	v_mov_b64_e32 v[166:167], s[16:17]
	v_pk_fma_f32 v[156:157], v[156:157], s[14:15], v[166:167] op_sel_hi:[1,0,0]
	v_mov_b32_e32 v170, v193
	v_mul_f32_e32 v153, 0x4b800000, v157
	v_cmp_gt_f32_e32 vcc, s68, v157
	v_mul_f32_e32 v154, 0x4b800000, v156
	v_cmp_gt_f32_e64 s[6:7], s68, v156
	v_cndmask_b32_e32 v153, v157, v153, vcc
	v_rsq_f32_e32 v153, v153
	v_cndmask_b32_e64 v154, v156, v154, s[6:7]
	v_mov_b32_e32 v156, v189
	v_mov_b32_e32 v157, v190
	v_mov_b32_e32 v189, v191
	v_mov_b32_e32 v171, v194
	v_mov_b32_e32 v193, v195
	v_pk_add_f32 v[156:157], v[156:157], v[188:189]
	v_pk_add_f32 v[170:171], v[170:171], v[192:193]
	v_mov_b32_e32 v177, v156
	v_mov_b32_e32 v176, v170
	v_mov_b32_e32 v156, v171
	v_pk_add_f32 v[156:157], v[176:177], v[156:157]
	ds_read_b128 v[180:183], v128 offset:1536
	ds_read_b128 v[184:187], v128 offset:1792
	v_mul_f32_e32 v128, 0x45800000, v153
	v_pk_fma_f32 v[156:157], v[156:157], s[14:15], v[166:167] op_sel_hi:[1,0,0]
	v_cndmask_b32_e32 v178, v153, v128, vcc
	v_mul_f32_e32 v153, 0x4b800000, v157
	v_cmp_gt_f32_e32 vcc, s68, v157
	v_cmp_gt_f32_e64 s[8:9], s68, v156
	v_rsq_f32_e32 v154, v154
	v_cndmask_b32_e32 v153, v157, v153, vcc
	v_mul_f32_e32 v157, 0x4b800000, v156
	v_cndmask_b32_e64 v156, v156, v157, s[8:9]
	v_rsq_f32_e32 v153, v153
	v_rsq_f32_e32 v158, v156
	v_mov_b32_e32 v156, v197
	v_mov_b32_e32 v157, v198
	v_mov_b32_e32 v197, v199
	v_mov_b32_e32 v170, v205
	v_mov_b32_e32 v171, v206
	v_mov_b32_e32 v205, v207
	v_pk_add_f32 v[156:157], v[156:157], v[196:197]
	v_pk_add_f32 v[170:171], v[170:171], v[204:205]
	v_mov_b32_e32 v177, v156
	v_mov_b32_e32 v176, v170
	v_mov_b32_e32 v156, v171
	v_mul_f32_e32 v128, 0x45800000, v154
	v_pk_add_f32 v[156:157], v[176:177], v[156:157]
	v_cndmask_b32_e64 v172, v154, v128, s[6:7]
	v_mul_f32_e32 v128, 0x45800000, v153
	v_pk_fma_f32 v[156:157], v[156:157], s[14:15], v[166:167] op_sel_hi:[1,0,0]
	v_cndmask_b32_e32 v168, v153, v128, vcc
	v_mul_f32_e32 v153, 0x4b800000, v157
	v_cmp_gt_f32_e32 vcc, s68, v157
	v_mul_f32_e32 v154, 0x4b800000, v156
	v_cmp_gt_f32_e64 s[6:7], s68, v156
	v_cndmask_b32_e32 v153, v157, v153, vcc
	v_rsq_f32_e32 v153, v153
	v_cndmask_b32_e64 v154, v156, v154, s[6:7]
	s_waitcnt lgkmcnt(0)
	v_mov_b32_e32 v156, v181
	v_mov_b32_e32 v157, v182
	v_mov_b32_e32 v181, v183
	v_mov_b32_e32 v170, v185
	v_mov_b32_e32 v171, v186
	v_mov_b32_e32 v185, v187
	v_pk_add_f32 v[156:157], v[156:157], v[180:181]
	v_pk_add_f32 v[170:171], v[170:171], v[184:185]
	v_mov_b32_e32 v177, v156
	v_mov_b32_e32 v176, v170
	v_mov_b32_e32 v156, v171
	v_mul_f32_e32 v128, 0x45800000, v158
	v_pk_add_f32 v[156:157], v[176:177], v[156:157]
	v_cndmask_b32_e64 v164, v158, v128, s[8:9]
	v_mul_f32_e32 v128, 0x45800000, v153
	v_pk_fma_f32 v[156:157], v[156:157], s[14:15], v[166:167] op_sel_hi:[1,0,0]
	v_cndmask_b32_e32 v162, v153, v128, vcc
	v_mul_f32_e32 v153, 0x4b800000, v157
	v_cmp_gt_f32_e32 vcc, s68, v157
	v_rsq_f32_e32 v154, v154
	v_cmp_gt_f32_e64 s[8:9], s68, v156
	v_cndmask_b32_e32 v153, v157, v153, vcc
	v_mul_f32_e32 v157, 0x4b800000, v156
	v_rsq_f32_e32 v153, v153
	v_cndmask_b32_e64 v156, v156, v157, s[8:9]
	v_rsq_f32_e32 v156, v156
	v_mul_f32_e32 v128, 0x45800000, v154
	v_cndmask_b32_e64 v160, v154, v128, s[6:7]
	v_mul_f32_e32 v128, 0x45800000, v153
	v_cndmask_b32_e32 v158, v153, v128, vcc
	v_mul_f32_e32 v128, 0x45800000, v156
	v_lshl_or_b32 v174, s53, 6, v142
	v_cndmask_b32_e64 v154, v156, v128, s[8:9]
	v_lshl_add_u32 v156, s62, 8, v169
	s_mov_b64 s[6:7], -1
	s_andn2_b64 vcc, exec, s[64:65]
	v_ashrrev_i32_e32 v175, 31, v174
	v_ashrrev_i32_e32 v157, 31, v156
	v_or_b32_e32 v176, 16, v156
	v_or_b32_e32 v170, 32, v156
	v_or_b32_e32 v166, 48, v156
	s_cbranch_vccz .LBB0_2546
	v_lshlrev_b32_e32 v128, 7, v156
	v_lshl_add_u64 v[180:181], s[66:67], 2, v[144:145]
	v_and_b32_e32 v128, 0x3e780, v128
	global_load_dwordx4 v[182:185], v[180:181], off
	global_load_dwordx4 v[204:207], v[180:181], off offset:16
	v_mov_b32_e32 v153, v129
	v_lshl_add_u64 v[180:181], s[28:29], 0, v[128:129]
	v_lshl_add_u64 v[198:199], v[180:181], 0, v[152:153]
	global_load_dwordx4 v[208:211], v[198:199], off
	global_load_dwordx4 v[212:215], v[198:199], off offset:16
	v_cmp_lt_i32_e32 vcc, v201, v200
	v_mul_f32_e32 v171, v116, v116
	v_mul_f32_e32 v177, v117, v117
	v_cndmask_b32_e32 v128, v159, v201, vcc
	v_pk_mul_f32 v[180:181], v[118:119], v[118:119]
	v_fmac_f32_e32 v171, v124, v124
	v_fmac_f32_e32 v177, v125, v125
	v_lshlrev_b32_e32 v167, 2, v128
	v_pk_fma_f32 v[180:181], v[126:127], v[126:127], v[180:181]
	v_add_f32_e32 v128, v171, v177
	v_pk_mul_f32 v[188:189], v[112:113], v[112:113]
	v_add_f32_e32 v128, v180, v128
	v_pk_fma_f32 v[188:189], v[120:121], v[120:121], v[188:189]
	v_add_f32_e32 v128, v181, v128
	v_pk_mul_f32 v[186:187], v[114:115], v[114:115]
	v_add_f32_e32 v128, v188, v128
	v_pk_fma_f32 v[186:187], v[122:123], v[122:123], v[186:187]
	v_add_f32_e32 v128, v189, v128
	v_add_f32_e32 v128, v186, v128
	v_add_f32_e32 v128, v187, v128
	ds_bpermute_b32 v177, v167, v128
	v_cmp_lt_i32_e32 vcc, v202, v200
	global_load_dwordx4 v[216:219], v[198:199], off offset:2048
	v_lshl_add_u64 v[180:181], v[174:175], 1, s[48:49]
	v_cndmask_b32_e32 v171, v159, v202, vcc
	v_lshlrev_b32_e32 v171, 2, v171
	s_waitcnt lgkmcnt(0)
	v_add_f32_e32 v128, v128, v177
	ds_bpermute_b32 v177, v171, v128
	v_pk_mul_f32 v[234:235], v[80:81], v[80:81]
	s_waitcnt lgkmcnt(0)
	v_add_f32_e32 v128, v128, v177
	v_mul_f32_e32 v128, v178, v128
	v_mul_f32_e32 v128, v178, v128
	v_fmamk_f32 v128, v128, 0x3c800000, v143
	v_mul_f32_e32 v177, 0x4b800000, v128
	v_cmp_gt_f32_e32 vcc, s68, v128
	v_pk_fma_f32 v[234:235], v[88:89], v[88:89], v[234:235]
	s_waitcnt vmcnt(4)
	v_cvt_f32_f16_sdwa v187, v185 dst_sel:DWORD dst_unused:UNUSED_PAD src0_sel:WORD_1
	v_cndmask_b32_e32 v128, v128, v177, vcc
	v_rsq_f32_e32 v128, v128
	v_cvt_f32_f16_sdwa v186, v184 dst_sel:DWORD dst_unused:UNUSED_PAD src0_sel:WORD_1
	v_cvt_f32_f16_sdwa v195, v183 dst_sel:DWORD dst_unused:UNUSED_PAD src0_sel:WORD_1
	v_cvt_f32_f16_sdwa v194, v182 dst_sel:DWORD dst_unused:UNUSED_PAD src0_sel:WORD_1
	v_mul_f32_e32 v177, 0x45800000, v128
	v_cndmask_b32_e32 v128, v128, v177, vcc
	v_cvt_f32_f16_e32 v191, v185
	v_cvt_f32_f16_e32 v190, v184
	v_mul_f32_e32 v128, v178, v128
	v_cvt_f32_f16_e32 v197, v183
	v_cvt_f32_f16_e32 v196, v182
	s_waitcnt vmcnt(2)
	v_cvt_f32_f16_sdwa v189, v209 dst_sel:DWORD dst_unused:UNUSED_PAD src0_sel:WORD_1
	v_cvt_f32_f16_sdwa v188, v208 dst_sel:DWORD dst_unused:UNUSED_PAD src0_sel:WORD_1
	v_cvt_f32_f16_e32 v193, v209
	v_cvt_f32_f16_e32 v192, v208
	v_cvt_f32_f16_e32 v209, v211
	v_cvt_f32_f16_e32 v208, v210
	v_mul_f32_e32 v128, s84, v128
	v_cvt_f32_f16_e32 v185, v205
	v_cvt_f32_f16_e32 v184, v204
	v_cvt_f32_f16_sdwa v183, v205 dst_sel:DWORD dst_unused:UNUSED_PAD src0_sel:WORD_1
	v_cvt_f32_f16_sdwa v182, v204 dst_sel:DWORD dst_unused:UNUSED_PAD src0_sel:WORD_1
	v_cvt_f32_f16_sdwa v205, v211 dst_sel:DWORD dst_unused:UNUSED_PAD src0_sel:WORD_1
	v_cvt_f32_f16_sdwa v204, v210 dst_sel:DWORD dst_unused:UNUSED_PAD src0_sel:WORD_1
	v_pk_mul_f32 v[224:225], v[128:129], v[186:187] op_sel_hi:[0,1]
	v_pk_mul_f32 v[220:221], v[128:129], v[194:195] op_sel_hi:[0,1]
	v_pk_mul_f32 v[222:223], v[128:129], v[190:191] op_sel_hi:[0,1]
	v_pk_mul_f32 v[224:225], v[118:119], v[224:225]
	v_pk_mul_f32 v[210:211], v[128:129], v[196:197] op_sel_hi:[0,1]
	v_pk_mul_f32 v[220:221], v[116:117], v[220:221]
	v_pk_mul_f32 v[222:223], v[126:127], v[222:223]
	v_pk_mul_f32 v[230:231], v[224:225], v[208:209]
	v_pk_mul_f32 v[210:211], v[124:125], v[210:211]
	v_pk_mul_f32 v[228:229], v[220:221], v[192:193]
	v_pk_mul_f32 v[220:221], v[220:221], v[188:189]
	v_pk_mul_f32 v[224:225], v[224:225], v[204:205]
	v_pk_fma_f32 v[204:205], v[222:223], v[204:205], v[230:231]
	v_pk_fma_f32 v[192:193], v[210:211], v[192:193], v[220:221] neg_lo:[0,0,1] neg_hi:[0,0,1]
	v_cvt_pk_bf16_f32 v221, v204, v205
	s_waitcnt vmcnt(1)
	v_cvt_f32_f16_e32 v205, v213
	v_cvt_f32_f16_e32 v204, v212
	v_pk_fma_f32 v[188:189], v[210:211], v[188:189], v[228:229]
	v_pk_fma_f32 v[210:211], v[222:223], v[208:209], v[224:225] neg_lo:[0,0,1] neg_hi:[0,0,1]
	v_cvt_pk_bf16_f32 v208, v192, v193
	v_cvt_f32_f16_sdwa v193, v213 dst_sel:DWORD dst_unused:UNUSED_PAD src0_sel:WORD_1
	v_cvt_f32_f16_sdwa v192, v212 dst_sel:DWORD dst_unused:UNUSED_PAD src0_sel:WORD_1
	v_cvt_pk_bf16_f32 v209, v210, v211
	v_pk_mul_f32 v[210:211], v[128:129], v[182:183] op_sel_hi:[0,1]
	v_pk_mul_f32 v[226:227], v[128:129], v[184:185] op_sel_hi:[0,1]
	v_pk_mul_f32 v[210:211], v[112:113], v[210:211]
	v_cvt_pk_bf16_f32 v220, v188, v189
	v_pk_mul_f32 v[188:189], v[120:121], v[226:227]
	v_pk_mul_f32 v[212:213], v[210:211], v[204:205]
	v_cvt_f32_f16_e32 v225, v215
	v_pk_fma_f32 v[212:213], v[188:189], v[192:193], v[212:213]
	v_pk_mul_f32 v[192:193], v[210:211], v[192:193]
	v_cvt_f32_f16_e32 v224, v214
	v_pk_fma_f32 v[188:189], v[188:189], v[204:205], v[192:193] neg_lo:[0,0,1] neg_hi:[0,0,1]
	v_cvt_f32_f16_e32 v193, v207
	v_cvt_f32_f16_e32 v192, v206
	v_cvt_pk_bf16_f32 v210, v188, v189
	v_cvt_f32_f16_sdwa v189, v207 dst_sel:DWORD dst_unused:UNUSED_PAD src0_sel:WORD_1
	v_cvt_f32_f16_sdwa v188, v206 dst_sel:DWORD dst_unused:UNUSED_PAD src0_sel:WORD_1
	v_pk_mul_f32 v[204:205], v[128:129], v[192:193] op_sel_hi:[0,1]
	v_cvt_pk_bf16_f32 v222, v212, v213
	v_pk_mul_f32 v[212:213], v[122:123], v[204:205]
	v_cvt_f32_f16_sdwa v205, v215 dst_sel:DWORD dst_unused:UNUSED_PAD src0_sel:WORD_1
	v_cvt_f32_f16_sdwa v204, v214 dst_sel:DWORD dst_unused:UNUSED_PAD src0_sel:WORD_1
	v_pk_mul_f32 v[206:207], v[128:129], v[188:189] op_sel_hi:[0,1]
	v_pk_mul_f32 v[206:207], v[114:115], v[206:207]
	v_mul_f32_e32 v128, v100, v100
	v_pk_mul_f32 v[214:215], v[206:207], v[224:225]
	v_mul_f32_e32 v177, v101, v101
	v_pk_fma_f32 v[214:215], v[212:213], v[204:205], v[214:215]
	v_fmac_f32_e32 v128, v108, v108
	v_cvt_pk_bf16_f32 v223, v214, v215
	v_pk_mul_f32 v[214:215], v[206:207], v[204:205]
	global_load_dwordx4 v[204:207], v[198:199], off offset:2064
	v_fmac_f32_e32 v177, v109, v109
	v_pk_mul_f32 v[226:227], v[102:103], v[102:103]
	v_add_f32_e32 v128, v128, v177
	v_pk_fma_f32 v[226:227], v[110:111], v[110:111], v[226:227]
	v_pk_mul_f32 v[228:229], v[96:97], v[96:97]
	v_add_f32_e32 v128, v226, v128
	v_add_f32_e32 v128, v227, v128
	v_pk_fma_f32 v[228:229], v[104:105], v[104:105], v[228:229]
	v_pk_mul_f32 v[226:227], v[98:99], v[98:99]
	v_add_f32_e32 v128, v228, v128
	v_pk_fma_f32 v[226:227], v[106:107], v[106:107], v[226:227]
	v_add_f32_e32 v128, v229, v128
	v_add_f32_e32 v128, v226, v128
	v_add_f32_e32 v128, v227, v128
	ds_bpermute_b32 v226, v167, v128
	v_pk_fma_f32 v[212:213], v[212:213], v[224:225], v[214:215] neg_lo:[0,0,1] neg_hi:[0,0,1]
	v_mul_lo_u32 v214, s61, v156
	v_cvt_pk_bf16_f32 v211, v212, v213
	v_mul_lo_u32 v177, s60, v157
	s_waitcnt lgkmcnt(0)
	v_add_f32_e32 v128, v128, v226
	ds_bpermute_b32 v215, v171, v128
	v_mad_u64_u32 v[212:213], s[6:7], s60, v156, 0
	v_add3_u32 v213, v213, v177, v214
	v_lshl_add_u64 v[212:213], v[212:213], 1, v[180:181]
	s_waitcnt lgkmcnt(0)
	v_add_f32_e32 v128, v128, v215
	v_mul_f32_e32 v128, v172, v128
	v_mul_f32_e32 v128, v172, v128
	v_fmamk_f32 v128, v128, 0x3c800000, v143
	global_store_dwordx4 v[212:213], v[208:211], off
	v_cmp_gt_f32_e32 vcc, s68, v128
	global_store_dwordx4 v[212:213], v[220:223], off offset:64
	v_mul_f32_e32 v208, 0x4b800000, v128
	v_cndmask_b32_e32 v128, v128, v208, vcc
	v_rsq_f32_e32 v128, v128
	s_waitcnt vmcnt(3)
	v_cvt_f32_f16_e32 v213, v217
	v_cvt_f32_f16_e32 v212, v216
	v_cvt_f32_f16_sdwa v211, v217 dst_sel:DWORD dst_unused:UNUSED_PAD src0_sel:WORD_1
	v_mul_f32_e32 v208, 0x45800000, v128
	v_cndmask_b32_e32 v128, v128, v208, vcc
	v_mul_f32_e32 v128, v172, v128
	v_mul_f32_e32 v128, s84, v128
	v_cvt_f32_f16_sdwa v210, v216 dst_sel:DWORD dst_unused:UNUSED_PAD src0_sel:WORD_1
	v_pk_mul_f32 v[214:215], v[128:129], v[194:195] op_sel_hi:[0,1]
	v_pk_mul_f32 v[208:209], v[128:129], v[196:197] op_sel_hi:[0,1]
	v_pk_mul_f32 v[214:215], v[100:101], v[214:215]
	v_pk_mul_f32 v[208:209], v[108:109], v[208:209]
	v_pk_mul_f32 v[216:217], v[214:215], v[212:213]
	v_add_co_u32_e32 v228, vcc, s17, v198
	v_pk_fma_f32 v[216:217], v[208:209], v[210:211], v[216:217]
	v_pk_mul_f32 v[210:211], v[214:215], v[210:211]
	v_addc_co_u32_e32 v229, vcc, 0, v199, vcc
	v_pk_fma_f32 v[212:213], v[208:209], v[212:213], v[210:211] neg_lo:[0,0,1] neg_hi:[0,0,1]
	v_pk_mul_f32 v[208:209], v[128:129], v[190:191] op_sel_hi:[0,1]
	v_pk_mul_f32 v[214:215], v[110:111], v[208:209]
	v_pk_mul_f32 v[208:209], v[128:129], v[186:187] op_sel_hi:[0,1]
	v_cvt_f32_f16_sdwa v223, v219 dst_sel:DWORD dst_unused:UNUSED_PAD src0_sel:WORD_1
	v_cvt_f32_f16_e32 v225, v219
	v_cvt_f32_f16_e32 v224, v218
	v_cvt_f32_f16_sdwa v222, v218 dst_sel:DWORD dst_unused:UNUSED_PAD src0_sel:WORD_1
	v_pk_mul_f32 v[218:219], v[102:103], v[208:209]
	global_load_dwordx4 v[208:211], v[228:229], off
	v_pk_mul_f32 v[226:227], v[218:219], v[224:225]
	v_pk_mul_f32 v[218:219], v[218:219], v[222:223]
	v_pk_fma_f32 v[226:227], v[214:215], v[222:223], v[226:227]
	v_pk_fma_f32 v[214:215], v[214:215], v[224:225], v[218:219] neg_lo:[0,0,1] neg_hi:[0,0,1]
	v_cvt_pk_bf16_f32 v212, v212, v213
	v_cvt_pk_bf16_f32 v213, v214, v215
	v_pk_mul_f32 v[214:215], v[128:129], v[184:185] op_sel_hi:[0,1]
	v_pk_mul_f32 v[214:215], v[104:105], v[214:215]
	v_lshl_add_u64 v[220:221], v[198:199], 0, s[18:19]
	v_cvt_pk_bf16_f32 v216, v216, v217
	v_cvt_pk_bf16_f32 v217, v226, v227
	v_pk_mul_f32 v[230:231], v[128:129], v[188:189] op_sel_hi:[0,1]
	v_lshl_add_u64 v[198:199], v[198:199], 0, s[20:21]
	s_waitcnt vmcnt(3)
	v_cvt_f32_f16_sdwa v223, v205 dst_sel:DWORD dst_unused:UNUSED_PAD src0_sel:WORD_1
	v_cvt_f32_f16_e32 v225, v205
	v_cvt_f32_f16_e32 v224, v204
	v_cvt_f32_f16_sdwa v222, v204 dst_sel:DWORD dst_unused:UNUSED_PAD src0_sel:WORD_1
	v_pk_mul_f32 v[204:205], v[128:129], v[182:183] op_sel_hi:[0,1]
	v_pk_mul_f32 v[204:205], v[96:97], v[204:205]
	v_cvt_f32_f16_e32 v227, v207
	v_pk_mul_f32 v[218:219], v[204:205], v[224:225]
	v_pk_mul_f32 v[204:205], v[204:205], v[222:223]
	v_pk_fma_f32 v[218:219], v[214:215], v[222:223], v[218:219]
	v_pk_fma_f32 v[204:205], v[214:215], v[224:225], v[204:205] neg_lo:[0,0,1] neg_hi:[0,0,1]
	v_cvt_f32_f16_sdwa v225, v207 dst_sel:DWORD dst_unused:UNUSED_PAD src0_sel:WORD_1
	v_cvt_pk_bf16_f32 v214, v204, v205
	v_pk_mul_f32 v[204:205], v[128:129], v[192:193] op_sel_hi:[0,1]
	v_pk_mul_f32 v[222:223], v[106:107], v[204:205]
	v_cvt_f32_f16_sdwa v224, v206 dst_sel:DWORD dst_unused:UNUSED_PAD src0_sel:WORD_1
	v_cvt_f32_f16_e32 v226, v206
	global_load_dwordx4 v[204:207], v[220:221], off offset:16
	v_pk_mul_f32 v[220:221], v[98:99], v[230:231]
	v_mul_f32_e32 v128, v84, v84
	v_pk_mul_f32 v[230:231], v[220:221], v[226:227]
	v_mul_f32_e32 v215, v85, v85
	v_pk_fma_f32 v[230:231], v[222:223], v[224:225], v[230:231]
	v_cvt_pk_bf16_f32 v218, v218, v219
	v_cvt_pk_bf16_f32 v219, v230, v231
	v_fmac_f32_e32 v128, v92, v92
	v_fmac_f32_e32 v215, v93, v93
	v_pk_mul_f32 v[230:231], v[86:87], v[86:87]
	v_add_f32_e32 v128, v128, v215
	v_pk_fma_f32 v[230:231], v[94:95], v[94:95], v[230:231]
	v_pk_mul_f32 v[220:221], v[220:221], v[224:225]
	v_add_f32_e32 v128, v230, v128
	v_add_f32_e32 v128, v231, v128
	v_pk_mul_f32 v[230:231], v[82:83], v[82:83]
	v_add_f32_e32 v128, v234, v128
	v_pk_fma_f32 v[230:231], v[90:91], v[90:91], v[230:231]
	v_add_f32_e32 v128, v235, v128
	v_add_f32_e32 v128, v230, v128
	v_add_f32_e32 v128, v231, v128
	ds_bpermute_b32 v230, v167, v128
	v_pk_fma_f32 v[220:221], v[222:223], v[226:227], v[220:221] neg_lo:[0,0,1] neg_hi:[0,0,1]
	v_mul_lo_u32 v222, s61, v176
	v_cvt_pk_bf16_f32 v215, v220, v221
	v_mad_u64_u32 v[220:221], s[6:7], s60, v176, 0
	s_waitcnt lgkmcnt(0)
	v_add_f32_e32 v128, v128, v230
	ds_bpermute_b32 v223, v171, v128
	v_add3_u32 v221, v221, v177, v222
	v_lshl_add_u64 v[220:221], v[220:221], 1, v[180:181]
	global_store_dwordx4 v[220:221], v[212:215], off
	global_store_dwordx4 v[220:221], v[216:219], off offset:64
	s_waitcnt lgkmcnt(0)
	v_add_f32_e32 v128, v128, v223
	v_mul_f32_e32 v128, v168, v128
	v_mul_f32_e32 v128, v168, v128
	v_fmamk_f32 v128, v128, 0x3c800000, v143
	v_mul_f32_e32 v212, 0x4b800000, v128
	v_cmp_gt_f32_e32 vcc, s68, v128
	s_waitcnt vmcnt(3)
	v_cvt_f32_f16_sdwa v215, v209 dst_sel:DWORD dst_unused:UNUSED_PAD src0_sel:WORD_1
	v_cndmask_b32_e32 v128, v128, v212, vcc
	v_rsq_f32_e32 v128, v128
	v_cvt_f32_f16_e32 v217, v209
	v_cvt_f32_f16_e32 v216, v208
	v_cvt_f32_f16_sdwa v214, v208 dst_sel:DWORD dst_unused:UNUSED_PAD src0_sel:WORD_1
	v_mul_f32_e32 v212, 0x45800000, v128
	v_cndmask_b32_e32 v128, v128, v212, vcc
	v_mul_f32_e32 v128, v168, v128
	v_mul_f32_e32 v128, s84, v128
	v_pk_mul_f32 v[208:209], v[128:129], v[194:195] op_sel_hi:[0,1]
	v_pk_mul_f32 v[212:213], v[128:129], v[196:197] op_sel_hi:[0,1]
	v_pk_mul_f32 v[208:209], v[84:85], v[208:209]
	v_pk_mul_f32 v[212:213], v[92:93], v[212:213]
	v_pk_mul_f32 v[218:219], v[208:209], v[216:217]
	v_pk_mul_f32 v[208:209], v[208:209], v[214:215]
	v_pk_fma_f32 v[218:219], v[212:213], v[214:215], v[218:219]
	v_pk_fma_f32 v[212:213], v[212:213], v[216:217], v[208:209] neg_lo:[0,0,1] neg_hi:[0,0,1]
	v_cvt_f32_f16_sdwa v215, v211 dst_sel:DWORD dst_unused:UNUSED_PAD src0_sel:WORD_1
	v_cvt_f32_f16_e32 v217, v211
	v_cvt_f32_f16_e32 v216, v210
	v_cvt_f32_f16_sdwa v214, v210 dst_sel:DWORD dst_unused:UNUSED_PAD src0_sel:WORD_1
	v_pk_mul_f32 v[210:211], v[128:129], v[186:187] op_sel_hi:[0,1]
	v_pk_mul_f32 v[208:209], v[128:129], v[190:191] op_sel_hi:[0,1]
	v_pk_mul_f32 v[210:211], v[86:87], v[210:211]
	v_pk_mul_f32 v[208:209], v[94:95], v[208:209]
	v_pk_mul_f32 v[220:221], v[210:211], v[216:217]
	v_pk_mul_f32 v[210:211], v[210:211], v[214:215]
	v_pk_fma_f32 v[220:221], v[208:209], v[214:215], v[220:221]
	v_pk_fma_f32 v[214:215], v[208:209], v[216:217], v[210:211] neg_lo:[0,0,1] neg_hi:[0,0,1]
	global_load_dwordx4 v[208:211], v[228:229], off offset:2048
	v_cvt_pk_bf16_f32 v217, v220, v221
	s_waitcnt vmcnt(3)
	v_cvt_f32_f16_sdwa v221, v205 dst_sel:DWORD dst_unused:UNUSED_PAD src0_sel:WORD_1
	v_cvt_f32_f16_e32 v223, v205
	v_cvt_f32_f16_e32 v222, v204
	v_cvt_f32_f16_sdwa v220, v204 dst_sel:DWORD dst_unused:UNUSED_PAD src0_sel:WORD_1
	v_pk_mul_f32 v[204:205], v[128:129], v[182:183] op_sel_hi:[0,1]
	v_cvt_pk_bf16_f32 v212, v212, v213
	v_cvt_pk_bf16_f32 v213, v214, v215
	v_pk_mul_f32 v[214:215], v[128:129], v[184:185] op_sel_hi:[0,1]
	v_pk_mul_f32 v[204:205], v[80:81], v[204:205]
	v_cvt_pk_bf16_f32 v216, v218, v219
	v_pk_mul_f32 v[214:215], v[88:89], v[214:215]
	v_pk_mul_f32 v[218:219], v[204:205], v[222:223]
	v_pk_mul_f32 v[204:205], v[204:205], v[220:221]
	v_cvt_f32_f16_e32 v225, v207
	v_pk_fma_f32 v[204:205], v[214:215], v[222:223], v[204:205] neg_lo:[0,0,1] neg_hi:[0,0,1]
	v_cvt_f32_f16_e32 v224, v206
	v_pk_fma_f32 v[218:219], v[214:215], v[220:221], v[218:219]
	v_cvt_pk_bf16_f32 v214, v204, v205
	v_pk_mul_f32 v[204:205], v[128:129], v[192:193] op_sel_hi:[0,1]
	v_cvt_f32_f16_sdwa v223, v207 dst_sel:DWORD dst_unused:UNUSED_PAD src0_sel:WORD_1
	v_cvt_f32_f16_sdwa v222, v206 dst_sel:DWORD dst_unused:UNUSED_PAD src0_sel:WORD_1
	v_pk_mul_f32 v[220:221], v[90:91], v[204:205]
	v_pk_mul_f32 v[204:205], v[128:129], v[188:189] op_sel_hi:[0,1]
	v_pk_mul_f32 v[226:227], v[82:83], v[204:205]
	v_mul_lo_u32 v128, s61, v170
	v_pk_mul_f32 v[204:205], v[226:227], v[224:225]
	v_cvt_pk_bf16_f32 v218, v218, v219
	v_pk_fma_f32 v[228:229], v[220:221], v[222:223], v[204:205]
	global_load_dwordx4 v[204:207], v[198:199], off offset:16
	v_pk_mul_f32 v[198:199], v[226:227], v[222:223]
	v_cvt_pk_bf16_f32 v219, v228, v229
	v_pk_fma_f32 v[198:199], v[220:221], v[224:225], v[198:199] neg_lo:[0,0,1] neg_hi:[0,0,1]
	s_waitcnt vmcnt(0)
	v_cvt_f32_f16_e32 v223, v205
	v_cvt_pk_bf16_f32 v215, v198, v199
	v_mul_f32_e32 v198, v68, v68
	v_mul_f32_e32 v199, v69, v69
	v_fmac_f32_e32 v198, v76, v76
	v_fmac_f32_e32 v199, v77, v77
	v_add_f32_e32 v220, v198, v199
	v_pk_mul_f32 v[198:199], v[70:71], v[70:71]
	v_cvt_f32_f16_e32 v225, v207
	v_pk_fma_f32 v[198:199], v[78:79], v[78:79], v[198:199]
	v_cvt_f32_f16_e32 v224, v206
	v_add_f32_e32 v198, v198, v220
	v_pk_mul_f32 v[220:221], v[64:65], v[64:65]
	v_add_f32_e32 v222, v199, v198
	v_pk_fma_f32 v[220:221], v[72:73], v[72:73], v[220:221]
	v_pk_mul_f32 v[198:199], v[66:67], v[66:67]
	v_add_f32_e32 v220, v220, v222
	v_pk_fma_f32 v[198:199], v[74:75], v[74:75], v[198:199]
	v_add_f32_e32 v220, v221, v220
	v_add_f32_e32 v198, v198, v220
	v_add_f32_e32 v220, v199, v198
	ds_bpermute_b32 v221, v167, v220
	v_mad_u64_u32 v[198:199], s[6:7], s60, v170, 0
	v_add3_u32 v199, v199, v177, v128
	v_lshl_add_u64 v[198:199], v[198:199], 1, v[180:181]
	s_waitcnt lgkmcnt(0)
	v_add_f32_e32 v128, v220, v221
	ds_bpermute_b32 v220, v171, v128
	global_store_dwordx4 v[198:199], v[212:215], off
	global_store_dwordx4 v[198:199], v[216:219], off offset:64
	v_lshl_add_u32 v198, v156, 5, v161
	v_cvt_f32_f16_sdwa v215, v209 dst_sel:DWORD dst_unused:UNUSED_PAD src0_sel:WORD_1
	v_cvt_f32_f16_e32 v217, v209
	s_waitcnt lgkmcnt(0)
	v_add_f32_e32 v128, v128, v220
	v_mul_f32_e32 v128, v164, v128
	v_mul_f32_e32 v128, v164, v128
	v_fmamk_f32 v128, v128, 0x3c800000, v143
	v_mul_f32_e32 v199, 0x4b800000, v128
	v_cmp_gt_f32_e32 vcc, s68, v128
	v_cvt_f32_f16_e32 v216, v208
	v_cvt_f32_f16_sdwa v214, v208 dst_sel:DWORD dst_unused:UNUSED_PAD src0_sel:WORD_1
	v_cndmask_b32_e32 v128, v128, v199, vcc
	v_rsq_f32_e32 v212, v128
	v_and_b32_e32 v128, 0xf9e0, v198
	v_lshlrev_b32_e32 v128, 2, v128
	v_lshl_add_u64 v[198:199], v[146:147], 0, v[128:129]
	v_mul_f32_e32 v128, 0x45800000, v212
	v_cndmask_b32_e32 v128, v212, v128, vcc
	v_mul_f32_e32 v128, v164, v128
	v_mul_f32_e32 v128, s84, v128
	v_pk_mul_f32 v[208:209], v[128:129], v[194:195] op_sel_hi:[0,1]
	v_pk_mul_f32 v[212:213], v[128:129], v[196:197] op_sel_hi:[0,1]
	v_pk_mul_f32 v[208:209], v[68:69], v[208:209]
	v_pk_mul_f32 v[212:213], v[76:77], v[212:213]
	v_pk_mul_f32 v[218:219], v[208:209], v[216:217]
	v_pk_mul_f32 v[208:209], v[208:209], v[214:215]
	v_pk_fma_f32 v[218:219], v[212:213], v[214:215], v[218:219]
	v_pk_fma_f32 v[208:209], v[212:213], v[216:217], v[208:209] neg_lo:[0,0,1] neg_hi:[0,0,1]
	v_cvt_f32_f16_sdwa v215, v211 dst_sel:DWORD dst_unused:UNUSED_PAD src0_sel:WORD_1
	v_cvt_f32_f16_e32 v217, v211
	v_cvt_f32_f16_e32 v216, v210
	v_cvt_f32_f16_sdwa v214, v210 dst_sel:DWORD dst_unused:UNUSED_PAD src0_sel:WORD_1
	v_pk_mul_f32 v[210:211], v[128:129], v[186:187] op_sel_hi:[0,1]
	v_pk_mul_f32 v[212:213], v[128:129], v[190:191] op_sel_hi:[0,1]
	v_pk_mul_f32 v[210:211], v[70:71], v[210:211]
	v_pk_mul_f32 v[212:213], v[78:79], v[212:213]
	v_pk_mul_f32 v[220:221], v[210:211], v[216:217]
	v_pk_mul_f32 v[210:211], v[210:211], v[214:215]
	v_pk_fma_f32 v[220:221], v[212:213], v[214:215], v[220:221]
	v_pk_fma_f32 v[210:211], v[212:213], v[216:217], v[210:211] neg_lo:[0,0,1] neg_hi:[0,0,1]
	global_load_dwordx4 v[212:215], v[198:199], off
	v_cvt_pk_bf16_f32 v217, v220, v221
	v_cvt_f32_f16_sdwa v221, v205 dst_sel:DWORD dst_unused:UNUSED_PAD src0_sel:WORD_1
	v_cvt_f32_f16_e32 v222, v204
	v_cvt_f32_f16_sdwa v220, v204 dst_sel:DWORD dst_unused:UNUSED_PAD src0_sel:WORD_1
	v_pk_mul_f32 v[204:205], v[128:129], v[182:183] op_sel_hi:[0,1]
	v_cvt_pk_bf16_f32 v208, v208, v209
	v_cvt_pk_bf16_f32 v209, v210, v211
	v_pk_mul_f32 v[210:211], v[128:129], v[184:185] op_sel_hi:[0,1]
	v_pk_mul_f32 v[204:205], v[64:65], v[204:205]
	v_cvt_pk_bf16_f32 v216, v218, v219
	v_pk_mul_f32 v[210:211], v[72:73], v[210:211]
	v_pk_mul_f32 v[218:219], v[204:205], v[222:223]
	v_pk_mul_f32 v[204:205], v[204:205], v[220:221]
	v_pk_fma_f32 v[218:219], v[210:211], v[220:221], v[218:219]
	v_pk_fma_f32 v[204:205], v[210:211], v[222:223], v[204:205] neg_lo:[0,0,1] neg_hi:[0,0,1]
	v_cvt_f32_f16_sdwa v223, v207 dst_sel:DWORD dst_unused:UNUSED_PAD src0_sel:WORD_1
	v_cvt_pk_bf16_f32 v210, v204, v205
	v_pk_mul_f32 v[204:205], v[128:129], v[192:193] op_sel_hi:[0,1]
	v_cvt_f32_f16_sdwa v222, v206 dst_sel:DWORD dst_unused:UNUSED_PAD src0_sel:WORD_1
	v_pk_mul_f32 v[220:221], v[74:75], v[204:205]
	v_pk_mul_f32 v[204:205], v[128:129], v[188:189] op_sel_hi:[0,1]
	v_pk_mul_f32 v[226:227], v[66:67], v[204:205]
	v_cvt_pk_bf16_f32 v218, v218, v219
	v_pk_mul_f32 v[204:205], v[226:227], v[224:225]
	v_mul_lo_u32 v128, s61, v166
	v_pk_fma_f32 v[204:205], v[220:221], v[222:223], v[204:205]
	s_nop 0
	v_cvt_pk_bf16_f32 v219, v204, v205
	global_load_dwordx4 v[204:207], v[198:199], off offset:16
	v_pk_mul_f32 v[198:199], v[226:227], v[222:223]
	v_add_u32_e32 v226, 0x80, v156
	v_pk_fma_f32 v[198:199], v[220:221], v[224:225], v[198:199] neg_lo:[0,0,1] neg_hi:[0,0,1]
	s_waitcnt vmcnt(0)
	v_cvt_f32_f16_e32 v223, v205
	v_cvt_pk_bf16_f32 v211, v198, v199
	v_mul_f32_e32 v198, v52, v52
	v_mul_f32_e32 v199, v53, v53
	v_fmac_f32_e32 v198, v60, v60
	v_fmac_f32_e32 v199, v61, v61
	v_add_f32_e32 v220, v198, v199
	v_pk_mul_f32 v[198:199], v[54:55], v[54:55]
	s_nop 0
	v_pk_fma_f32 v[198:199], v[62:63], v[62:63], v[198:199]
	s_nop 0
	v_add_f32_e32 v198, v198, v220
	v_pk_mul_f32 v[220:221], v[48:49], v[48:49]
	v_add_f32_e32 v222, v199, v198
	v_pk_fma_f32 v[220:221], v[56:57], v[56:57], v[220:221]
	v_pk_mul_f32 v[198:199], v[50:51], v[50:51]
	v_add_f32_e32 v220, v220, v222
	v_pk_fma_f32 v[198:199], v[58:59], v[58:59], v[198:199]
	v_add_f32_e32 v220, v221, v220
	v_add_f32_e32 v198, v198, v220
	v_add_f32_e32 v220, v199, v198
	ds_bpermute_b32 v221, v167, v220
	v_mad_u64_u32 v[198:199], s[6:7], s60, v166, 0
	v_add3_u32 v199, v199, v177, v128
	v_lshl_add_u64 v[198:199], v[198:199], 1, v[180:181]
	s_waitcnt lgkmcnt(0)
	v_add_f32_e32 v128, v220, v221
	ds_bpermute_b32 v177, v171, v128
	global_store_dwordx4 v[198:199], v[208:211], off
	global_store_dwordx4 v[198:199], v[216:219], off offset:64
	v_lshlrev_b32_e32 v198, 7, v226
	v_cvt_f32_f16_sdwa v211, v213 dst_sel:DWORD dst_unused:UNUSED_PAD src0_sel:WORD_1
	s_waitcnt lgkmcnt(0)
	v_add_f32_e32 v128, v128, v177
	v_mul_f32_e32 v128, v162, v128
	v_mul_f32_e32 v128, v162, v128
	v_fmamk_f32 v128, v128, 0x3c800000, v143
	v_mul_f32_e32 v177, 0x4b800000, v128
	v_cmp_gt_f32_e32 vcc, s68, v128
	v_cvt_f32_f16_e32 v217, v213
	v_cvt_f32_f16_e32 v216, v212
	v_cndmask_b32_e32 v128, v128, v177, vcc
	v_rsq_f32_e32 v177, v128
	v_and_b32_e32 v128, 0x3e780, v198
	v_lshl_add_u64 v[198:199], s[28:29], 0, v[128:129]
	v_cvt_f32_f16_sdwa v210, v212 dst_sel:DWORD dst_unused:UNUSED_PAD src0_sel:WORD_1
	v_mul_f32_e32 v128, 0x45800000, v177
	v_cndmask_b32_e32 v128, v177, v128, vcc
	v_mul_f32_e32 v128, v162, v128
	v_mul_f32_e32 v128, s84, v128
	v_pk_mul_f32 v[212:213], v[128:129], v[194:195] op_sel_hi:[0,1]
	v_pk_mul_f32 v[208:209], v[128:129], v[196:197] op_sel_hi:[0,1]
	v_pk_mul_f32 v[212:213], v[52:53], v[212:213]
	v_pk_mul_f32 v[208:209], v[60:61], v[208:209]
	v_pk_mul_f32 v[218:219], v[212:213], v[216:217]
	v_lshl_add_u64 v[198:199], v[198:199], 0, v[152:153]
	v_pk_fma_f32 v[218:219], v[208:209], v[210:211], v[218:219]
	v_pk_mul_f32 v[210:211], v[212:213], v[210:211]
	v_cvt_f32_f16_e32 v222, v204
	v_pk_fma_f32 v[212:213], v[208:209], v[216:217], v[210:211] neg_lo:[0,0,1] neg_hi:[0,0,1]
	v_cvt_f32_f16_e32 v217, v215
	v_cvt_f32_f16_e32 v216, v214
	v_cvt_f32_f16_sdwa v211, v215 dst_sel:DWORD dst_unused:UNUSED_PAD src0_sel:WORD_1
	v_cvt_f32_f16_sdwa v210, v214 dst_sel:DWORD dst_unused:UNUSED_PAD src0_sel:WORD_1
	v_pk_mul_f32 v[214:215], v[128:129], v[186:187] op_sel_hi:[0,1]
	v_pk_mul_f32 v[208:209], v[128:129], v[190:191] op_sel_hi:[0,1]
	v_pk_mul_f32 v[214:215], v[54:55], v[214:215]
	v_pk_mul_f32 v[208:209], v[62:63], v[208:209]
	v_pk_mul_f32 v[220:221], v[214:215], v[216:217]
	v_cvt_pk_bf16_f32 v212, v212, v213
	v_pk_fma_f32 v[220:221], v[208:209], v[210:211], v[220:221]
	v_pk_mul_f32 v[210:211], v[214:215], v[210:211]
	v_mul_f32_e32 v153, v36, v36
	v_pk_fma_f32 v[214:215], v[208:209], v[216:217], v[210:211] neg_lo:[0,0,1] neg_hi:[0,0,1]
	global_load_dwordx4 v[208:211], v[198:199], off offset:2048
	v_cvt_pk_bf16_f32 v217, v220, v221
	v_cvt_f32_f16_sdwa v221, v205 dst_sel:DWORD dst_unused:UNUSED_PAD src0_sel:WORD_1
	v_cvt_f32_f16_sdwa v220, v204 dst_sel:DWORD dst_unused:UNUSED_PAD src0_sel:WORD_1
	v_pk_mul_f32 v[204:205], v[128:129], v[182:183] op_sel_hi:[0,1]
	v_cvt_pk_bf16_f32 v213, v214, v215
	v_pk_mul_f32 v[214:215], v[128:129], v[184:185] op_sel_hi:[0,1]
	v_pk_mul_f32 v[204:205], v[48:49], v[204:205]
	v_cvt_pk_bf16_f32 v216, v218, v219
	v_pk_mul_f32 v[214:215], v[56:57], v[214:215]
	v_pk_mul_f32 v[218:219], v[204:205], v[222:223]
	v_pk_mul_f32 v[204:205], v[204:205], v[220:221]
	v_pk_fma_f32 v[218:219], v[214:215], v[220:221], v[218:219]
	v_pk_fma_f32 v[204:205], v[214:215], v[222:223], v[204:205] neg_lo:[0,0,1] neg_hi:[0,0,1]
	v_cvt_f32_f16_sdwa v221, v207 dst_sel:DWORD dst_unused:UNUSED_PAD src0_sel:WORD_1
	v_cvt_f32_f16_e32 v223, v207
	v_cvt_f32_f16_e32 v222, v206
	v_cvt_f32_f16_sdwa v220, v206 dst_sel:DWORD dst_unused:UNUSED_PAD src0_sel:WORD_1
	v_pk_mul_f32 v[206:207], v[128:129], v[188:189] op_sel_hi:[0,1]
	v_cvt_pk_bf16_f32 v214, v204, v205
	v_pk_mul_f32 v[204:205], v[128:129], v[192:193] op_sel_hi:[0,1]
	v_pk_mul_f32 v[206:207], v[50:51], v[206:207]
	v_pk_mul_f32 v[204:205], v[58:59], v[204:205]
	v_pk_mul_f32 v[224:225], v[206:207], v[222:223]
	v_pk_mul_f32 v[206:207], v[206:207], v[220:221]
	v_pk_fma_f32 v[224:225], v[204:205], v[220:221], v[224:225]
	v_pk_fma_f32 v[204:205], v[204:205], v[222:223], v[206:207] neg_lo:[0,0,1] neg_hi:[0,0,1]
	v_mul_f32_e32 v177, v37, v37
	v_cvt_pk_bf16_f32 v215, v204, v205
	global_load_dwordx4 v[204:207], v[198:199], off offset:2064
	v_fmac_f32_e32 v153, v44, v44
	v_fmac_f32_e32 v177, v45, v45
	v_pk_mul_f32 v[220:221], v[38:39], v[38:39]
	v_add_f32_e32 v153, v153, v177
	v_pk_fma_f32 v[220:221], v[46:47], v[46:47], v[220:221]
	v_pk_mul_f32 v[222:223], v[32:33], v[32:33]
	v_add_f32_e32 v153, v220, v153
	v_add_f32_e32 v153, v221, v153
	v_pk_fma_f32 v[222:223], v[40:41], v[40:41], v[222:223]
	v_pk_mul_f32 v[220:221], v[34:35], v[34:35]
	v_add_f32_e32 v153, v222, v153
	v_pk_fma_f32 v[220:221], v[42:43], v[42:43], v[220:221]
	v_add_f32_e32 v153, v223, v153
	v_add_f32_e32 v153, v220, v153
	v_add_f32_e32 v153, v221, v153
	ds_bpermute_b32 v177, v167, v153
	v_ashrrev_i32_e32 v128, 31, v226
	v_mul_lo_u32 v128, s60, v128
	v_mul_lo_u32 v222, s61, v226
	v_mad_u64_u32 v[220:221], s[6:7], s60, v226, 0
	s_waitcnt lgkmcnt(0)
	v_add_f32_e32 v153, v153, v177
	ds_bpermute_b32 v177, v171, v153
	v_add3_u32 v221, v221, v128, v222
	v_lshl_add_u64 v[220:221], v[220:221], 1, v[180:181]
	v_cvt_pk_bf16_f32 v218, v218, v219
	v_cvt_pk_bf16_f32 v219, v224, v225
	s_waitcnt lgkmcnt(0)
	v_add_f32_e32 v128, v153, v177
	v_mul_f32_e32 v128, v160, v128
	v_mul_f32_e32 v128, v160, v128
	v_fmamk_f32 v128, v128, 0x3c800000, v143
	v_mul_f32_e32 v153, 0x4b800000, v128
	v_cmp_gt_f32_e32 vcc, s68, v128
	global_store_dwordx4 v[220:221], v[212:215], off
	global_store_dwordx4 v[220:221], v[216:219], off offset:64
	v_cndmask_b32_e32 v128, v128, v153, vcc
	v_rsq_f32_e32 v128, v128
	v_lshl_add_u64 v[220:221], v[198:199], 0, s[18:19]
	v_add_u32_e32 v153, 0x90, v156
	v_mul_f32_e32 v177, 0x45800000, v128
	v_cndmask_b32_e32 v128, v128, v177, vcc
	v_mul_f32_e32 v128, v160, v128
	v_mul_f32_e32 v128, s84, v128
	v_pk_mul_f32 v[212:213], v[128:129], v[196:197] op_sel_hi:[0,1]
	v_pk_mul_f32 v[212:213], v[44:45], v[212:213]
	v_add_co_u32_e32 v224, vcc, s17, v198
	v_mul_f32_e32 v177, v20, v20
	s_nop 0
	v_addc_co_u32_e32 v225, vcc, 0, v199, vcc
	s_waitcnt vmcnt(3)
	v_cvt_f32_f16_sdwa v215, v209 dst_sel:DWORD dst_unused:UNUSED_PAD src0_sel:WORD_1
	v_cvt_f32_f16_e32 v217, v209
	v_cvt_f32_f16_e32 v216, v208
	v_cvt_f32_f16_sdwa v214, v208 dst_sel:DWORD dst_unused:UNUSED_PAD src0_sel:WORD_1
	v_pk_mul_f32 v[208:209], v[128:129], v[194:195] op_sel_hi:[0,1]
	v_pk_mul_f32 v[208:209], v[36:37], v[208:209]
	v_fmac_f32_e32 v177, v28, v28
	v_pk_mul_f32 v[218:219], v[208:209], v[216:217]
	v_pk_mul_f32 v[208:209], v[208:209], v[214:215]
	v_pk_fma_f32 v[218:219], v[212:213], v[214:215], v[218:219]
	v_pk_fma_f32 v[212:213], v[212:213], v[216:217], v[208:209] neg_lo:[0,0,1] neg_hi:[0,0,1]
	v_cvt_f32_f16_sdwa v215, v211 dst_sel:DWORD dst_unused:UNUSED_PAD src0_sel:WORD_1
	v_cvt_f32_f16_e32 v217, v211
	v_cvt_f32_f16_e32 v216, v210
	v_cvt_f32_f16_sdwa v214, v210 dst_sel:DWORD dst_unused:UNUSED_PAD src0_sel:WORD_1
	v_pk_mul_f32 v[210:211], v[128:129], v[186:187] op_sel_hi:[0,1]
	v_pk_mul_f32 v[208:209], v[128:129], v[190:191] op_sel_hi:[0,1]
	v_pk_mul_f32 v[210:211], v[38:39], v[210:211]
	v_pk_mul_f32 v[208:209], v[46:47], v[208:209]
	v_pk_mul_f32 v[222:223], v[210:211], v[216:217]
	v_pk_mul_f32 v[210:211], v[210:211], v[214:215]
	v_pk_fma_f32 v[222:223], v[208:209], v[214:215], v[222:223]
	v_pk_fma_f32 v[214:215], v[208:209], v[216:217], v[210:211] neg_lo:[0,0,1] neg_hi:[0,0,1]
	global_load_dwordx4 v[208:211], v[224:225], off
	v_cvt_pk_bf16_f32 v217, v222, v223
	v_cvt_pk_bf16_f32 v212, v212, v213
	v_cvt_pk_bf16_f32 v213, v214, v215
	v_pk_mul_f32 v[214:215], v[128:129], v[184:185] op_sel_hi:[0,1]
	v_cvt_pk_bf16_f32 v216, v218, v219
	s_waitcnt vmcnt(3)
	v_cvt_f32_f16_sdwa v223, v205 dst_sel:DWORD dst_unused:UNUSED_PAD src0_sel:WORD_1
	v_cvt_f32_f16_e32 v227, v205
	v_cvt_f32_f16_e32 v226, v204
	v_cvt_f32_f16_sdwa v222, v204 dst_sel:DWORD dst_unused:UNUSED_PAD src0_sel:WORD_1
	v_pk_mul_f32 v[204:205], v[128:129], v[182:183] op_sel_hi:[0,1]
	v_pk_mul_f32 v[204:205], v[32:33], v[204:205]
	v_pk_mul_f32 v[214:215], v[40:41], v[214:215]
	v_pk_mul_f32 v[218:219], v[204:205], v[226:227]
	v_pk_mul_f32 v[204:205], v[204:205], v[222:223]
	v_cvt_f32_f16_e32 v229, v207
	v_pk_fma_f32 v[204:205], v[214:215], v[226:227], v[204:205] neg_lo:[0,0,1] neg_hi:[0,0,1]
	v_cvt_f32_f16_e32 v228, v206
	v_pk_fma_f32 v[218:219], v[214:215], v[222:223], v[218:219]
	v_cvt_pk_bf16_f32 v214, v204, v205
	v_pk_mul_f32 v[204:205], v[128:129], v[192:193] op_sel_hi:[0,1]
	v_cvt_f32_f16_sdwa v227, v207 dst_sel:DWORD dst_unused:UNUSED_PAD src0_sel:WORD_1
	v_cvt_f32_f16_sdwa v226, v206 dst_sel:DWORD dst_unused:UNUSED_PAD src0_sel:WORD_1
	v_pk_mul_f32 v[222:223], v[42:43], v[204:205]
	v_pk_mul_f32 v[204:205], v[128:129], v[188:189] op_sel_hi:[0,1]
	v_pk_mul_f32 v[230:231], v[34:35], v[204:205]
	v_ashrrev_i32_e32 v128, 31, v153
	v_pk_mul_f32 v[204:205], v[230:231], v[228:229]
	v_mul_lo_u32 v128, s60, v128
	v_pk_fma_f32 v[234:235], v[222:223], v[226:227], v[204:205]
	global_load_dwordx4 v[204:207], v[220:221], off offset:16
	v_pk_mul_f32 v[220:221], v[230:231], v[226:227]
	v_cvt_pk_bf16_f32 v218, v218, v219
	v_pk_fma_f32 v[220:221], v[222:223], v[228:229], v[220:221] neg_lo:[0,0,1] neg_hi:[0,0,1]
	v_pk_mul_f32 v[222:223], v[16:17], v[16:17]
	v_cvt_pk_bf16_f32 v215, v220, v221
	v_mul_f32_e32 v220, v21, v21
	v_fmac_f32_e32 v220, v29, v29
	v_add_f32_e32 v177, v177, v220
	v_pk_mul_f32 v[220:221], v[22:23], v[22:23]
	v_pk_fma_f32 v[222:223], v[24:25], v[24:25], v[222:223]
	v_pk_fma_f32 v[220:221], v[30:31], v[30:31], v[220:221]
	v_cvt_pk_bf16_f32 v219, v234, v235
	v_add_f32_e32 v177, v220, v177
	v_add_f32_e32 v177, v221, v177
	v_pk_mul_f32 v[220:221], v[18:19], v[18:19]
	v_add_f32_e32 v177, v222, v177
	v_pk_fma_f32 v[220:221], v[26:27], v[26:27], v[220:221]
	v_add_f32_e32 v177, v223, v177
	v_add_f32_e32 v177, v220, v177
	v_add_f32_e32 v177, v221, v177
	ds_bpermute_b32 v222, v167, v177
	v_mul_lo_u32 v223, s61, v153
	v_mad_u64_u32 v[220:221], s[6:7], s60, v153, 0
	v_add3_u32 v221, v221, v128, v223
	s_waitcnt lgkmcnt(0)
	v_add_f32_e32 v153, v177, v222
	ds_bpermute_b32 v177, v171, v153
	v_lshl_add_u64 v[220:221], v[220:221], 1, v[180:181]
	global_store_dwordx4 v[220:221], v[212:215], off
	global_store_dwordx4 v[220:221], v[216:219], off offset:64
	v_lshl_add_u64 v[198:199], v[198:199], 0, s[20:21]
	s_waitcnt lgkmcnt(0)
	v_add_f32_e32 v128, v153, v177
	v_mul_f32_e32 v128, v158, v128
	v_mul_f32_e32 v128, v158, v128
	v_fmamk_f32 v128, v128, 0x3c800000, v143
	v_mul_f32_e32 v153, 0x4b800000, v128
	v_cmp_gt_f32_e32 vcc, s68, v128
	s_waitcnt vmcnt(3)
	v_cvt_f32_f16_sdwa v215, v209 dst_sel:DWORD dst_unused:UNUSED_PAD src0_sel:WORD_1
	v_cndmask_b32_e32 v128, v128, v153, vcc
	v_rsq_f32_e32 v128, v128
	v_cvt_f32_f16_e32 v217, v209
	v_cvt_f32_f16_e32 v216, v208
	v_cvt_f32_f16_sdwa v214, v208 dst_sel:DWORD dst_unused:UNUSED_PAD src0_sel:WORD_1
	v_mul_f32_e32 v177, 0x45800000, v128
	v_cndmask_b32_e32 v128, v128, v177, vcc
	v_mul_f32_e32 v128, v158, v128
	v_mul_f32_e32 v128, s84, v128
	v_pk_mul_f32 v[208:209], v[128:129], v[194:195] op_sel_hi:[0,1]
	v_pk_mul_f32 v[212:213], v[128:129], v[196:197] op_sel_hi:[0,1]
	v_pk_mul_f32 v[208:209], v[20:21], v[208:209]
	v_pk_mul_f32 v[212:213], v[28:29], v[212:213]
	v_pk_mul_f32 v[218:219], v[208:209], v[216:217]
	v_pk_mul_f32 v[208:209], v[208:209], v[214:215]
	v_pk_fma_f32 v[218:219], v[212:213], v[214:215], v[218:219]
	v_pk_fma_f32 v[212:213], v[212:213], v[216:217], v[208:209] neg_lo:[0,0,1] neg_hi:[0,0,1]
	v_pk_mul_f32 v[208:209], v[128:129], v[190:191] op_sel_hi:[0,1]
	v_cvt_f32_f16_e32 v217, v211
	v_cvt_f32_f16_e32 v216, v210
	v_pk_mul_f32 v[214:215], v[30:31], v[208:209]
	v_cvt_f32_f16_sdwa v209, v211 dst_sel:DWORD dst_unused:UNUSED_PAD src0_sel:WORD_1
	v_cvt_f32_f16_sdwa v208, v210 dst_sel:DWORD dst_unused:UNUSED_PAD src0_sel:WORD_1
	v_pk_mul_f32 v[210:211], v[128:129], v[186:187] op_sel_hi:[0,1]
	v_pk_mul_f32 v[210:211], v[22:23], v[210:211]
	v_cvt_pk_bf16_f32 v212, v212, v213
	v_pk_mul_f32 v[220:221], v[210:211], v[216:217]
	v_pk_mul_f32 v[222:223], v[210:211], v[208:209]
	v_pk_fma_f32 v[220:221], v[214:215], v[208:209], v[220:221]
	global_load_dwordx4 v[208:211], v[224:225], off offset:2048
	v_pk_fma_f32 v[214:215], v[214:215], v[216:217], v[222:223] neg_lo:[0,0,1] neg_hi:[0,0,1]
	v_cvt_pk_bf16_f32 v217, v220, v221
	s_waitcnt vmcnt(3)
	v_cvt_f32_f16_sdwa v221, v205 dst_sel:DWORD dst_unused:UNUSED_PAD src0_sel:WORD_1
	v_cvt_f32_f16_e32 v223, v205
	v_cvt_f32_f16_e32 v222, v204
	v_cvt_f32_f16_sdwa v220, v204 dst_sel:DWORD dst_unused:UNUSED_PAD src0_sel:WORD_1
	v_pk_mul_f32 v[204:205], v[128:129], v[182:183] op_sel_hi:[0,1]
	v_cvt_pk_bf16_f32 v213, v214, v215
	v_pk_mul_f32 v[214:215], v[128:129], v[184:185] op_sel_hi:[0,1]
	v_pk_mul_f32 v[204:205], v[16:17], v[204:205]
	v_cvt_pk_bf16_f32 v216, v218, v219
	v_pk_mul_f32 v[214:215], v[24:25], v[214:215]
	v_pk_mul_f32 v[218:219], v[204:205], v[222:223]
	v_pk_mul_f32 v[204:205], v[204:205], v[220:221]
	v_pk_fma_f32 v[218:219], v[214:215], v[220:221], v[218:219]
	v_pk_fma_f32 v[204:205], v[214:215], v[222:223], v[204:205] neg_lo:[0,0,1] neg_hi:[0,0,1]
	v_cvt_f32_f16_sdwa v223, v207 dst_sel:DWORD dst_unused:UNUSED_PAD src0_sel:WORD_1
	v_cvt_pk_bf16_f32 v214, v204, v205
	v_pk_mul_f32 v[204:205], v[128:129], v[192:193] op_sel_hi:[0,1]
	v_pk_mul_f32 v[220:221], v[26:27], v[204:205]
	v_pk_mul_f32 v[204:205], v[128:129], v[188:189] op_sel_hi:[0,1]
	v_cvt_f32_f16_sdwa v222, v206 dst_sel:DWORD dst_unused:UNUSED_PAD src0_sel:WORD_1
	v_cvt_f32_f16_e32 v225, v207
	v_cvt_f32_f16_e32 v224, v206
	v_pk_mul_f32 v[226:227], v[18:19], v[204:205]
	global_load_dwordx4 v[204:207], v[198:199], off offset:16
	v_cvt_pk_bf16_f32 v218, v218, v219
	v_pk_mul_f32 v[198:199], v[226:227], v[224:225]
	v_mul_f32_e32 v128, v4, v4
	v_pk_fma_f32 v[198:199], v[220:221], v[222:223], v[198:199]
	v_mul_f32_e32 v177, v5, v5
	v_cvt_pk_bf16_f32 v219, v198, v199
	v_pk_mul_f32 v[198:199], v[226:227], v[222:223]
	v_fmac_f32_e32 v128, v12, v12
	v_pk_fma_f32 v[198:199], v[220:221], v[224:225], v[198:199] neg_lo:[0,0,1] neg_hi:[0,0,1]
	v_fmac_f32_e32 v177, v13, v13
	v_pk_mul_f32 v[220:221], v[6:7], v[6:7]
	v_add_f32_e32 v128, v128, v177
	v_pk_fma_f32 v[220:221], v[14:15], v[14:15], v[220:221]
	v_pk_mul_f32 v[222:223], v[0:1], v[0:1]
	v_add_f32_e32 v128, v220, v128
	v_add_f32_e32 v128, v221, v128
	v_pk_fma_f32 v[222:223], v[8:9], v[8:9], v[222:223]
	v_pk_mul_f32 v[220:221], v[2:3], v[2:3]
	v_add_f32_e32 v128, v222, v128
	v_pk_fma_f32 v[220:221], v[10:11], v[10:11], v[220:221]
	v_add_f32_e32 v128, v223, v128
	v_add_f32_e32 v128, v220, v128
	v_add_f32_e32 v128, v221, v128
	ds_bpermute_b32 v167, v167, v128
	v_add_u32_e32 v153, 0xa0, v156
	v_cvt_pk_bf16_f32 v215, v198, v199
	v_ashrrev_i32_e32 v177, 31, v153
	v_mul_lo_u32 v220, s61, v153
	s_waitcnt lgkmcnt(0)
	v_add_f32_e32 v128, v128, v167
	ds_bpermute_b32 v167, v171, v128
	v_mad_u64_u32 v[198:199], s[6:7], s60, v153, 0
	v_mul_lo_u32 v177, s60, v177
	v_add3_u32 v199, v199, v177, v220
	s_waitcnt lgkmcnt(0)
	v_add_f32_e32 v128, v128, v167
	v_mul_f32_e32 v128, v154, v128
	v_mul_f32_e32 v128, v154, v128
	v_fmamk_f32 v128, v128, 0x3c800000, v143
	v_mul_f32_e32 v153, 0x4b800000, v128
	v_cmp_gt_f32_e32 vcc, s68, v128
	v_lshl_add_u64 v[198:199], v[198:199], 1, v[180:181]
	global_store_dwordx4 v[198:199], v[212:215], off
	v_cndmask_b32_e32 v128, v128, v153, vcc
	v_rsq_f32_e32 v128, v128
	global_store_dwordx4 v[198:199], v[216:219], off offset:64
	v_add_u32_e32 v153, 0xb0, v156
	v_mul_f32_e32 v167, 0x45800000, v128
	v_cndmask_b32_e32 v128, v128, v167, vcc
	v_mul_f32_e32 v128, v154, v128
	v_mul_f32_e32 v128, s84, v128
	v_pk_mul_f32 v[194:195], v[128:129], v[194:195] op_sel_hi:[0,1]
	v_pk_mul_f32 v[196:197], v[128:129], v[196:197] op_sel_hi:[0,1]
	s_waitcnt vmcnt(3)
	v_cvt_f32_f16_sdwa v199, v209 dst_sel:DWORD dst_unused:UNUSED_PAD src0_sel:WORD_1
	v_cvt_f32_f16_e32 v213, v209
	v_cvt_f32_f16_e32 v212, v208
	v_cvt_f32_f16_sdwa v198, v208 dst_sel:DWORD dst_unused:UNUSED_PAD src0_sel:WORD_1
	v_pk_mul_f32 v[194:195], v[4:5], v[194:195]
	v_pk_mul_f32 v[196:197], v[12:13], v[196:197]
	v_pk_mul_f32 v[208:209], v[194:195], v[212:213]
	v_pk_mul_f32 v[194:195], v[194:195], v[198:199]
	v_pk_fma_f32 v[208:209], v[196:197], v[198:199], v[208:209]
	v_pk_fma_f32 v[194:195], v[196:197], v[212:213], v[194:195] neg_lo:[0,0,1] neg_hi:[0,0,1]
	v_cvt_f32_f16_sdwa v197, v211 dst_sel:DWORD dst_unused:UNUSED_PAD src0_sel:WORD_1
	v_cvt_f32_f16_e32 v199, v211
	v_cvt_f32_f16_e32 v198, v210
	v_cvt_f32_f16_sdwa v196, v210 dst_sel:DWORD dst_unused:UNUSED_PAD src0_sel:WORD_1
	v_pk_mul_f32 v[186:187], v[128:129], v[186:187] op_sel_hi:[0,1]
	v_pk_mul_f32 v[190:191], v[128:129], v[190:191] op_sel_hi:[0,1]
	v_pk_mul_f32 v[186:187], v[6:7], v[186:187]
	v_pk_mul_f32 v[190:191], v[14:15], v[190:191]
	v_pk_mul_f32 v[210:211], v[186:187], v[198:199]
	v_pk_mul_f32 v[186:187], v[186:187], v[196:197]
	v_pk_fma_f32 v[210:211], v[190:191], v[196:197], v[210:211]
	v_pk_fma_f32 v[186:187], v[190:191], v[198:199], v[186:187] neg_lo:[0,0,1] neg_hi:[0,0,1]
	v_cvt_pk_bf16_f32 v194, v194, v195
	v_cvt_pk_bf16_f32 v195, v186, v187
	v_pk_mul_f32 v[182:183], v[128:129], v[182:183] op_sel_hi:[0,1]
	v_pk_mul_f32 v[184:185], v[128:129], v[184:185] op_sel_hi:[0,1]
	s_waitcnt vmcnt(2)
	v_cvt_f32_f16_e32 v191, v205
	v_cvt_f32_f16_e32 v190, v204
	v_cvt_f32_f16_sdwa v187, v205 dst_sel:DWORD dst_unused:UNUSED_PAD src0_sel:WORD_1
	v_cvt_f32_f16_sdwa v186, v204 dst_sel:DWORD dst_unused:UNUSED_PAD src0_sel:WORD_1
	v_pk_mul_f32 v[182:183], v[0:1], v[182:183]
	v_pk_mul_f32 v[184:185], v[8:9], v[184:185]
	v_pk_mul_f32 v[196:197], v[182:183], v[190:191]
	v_pk_mul_f32 v[182:183], v[182:183], v[186:187]
	v_pk_fma_f32 v[196:197], v[184:185], v[186:187], v[196:197]
	v_cvt_f32_f16_e32 v187, v207
	v_cvt_f32_f16_e32 v186, v206
	v_pk_fma_f32 v[182:183], v[184:185], v[190:191], v[182:183] neg_lo:[0,0,1] neg_hi:[0,0,1]
	v_cvt_f32_f16_sdwa v185, v207 dst_sel:DWORD dst_unused:UNUSED_PAD src0_sel:WORD_1
	v_cvt_f32_f16_sdwa v184, v206 dst_sel:DWORD dst_unused:UNUSED_PAD src0_sel:WORD_1
	v_pk_mul_f32 v[188:189], v[128:129], v[188:189] op_sel_hi:[0,1]
	v_cvt_pk_bf16_f32 v208, v208, v209
	v_cvt_pk_bf16_f32 v209, v210, v211
	v_cvt_pk_bf16_f32 v210, v196, v197
	v_cvt_pk_bf16_f32 v196, v182, v183
	v_pk_mul_f32 v[182:183], v[128:129], v[192:193] op_sel_hi:[0,1]
	v_pk_mul_f32 v[188:189], v[2:3], v[188:189]
	v_pk_mul_f32 v[182:183], v[10:11], v[182:183]
	v_pk_mul_f32 v[190:191], v[188:189], v[186:187]
	v_ashrrev_i32_e32 v128, 31, v153
	v_pk_fma_f32 v[190:191], v[182:183], v[184:185], v[190:191]
	v_pk_mul_f32 v[184:185], v[188:189], v[184:185]
	v_mul_lo_u32 v128, s60, v128
	v_pk_fma_f32 v[182:183], v[182:183], v[186:187], v[184:185] neg_lo:[0,0,1] neg_hi:[0,0,1]
	v_mul_lo_u32 v167, s61, v153
	v_cvt_pk_bf16_f32 v197, v182, v183
	v_mad_u64_u32 v[182:183], s[6:7], s60, v153, 0
	v_add3_u32 v183, v183, v128, v167
	v_lshl_add_u64 v[180:181], v[182:183], 1, v[180:181]
	v_cvt_pk_bf16_f32 v211, v190, v191
	global_store_dwordx4 v[180:181], v[194:197], off
	global_store_dwordx4 v[180:181], v[208:211], off offset:64
	s_mov_b64 s[6:7], 0
